# v6 plus D1 triangular solve rows restructured: rhs reads first, coefficient reads in use order, progressive counted lgkmcnt waits inside the FMA chain
# speedup vs baseline: 1.0208x; 1.0070x over previous
; __device__ __forceinline__ bf16_t f2bf(float f) { return (bf16_t)(cvt_pk_bf16(f, 0.f) & 0xffffu); }
; __device__ __forceinline__ float bf2f(bf16_t b) { return __uint_as_float(((unsigned)b) << 16); }
; template <int I>
; __device__ __forceinline__ void solve_rows(float (&x)[64], const f32x4* A4, const bf16_t* src, const float* sBeta, const float* sGam, int part, bf16_t* dst, int nvalid) {
;     if constexpr (I < 64) {
;         f32x4 a4[(I + 3) / 4 + 1];
; #pragma unroll
;         for (int q = 0; q < (I + 3) / 4; ++q) a4[q] = A4[I * 16 + q];
;         float a = bf2f(src[I * 136]) * sBeta[I];
;         if (part == 1) a *= __expf(sGam[I]);
; #pragma unroll
;         for (int j = 0; j < I; ++j) a -= a4[j >> 2][j & 3] * x[j];
;         x[I] = a;
;         if (I < nvalid) *dst = f2bf(a);
;         dst += 1024;
;         asm volatile("" : "+v"(dst) :: "memory");
;         solve_rows<I + 1>(x, A4, src, sBeta, sGam, part, dst, nvalid);
.LBB0_433:
	v_fma_f32 v65, -v64, v0, v1
	v_cvt_pk_bf16_f32 v0, v65, s0
	global_store_short v[4:5], v0, off
	v_lshl_add_u64 v[0:1], v[4:5], 0, s[0:1]
	ds_read_u16 v4, v108 offset:544
	ds_read_b32 v5, v107 offset:8
	ds_read_b64 v[2:3], v54 offset:52736
	s_and_b64 vcc, exec, s[50:51]
	s_waitcnt lgkmcnt(0)
	v_lshlrev_b32_e32 v4, 16, v4
	v_mul_f32_e32 v4, v5, v4
	s_cbranch_vccnz .LBB0_435
	ds_read_b32 v5, v106 offset:8
	s_waitcnt lgkmcnt(0)
	v_mul_f32_e32 v5, 0x3fb8aa3b, v5
	v_exp_f32_e32 v5, v5
	s_nop 0
	v_mul_f32_e32 v4, v4, v5
.LBB0_435:
	v_pk_mul_f32 v[2:3], v[64:65], v[2:3]
	s_and_b64 vcc, exec, s[50:51]
	v_sub_f32_e32 v2, v4, v2
	v_sub_f32_e32 v67, v2, v3
	v_cvt_pk_bf16_f32 v2, v67, s0
	global_store_short v[0:1], v2, off
	v_lshl_add_u64 v[4:5], v[0:1], 0, s[0:1]
	ds_read_u16 v6, v108 offset:816
	ds_read_b32 v7, v107 offset:12
	ds_read_b128 v[0:3], v54 offset:52992
	s_waitcnt lgkmcnt(0)
	v_lshlrev_b32_e32 v3, 16, v6
	v_mul_f32_e32 v3, v7, v3
	s_cbranch_vccnz .LBB0_437
	ds_read_b32 v6, v106 offset:12
	s_waitcnt lgkmcnt(0)
	v_mul_f32_e32 v6, 0x3fb8aa3b, v6
	v_exp_f32_e32 v6, v6
	s_nop 0
	v_mul_f32_e32 v3, v3, v6
.LBB0_437:
	v_fma_f32 v3, -v64, v0, v3
	v_mov_b32_e32 v66, v65
	v_mov_b32_e32 v0, v1
	v_mov_b32_e32 v1, v2
	v_pk_mul_f32 v[0:1], v[66:67], v[0:1]
	s_and_b64 vcc, exec, s[50:51]
	v_sub_f32_e32 v0, v3, v0
	v_sub_f32_e32 v69, v0, v1
	v_cvt_pk_bf16_f32 v0, v69, s0
	global_store_short v[4:5], v0, off
	v_lshl_add_u64 v[4:5], v[4:5], 0, s[0:1]
	ds_read_u16 v6, v108 offset:1088
	ds_read_b32 v7, v107 offset:16
	ds_read_b128 v[0:3], v54 offset:53248
	s_waitcnt lgkmcnt(0)
	v_lshlrev_b32_e32 v6, 16, v6
	v_mul_f32_e32 v6, v7, v6
	s_cbranch_vccnz .LBB0_439
	ds_read_b32 v7, v106 offset:16
	s_waitcnt lgkmcnt(0)
	v_mul_f32_e32 v7, 0x3fb8aa3b, v7
	v_exp_f32_e32 v7, v7
	s_nop 0
	v_mul_f32_e32 v6, v6, v7
.LBB0_439:
	v_pk_mul_f32 v[0:1], v[64:65], v[0:1]
	v_mov_b32_e32 v68, v67
	v_sub_f32_e32 v0, v6, v0
	v_sub_f32_e32 v6, v0, v1
	v_pk_mul_f32 v[0:1], v[68:69], v[2:3]
	s_waitcnt vmcnt(0)
	v_lshl_add_u64 v[8:9], v[4:5], 0, s[0:1]
	v_sub_f32_e32 v0, v6, v0
	v_sub_f32_e32 v71, v0, v1
	v_cvt_pk_bf16_f32 v0, v71, s0
	global_store_short v[4:5], v0, off
	ds_read_b128 v[0:3], v54 offset:53504
	ds_read_b128 v[4:7], v54 offset:53520
	s_waitcnt lgkmcnt(0)
	ds_read_u16 v5, v108 offset:1360
	ds_read_b32 v6, v107 offset:20
	s_and_b64 vcc, exec, s[50:51]
	s_waitcnt lgkmcnt(0)
	v_lshlrev_b32_e32 v5, 16, v5
	v_mul_f32_e32 v5, v6, v5
	s_cbranch_vccnz .LBB0_441
	ds_read_b32 v6, v106 offset:20
	s_waitcnt lgkmcnt(0)
	v_mul_f32_e32 v6, 0x3fb8aa3b, v6
	v_exp_f32_e32 v6, v6
	s_nop 0
	v_mul_f32_e32 v5, v5, v6
.LBB0_441:
	v_fma_f32 v5, -v64, v0, v5
	v_mov_b32_e32 v0, v1
	v_mov_b32_e32 v1, v2
	v_pk_mul_f32 v[0:1], v[66:67], v[0:1]
	v_mov_b32_e32 v70, v69
	v_sub_f32_e32 v0, v5, v0
	v_sub_f32_e32 v2, v0, v1
	v_pk_mov_b32 v[0:1], v[2:3], v[4:5] op_sel:[1,0]
	v_lshl_add_u64 v[4:5], v[8:9], 0, s[0:1]
	v_pk_mul_f32 v[0:1], v[70:71], v[0:1]
	s_and_b64 vcc, exec, s[50:51]
	v_sub_f32_e32 v0, v2, v0
	s_waitcnt vmcnt(0)
	v_sub_f32_e32 v73, v0, v1
	v_cvt_pk_bf16_f32 v0, v73, s0
	global_store_short v[8:9], v0, off
	ds_read_u16 v8, v108 offset:1632
	ds_read_b128 v[0:3], v54 offset:53760
	ds_read_b32 v9, v107 offset:24
	ds_read_b64 v[6:7], v54 offset:53776
	s_waitcnt lgkmcnt(0)
	v_lshlrev_b32_e32 v8, 16, v8
	v_mul_f32_e32 v8, v9, v8
	s_cbranch_vccnz .LBB0_443
	ds_read_b32 v9, v106 offset:24
	s_waitcnt lgkmcnt(0)
	v_mul_f32_e32 v9, 0x3fb8aa3b, v9
	v_exp_f32_e32 v9, v9
	s_nop 0
	v_mul_f32_e32 v8, v8, v9
.LBB0_443:
	v_pk_mul_f32 v[0:1], v[64:65], v[0:1]
	v_mov_b32_e32 v72, v71
	v_sub_f32_e32 v0, v8, v0
	v_sub_f32_e32 v8, v0, v1
	v_pk_mul_f32 v[0:1], v[68:69], v[2:3]
	s_and_b64 vcc, exec, s[50:51]
	v_sub_f32_e32 v0, v8, v0
	v_sub_f32_e32 v2, v0, v1
	v_pk_mul_f32 v[0:1], v[72:73], v[6:7]
	v_lshl_add_u64 v[8:9], v[4:5], 0, s[0:1]
	v_sub_f32_e32 v0, v2, v0
	v_sub_f32_e32 v75, v0, v1
	v_cvt_pk_bf16_f32 v0, v75, s0
	global_store_short v[4:5], v0, off
	ds_read_u16 v10, v108 offset:1904
	ds_read_b128 v[4:7], v54 offset:54016
	ds_read_b32 v11, v107 offset:28
	ds_read_b128 v[0:3], v54 offset:54032
	s_waitcnt lgkmcnt(0)
	v_lshlrev_b32_e32 v3, 16, v10
	v_mul_f32_e32 v3, v11, v3
	s_cbranch_vccnz .LBB0_445
	ds_read_b32 v10, v106 offset:28
	s_waitcnt lgkmcnt(0)
	v_mul_f32_e32 v10, 0x3fb8aa3b, v10
	v_exp_f32_e32 v10, v10
	s_nop 0
	v_mul_f32_e32 v3, v3, v10
.LBB0_445:
	v_fma_f32 v3, -v64, v4, v3
	v_mov_b32_e32 v4, v5
	v_mov_b32_e32 v5, v6
	v_pk_mul_f32 v[4:5], v[66:67], v[4:5]
	v_mov_b32_e32 v74, v73
	v_sub_f32_e32 v3, v3, v4
	v_sub_f32_e32 v3, v3, v5
	v_pk_mov_b32 v[4:5], v[6:7], v[0:1] op_sel:[1,0]
	s_and_b64 vcc, exec, s[50:51]
	v_pk_mul_f32 v[4:5], v[70:71], v[4:5]
	s_nop 0
	v_sub_f32_e32 v0, v3, v4
	v_sub_f32_e32 v3, v0, v5
	v_mov_b32_e32 v0, v1
	v_mov_b32_e32 v1, v2
	v_pk_mul_f32 v[0:1], v[74:75], v[0:1]
	s_nop 0
	v_sub_f32_e32 v0, v3, v0
	v_sub_f32_e32 v77, v0, v1
	v_cvt_pk_bf16_f32 v0, v77, s0
	global_store_short v[8:9], v0, off
	v_lshl_add_u64 v[8:9], v[8:9], 0, s[0:1]
	ds_read_u16 v10, v108 offset:2176
	ds_read_b128 v[4:7], v54 offset:54272
	ds_read_b32 v11, v107 offset:32
	ds_read_b128 v[0:3], v54 offset:54288
	s_waitcnt lgkmcnt(0)
	v_lshlrev_b32_e32 v10, 16, v10
	v_mul_f32_e32 v10, v11, v10
	s_cbranch_vccnz .LBB0_447
	ds_read_b32 v11, v106 offset:32
	s_waitcnt lgkmcnt(0)
	v_mul_f32_e32 v11, 0x3fb8aa3b, v11
	v_exp_f32_e32 v11, v11
	s_nop 0
	v_mul_f32_e32 v10, v10, v11
; __device__ __forceinline__ bf16_t f2bf(float f) { return (bf16_t)(cvt_pk_bf16(f, 0.f) & 0xffffu); }
; __device__ __forceinline__ float bf2f(bf16_t b) { return __uint_as_float(((unsigned)b) << 16); }
; template <int I>
; __device__ __forceinline__ void solve_rows(float (&x)[64], const f32x4* A4, const bf16_t* src, const float* sBeta, const float* sGam, int part, bf16_t* dst, int nvalid) {
;     if constexpr (I < 64) {
;         f32x4 a4[(I + 3) / 4 + 1];
; #pragma unroll
;         for (int q = 0; q < (I + 3) / 4; ++q) a4[q] = A4[I * 16 + q];
;         float a = bf2f(src[I * 136]) * sBeta[I];
;         if (part == 1) a *= __expf(sGam[I]);
; #pragma unroll
;         for (int j = 0; j < I; ++j) a -= a4[j >> 2][j & 3] * x[j];
;         x[I] = a;
;         if (I < nvalid) *dst = f2bf(a);
;         dst += 1024;
;         asm volatile("" : "+v"(dst) :: "memory");
;         solve_rows<I + 1>(x, A4, src, sBeta, sGam, part, dst, nvalid);
.LBB0_447:
	v_pk_mul_f32 v[4:5], v[64:65], v[4:5]
	v_pk_mul_f32 v[0:1], v[72:73], v[0:1]
	v_sub_f32_e32 v4, v10, v4
	v_sub_f32_e32 v10, v4, v5
	v_pk_mul_f32 v[4:5], v[68:69], v[6:7]
	v_mov_b32_e32 v76, v75
	v_sub_f32_e32 v4, v10, v4
	v_sub_f32_e32 v4, v4, v5
	v_sub_f32_e32 v0, v4, v0
	v_sub_f32_e32 v4, v0, v1
	v_pk_mul_f32 v[0:1], v[76:77], v[2:3]
	v_lshl_add_u64 v[12:13], v[8:9], 0, s[0:1]
	v_sub_f32_e32 v0, v4, v0
	v_sub_f32_e32 v79, v0, v1
	v_cvt_pk_bf16_f32 v0, v79, s0
	global_store_short v[8:9], v0, off
	ds_read_b128 v[8:11], v54 offset:54528
	ds_read_b128 v[0:3], v54 offset:54544
	ds_read_b128 v[4:7], v54 offset:54560
	s_waitcnt lgkmcnt(0)
	ds_read_u16 v5, v108 offset:2448
	ds_read_b32 v6, v107 offset:36
	s_and_b64 vcc, exec, s[50:51]
	s_waitcnt lgkmcnt(0)
	v_lshlrev_b32_e32 v5, 16, v5
	v_mul_f32_e32 v5, v6, v5
	s_cbranch_vccnz .LBB0_449
	ds_read_b32 v6, v106 offset:36
	s_waitcnt lgkmcnt(0)
	v_mul_f32_e32 v6, 0x3fb8aa3b, v6
	v_exp_f32_e32 v6, v6
	s_nop 0
	v_mul_f32_e32 v5, v5, v6
.LBB0_449:
	v_mov_b32_e32 v6, v9
	v_mov_b32_e32 v7, v10
	v_fma_f32 v5, -v64, v8, v5
	v_pk_mul_f32 v[6:7], v[66:67], v[6:7]
	v_mov_b32_e32 v78, v77
	v_sub_f32_e32 v5, v5, v6
	v_sub_f32_e32 v5, v5, v7
	v_pk_mov_b32 v[6:7], v[10:11], v[0:1] op_sel:[1,0]
	v_lshl_add_u64 v[8:9], v[12:13], 0, s[0:1]
	v_pk_mul_f32 v[6:7], v[70:71], v[6:7]
	s_and_b64 vcc, exec, s[50:51]
	v_sub_f32_e32 v0, v5, v6
	v_sub_f32_e32 v5, v0, v7
	v_mov_b32_e32 v0, v1
	v_mov_b32_e32 v1, v2
	v_pk_mul_f32 v[0:1], v[74:75], v[0:1]
	s_nop 0
	v_sub_f32_e32 v0, v5, v0
	v_sub_f32_e32 v2, v0, v1
	v_pk_mov_b32 v[0:1], v[2:3], v[4:5] op_sel:[1,0]
	s_nop 0
	v_pk_mul_f32 v[0:1], v[78:79], v[0:1]
	s_nop 0
	v_sub_f32_e32 v0, v2, v0
	v_sub_f32_e32 v81, v0, v1
	v_cvt_pk_bf16_f32 v0, v81, s0
	global_store_short v[12:13], v0, off
	ds_read_u16 v12, v108 offset:2720
	ds_read_b128 v[4:7], v54 offset:54784
	ds_read_b32 v13, v107 offset:40
	ds_read_b128 v[0:3], v54 offset:54800
	ds_read_b64 v[10:11], v54 offset:54816
	s_waitcnt lgkmcnt(0)
	v_lshlrev_b32_e32 v12, 16, v12
	v_mul_f32_e32 v12, v13, v12
	s_cbranch_vccnz .LBB0_451
	ds_read_b32 v13, v106 offset:40
	s_waitcnt lgkmcnt(0)
	v_mul_f32_e32 v13, 0x3fb8aa3b, v13
	v_exp_f32_e32 v13, v13
	s_nop 0
	v_mul_f32_e32 v12, v12, v13
.LBB0_451:
	v_pk_mul_f32 v[4:5], v[64:65], v[4:5]
	v_pk_mul_f32 v[0:1], v[72:73], v[0:1]
	v_sub_f32_e32 v4, v12, v4
	v_sub_f32_e32 v12, v4, v5
	v_pk_mul_f32 v[4:5], v[68:69], v[6:7]
	v_mov_b32_e32 v80, v79
	v_sub_f32_e32 v4, v12, v4
	v_sub_f32_e32 v4, v4, v5
	v_sub_f32_e32 v0, v4, v0
	v_sub_f32_e32 v4, v0, v1
	v_pk_mul_f32 v[0:1], v[76:77], v[2:3]
	v_lshl_add_u64 v[12:13], v[8:9], 0, s[0:1]
	v_sub_f32_e32 v0, v4, v0
	v_sub_f32_e32 v2, v0, v1
	v_pk_mul_f32 v[0:1], v[80:81], v[10:11]
	s_and_b64 vcc, exec, s[50:51]
	v_sub_f32_e32 v0, v2, v0
	v_sub_f32_e32 v83, v0, v1
	v_cvt_pk_bf16_f32 v0, v83, s0
	global_store_short v[8:9], v0, off
	ds_read_u16 v14, v108 offset:2992
	ds_read_b32 v15, v107 offset:44
	ds_read_b32 v234, v106 offset:44
	ds_read_b128 v[8:11], v54 offset:55040
	ds_read_b128 v[4:7], v54 offset:55056
	ds_read_b128 v[0:3], v54 offset:55072
	s_waitcnt lgkmcnt(3)
	v_lshlrev_b32_e32 v235, 16, v14
	v_mul_f32_e32 v235, v15, v235
	s_cbranch_vccnz .LBB0_453
	v_mul_f32_e32 v14, 0x3fb8aa3b, v234
	v_exp_f32_e32 v14, v14
	s_nop 0
	v_mul_f32_e32 v235, v235, v14
.LBB0_453:
	s_waitcnt lgkmcnt(0)
	v_fma_f32 v3, -v64, v8, v235
	v_mov_b32_e32 v8, v9
	v_mov_b32_e32 v9, v10
	v_pk_mul_f32 v[8:9], v[66:67], v[8:9]
	v_mov_b32_e32 v82, v81
	v_sub_f32_e32 v3, v3, v8
	v_sub_f32_e32 v3, v3, v9
	v_pk_mov_b32 v[8:9], v[10:11], v[4:5] op_sel:[1,0]
	v_mov_b32_e32 v4, v5
	v_pk_mul_f32 v[8:9], v[70:71], v[8:9]
	v_mov_b32_e32 v5, v6
	v_sub_f32_e32 v3, v3, v8
	v_sub_f32_e32 v3, v3, v9
	v_pk_mul_f32 v[4:5], v[74:75], v[4:5]
	s_and_b64 vcc, exec, s[50:51]
	v_sub_f32_e32 v3, v3, v4
	v_sub_f32_e32 v3, v3, v5
	v_pk_mov_b32 v[4:5], v[6:7], v[0:1] op_sel:[1,0]
	s_nop 0
	v_pk_mul_f32 v[4:5], v[78:79], v[4:5]
	s_nop 0
	v_sub_f32_e32 v0, v3, v4
	v_sub_f32_e32 v3, v0, v5
	v_mov_b32_e32 v0, v1
	v_mov_b32_e32 v1, v2
	v_pk_mul_f32 v[0:1], v[82:83], v[0:1]
	s_nop 0
	v_sub_f32_e32 v0, v3, v0
	v_sub_f32_e32 v85, v0, v1
	v_cvt_pk_bf16_f32 v0, v85, s0
	global_store_short v[12:13], v0, off
	v_lshl_add_u64 v[12:13], v[12:13], 0, s[0:1]
	ds_read_u16 v14, v108 offset:3264
	ds_read_b128 v[8:11], v54 offset:55296
	ds_read_b32 v15, v107 offset:48
	ds_read_b128 v[4:7], v54 offset:55312
	ds_read_b128 v[0:3], v54 offset:55328
	s_waitcnt lgkmcnt(0)
	v_lshlrev_b32_e32 v14, 16, v14
	v_mul_f32_e32 v14, v15, v14
	s_cbranch_vccnz .LBB0_455
	ds_read_b32 v15, v106 offset:48
	s_waitcnt lgkmcnt(0)
	v_mul_f32_e32 v15, 0x3fb8aa3b, v15
	v_exp_f32_e32 v15, v15
	s_nop 0
	v_mul_f32_e32 v14, v14, v15
.LBB0_455:
	v_pk_mul_f32 v[8:9], v[64:65], v[8:9]
	v_pk_mul_f32 v[4:5], v[72:73], v[4:5]
	v_sub_f32_e32 v8, v14, v8
	v_sub_f32_e32 v14, v8, v9
	v_pk_mul_f32 v[8:9], v[68:69], v[10:11]
	v_pk_mul_f32 v[0:1], v[80:81], v[0:1]
	v_sub_f32_e32 v8, v14, v8
	v_sub_f32_e32 v8, v8, v9
	v_sub_f32_e32 v4, v8, v4
	v_sub_f32_e32 v8, v4, v5
	v_pk_mul_f32 v[4:5], v[76:77], v[6:7]
	v_mov_b32_e32 v84, v83
	v_sub_f32_e32 v4, v8, v4
	v_sub_f32_e32 v4, v4, v5
	v_sub_f32_e32 v0, v4, v0
	v_sub_f32_e32 v4, v0, v1
	v_pk_mul_f32 v[0:1], v[84:85], v[2:3]
	v_lshl_add_u64 v[16:17], v[12:13], 0, s[0:1]
	v_sub_f32_e32 v0, v4, v0
	v_sub_f32_e32 v87, v0, v1
	v_cvt_pk_bf16_f32 v0, v87, s0
	global_store_short v[12:13], v0, off
	ds_read_b128 v[12:15], v54 offset:55552
	ds_read_b128 v[8:11], v54 offset:55568
	ds_read_b128 v[0:3], v54 offset:55584
	ds_read_b128 v[4:7], v54 offset:55600
	s_waitcnt lgkmcnt(0)
	ds_read_u16 v5, v108 offset:3536
	ds_read_b32 v6, v107 offset:52
	s_and_b64 vcc, exec, s[50:51]
	s_waitcnt lgkmcnt(0)
	v_lshlrev_b32_e32 v5, 16, v5
	v_mul_f32_e32 v5, v6, v5
	s_cbranch_vccnz .LBB0_457
	ds_read_b32 v6, v106 offset:52
	s_waitcnt lgkmcnt(0)
	v_mul_f32_e32 v6, 0x3fb8aa3b, v6
	v_exp_f32_e32 v6, v6
	s_nop 0
	v_mul_f32_e32 v5, v5, v6
; __device__ __forceinline__ bf16_t f2bf(float f) { return (bf16_t)(cvt_pk_bf16(f, 0.f) & 0xffffu); }
; __device__ __forceinline__ float bf2f(bf16_t b) { return __uint_as_float(((unsigned)b) << 16); }
; template <int I>
; __device__ __forceinline__ void solve_rows(float (&x)[64], const f32x4* A4, const bf16_t* src, const float* sBeta, const float* sGam, int part, bf16_t* dst, int nvalid) {
;     if constexpr (I < 64) {
;         f32x4 a4[(I + 3) / 4 + 1];
; #pragma unroll
;         for (int q = 0; q < (I + 3) / 4; ++q) a4[q] = A4[I * 16 + q];
;         float a = bf2f(src[I * 136]) * sBeta[I];
;         if (part == 1) a *= __expf(sGam[I]);
; #pragma unroll
;         for (int j = 0; j < I; ++j) a -= a4[j >> 2][j & 3] * x[j];
;         x[I] = a;
;         if (I < nvalid) *dst = f2bf(a);
;         dst += 1024;
;         asm volatile("" : "+v"(dst) :: "memory");
;         solve_rows<I + 1>(x, A4, src, sBeta, sGam, part, dst, nvalid);
.LBB0_457:
	v_mov_b32_e32 v6, v13
	v_mov_b32_e32 v7, v14
	v_fma_f32 v5, -v64, v12, v5
	v_pk_mul_f32 v[6:7], v[66:67], v[6:7]
	v_mov_b32_e32 v86, v85
	v_sub_f32_e32 v5, v5, v6
	v_sub_f32_e32 v5, v5, v7
	v_pk_mov_b32 v[6:7], v[14:15], v[8:9] op_sel:[1,0]
	v_lshl_add_u64 v[12:13], v[16:17], 0, s[0:1]
	v_pk_mul_f32 v[6:7], v[70:71], v[6:7]
	s_and_b64 vcc, exec, s[50:51]
	v_sub_f32_e32 v5, v5, v6
	v_sub_f32_e32 v5, v5, v7
	v_mov_b32_e32 v6, v9
	v_mov_b32_e32 v7, v10
	v_pk_mul_f32 v[6:7], v[74:75], v[6:7]
	s_nop 0
	v_sub_f32_e32 v5, v5, v6
	v_sub_f32_e32 v5, v5, v7
	v_pk_mov_b32 v[6:7], v[10:11], v[0:1] op_sel:[1,0]
	s_nop 0
	v_pk_mul_f32 v[6:7], v[78:79], v[6:7]
	s_nop 0
	v_sub_f32_e32 v0, v5, v6
	v_sub_f32_e32 v5, v0, v7
	v_mov_b32_e32 v0, v1
	v_mov_b32_e32 v1, v2
	v_pk_mul_f32 v[0:1], v[82:83], v[0:1]
	s_nop 0
	v_sub_f32_e32 v0, v5, v0
	v_sub_f32_e32 v2, v0, v1
	v_pk_mov_b32 v[0:1], v[2:3], v[4:5] op_sel:[1,0]
	s_nop 0
	v_pk_mul_f32 v[0:1], v[86:87], v[0:1]
	s_nop 0
	v_sub_f32_e32 v0, v2, v0
	v_sub_f32_e32 v89, v0, v1
	v_cvt_pk_bf16_f32 v0, v89, s0
	global_store_short v[16:17], v0, off
	ds_read_b128 v[4:7], v54 offset:55824
	ds_read_b128 v[0:3], v54 offset:55840
	ds_read_u16 v16, v108 offset:3808
	ds_read_b128 v[8:11], v54 offset:55808
	ds_read_b32 v17, v107 offset:56
	ds_read_b64 v[14:15], v54 offset:55856
	s_waitcnt lgkmcnt(0)
	v_lshlrev_b32_e32 v16, 16, v16
	v_mul_f32_e32 v16, v17, v16
	s_cbranch_vccnz .LBB0_459
	ds_read_b32 v17, v106 offset:56
	s_waitcnt lgkmcnt(0)
	v_mul_f32_e32 v17, 0x3fb8aa3b, v17
	v_exp_f32_e32 v17, v17
	s_nop 0
	v_mul_f32_e32 v16, v16, v17
.LBB0_459:
	v_fma_f32 v8, -v64, v8, v16
	v_fma_f32 v16, -v65, v9, v8
	v_pk_mul_f32 v[8:9], v[68:69], v[10:11]
	v_pk_mul_f32 v[4:5], v[72:73], v[4:5]
	v_sub_f32_e32 v8, v16, v8
	v_sub_f32_e32 v8, v8, v9
	v_sub_f32_e32 v4, v8, v4
	v_sub_f32_e32 v8, v4, v5
	v_pk_mul_f32 v[4:5], v[76:77], v[6:7]
	v_pk_mul_f32 v[0:1], v[80:81], v[0:1]
	v_sub_f32_e32 v4, v8, v4
	v_sub_f32_e32 v4, v4, v5
	v_sub_f32_e32 v0, v4, v0
	v_sub_f32_e32 v4, v0, v1
	v_pk_mul_f32 v[0:1], v[84:85], v[2:3]
	v_mov_b32_e32 v88, v87
	v_sub_f32_e32 v0, v4, v0
	v_sub_f32_e32 v2, v0, v1
	v_pk_mul_f32 v[0:1], v[88:89], v[14:15]
	v_lshl_add_u64 v[16:17], v[12:13], 0, s[0:1]
	v_sub_f32_e32 v0, v2, v0
	v_sub_f32_e32 v91, v0, v1
	v_cvt_pk_bf16_f32 v0, v91, s0
	global_store_short v[12:13], v0, off
	ds_read_u16 v18, v108 offset:4080
	ds_read_b32 v19, v107 offset:60
	ds_read_b32 v234, v106 offset:60
	ds_read_b128 v[12:15], v54 offset:56064
	ds_read_b128 v[8:11], v54 offset:56080
	ds_read_b128 v[4:7], v54 offset:56096
	ds_read_b128 v[0:3], v54 offset:56112
	s_waitcnt lgkmcnt(4)
	s_and_b64 vcc, exec, s[50:51]
	v_lshlrev_b32_e32 v235, 16, v18
	v_mul_f32_e32 v235, v19, v235
	s_cbranch_vccnz .LBB0_461
	v_mul_f32_e32 v18, 0x3fb8aa3b, v234
	v_exp_f32_e32 v18, v18
	s_nop 0
	v_mul_f32_e32 v235, v235, v18
.LBB0_461:
	s_waitcnt lgkmcnt(0)
	v_fma_f32 v3, -v64, v12, v235
	v_fma_f32 v3, -v65, v13, v3
	v_pk_mov_b32 v[12:13], v[14:15], v[8:9] op_sel:[1,0]
	v_fma_f32 v3, -v67, v14, v3
	v_pk_mul_f32 v[12:13], v[70:71], v[12:13]
	v_mov_b32_e32 v8, v9
	v_sub_f32_e32 v3, v3, v12
	v_mov_b32_e32 v9, v10
	v_sub_f32_e32 v3, v3, v13
	v_pk_mul_f32 v[8:9], v[74:75], v[8:9]
	v_mov_b32_e32 v90, v89
	v_sub_f32_e32 v3, v3, v8
	v_sub_f32_e32 v3, v3, v9
	v_pk_mov_b32 v[8:9], v[10:11], v[4:5] op_sel:[1,0]
	v_mov_b32_e32 v4, v5
	v_pk_mul_f32 v[8:9], v[78:79], v[8:9]
	v_mov_b32_e32 v5, v6
	v_sub_f32_e32 v3, v3, v8
	v_sub_f32_e32 v3, v3, v9
	v_pk_mul_f32 v[4:5], v[82:83], v[4:5]
	s_and_b64 vcc, exec, s[50:51]
	v_sub_f32_e32 v3, v3, v4
	v_sub_f32_e32 v3, v3, v5
	v_pk_mov_b32 v[4:5], v[6:7], v[0:1] op_sel:[1,0]
	s_nop 0
	v_pk_mul_f32 v[4:5], v[86:87], v[4:5]
	s_nop 0
	v_sub_f32_e32 v0, v3, v4
	v_sub_f32_e32 v3, v0, v5
	v_mov_b32_e32 v0, v1
	v_mov_b32_e32 v1, v2
	v_pk_mul_f32 v[0:1], v[90:91], v[0:1]
	s_nop 0
	v_sub_f32_e32 v0, v3, v0
	v_sub_f32_e32 v66, v0, v1
	v_cvt_pk_bf16_f32 v0, v66, s0
	global_store_short v[16:17], v0, off
	v_lshl_add_u64 v[16:17], v[16:17], 0, s[0:1]
	ds_read_u16 v18, v108 offset:4352
	ds_read_b32 v19, v107 offset:64
	ds_read_b32 v234, v106 offset:64
	ds_read_b128 v[12:15], v54 offset:56320
	ds_read_b128 v[8:11], v54 offset:56336
	ds_read_b128 v[4:7], v54 offset:56352
	ds_read_b128 v[0:3], v54 offset:56368
	s_waitcnt lgkmcnt(4)
	v_lshlrev_b32_e32 v18, 16, v18
	v_mul_f32_e32 v18, v19, v18
	s_cbranch_vccnz .LBB0_463
	v_mul_f32_e32 v19, 0x3fb8aa3b, v234
	v_exp_f32_e32 v19, v19
	s_nop 0
	v_mul_f32_e32 v18, v18, v19
.LBB0_463:
	s_waitcnt lgkmcnt(3)
	v_fma_f32 v12, -v64, v12, v18
	v_fma_f32 v12, -v65, v13, v12
	v_fma_f32 v12, -v67, v14, v12
	v_fma_f32 v12, -v69, v15, v12
	s_waitcnt lgkmcnt(2)
	v_fma_f32 v8, -v71, v8, v12
	v_fma_f32 v8, -v73, v9, v8
	v_fma_f32 v8, -v75, v10, v8
	v_fma_f32 v8, -v77, v11, v8
	s_waitcnt lgkmcnt(1)
	v_fma_f32 v4, -v79, v4, v8
	v_fma_f32 v4, -v81, v5, v4
	v_fma_f32 v4, -v83, v6, v4
	v_fma_f32 v4, -v85, v7, v4
	s_waitcnt lgkmcnt(0)
	v_fma_f32 v0, -v87, v0, v4
	v_fma_f32 v0, -v89, v1, v0
	v_fma_f32 v0, -v91, v2, v0
	v_cndmask_b32_e64 v1, 0, 1, s[62:63]
	v_cmp_ne_u32_e64 s[52:53], 1, v1
	s_andn2_b64 vcc, exec, s[62:63]
	v_fma_f32 v68, -v3, v66, v0
	s_cbranch_vccnz .LBB0_465
	v_cvt_pk_bf16_f32 v0, v68, s0
	global_store_short v[16:17], v0, off
.LBB0_465:
	v_lshl_add_u64 v[20:21], v[16:17], 0, s[0:1]
	ds_read_u16 v235, v108 offset:4624
	ds_read_b32 v239, v107 offset:68
	ds_read_b32 v234, v106 offset:68
	ds_read_b128 v[12:15], v54 offset:56576
	ds_read_b128 v[16:19], v54 offset:56592
	ds_read_b128 v[8:11], v54 offset:56608
	ds_read_b128 v[4:7], v54 offset:56624
	ds_read_b128 v[0:3], v54 offset:56640
	s_waitcnt lgkmcnt(5)
	s_and_b64 vcc, exec, s[50:51]
	v_lshlrev_b32_e32 v235, 16, v235
	v_mul_f32_e32 v235, v239, v235
	s_cbranch_vccnz .LBB0_467
	v_mul_f32_e32 v239, 0x3fb8aa3b, v234
	v_exp_f32_e32 v239, v239
	s_nop 0
	v_mul_f32_e32 v235, v235, v239
; __device__ __forceinline__ bf16_t f2bf(float f) { return (bf16_t)(cvt_pk_bf16(f, 0.f) & 0xffffu); }
; __device__ __forceinline__ float bf2f(bf16_t b) { return __uint_as_float(((unsigned)b) << 16); }
; template <int I>
; __device__ __forceinline__ void solve_rows(float (&x)[64], const f32x4* A4, const bf16_t* src, const float* sBeta, const float* sGam, int part, bf16_t* dst, int nvalid) {
;     if constexpr (I < 64) {
;         f32x4 a4[(I + 3) / 4 + 1];
; #pragma unroll
;         for (int q = 0; q < (I + 3) / 4; ++q) a4[q] = A4[I * 16 + q];
;         float a = bf2f(src[I * 136]) * sBeta[I];
;         if (part == 1) a *= __expf(sGam[I]);
; #pragma unroll
;         for (int j = 0; j < I; ++j) a -= a4[j >> 2][j & 3] * x[j];
;         x[I] = a;
;         if (I < nvalid) *dst = f2bf(a);
;         dst += 1024;
;         asm volatile("" : "+v"(dst) :: "memory");
;         solve_rows<I + 1>(x, A4, src, sBeta, sGam, part, dst, nvalid);
.LBB0_467:
	s_waitcnt lgkmcnt(0)
	v_fma_f32 v1, -v64, v12, v235
	v_fma_f32 v1, -v65, v13, v1
	v_fma_f32 v1, -v67, v14, v1
	v_fma_f32 v1, -v69, v15, v1
	v_fma_f32 v1, -v71, v16, v1
	v_fma_f32 v1, -v73, v17, v1
	v_fma_f32 v1, -v75, v18, v1
	v_fma_f32 v1, -v77, v19, v1
	v_fma_f32 v1, -v79, v8, v1
	v_fma_f32 v1, -v81, v9, v1
	v_fma_f32 v1, -v83, v10, v1
	v_fma_f32 v1, -v85, v11, v1
	v_fma_f32 v1, -v87, v4, v1
	v_fma_f32 v1, -v89, v5, v1
	v_fma_f32 v1, -v91, v6, v1
	v_fma_f32 v1, -v66, v7, v1
	s_and_b64 vcc, exec, s[52:53]
	v_fma_f32 v70, -v68, v0, v1
	s_cbranch_vccnz .LBB0_469
	v_cvt_pk_bf16_f32 v0, v70, s0
	global_store_short v[20:21], v0, off
.LBB0_469:
	v_lshl_add_u64 v[20:21], v[20:21], 0, s[0:1]
	ds_read_u16 v235, v108 offset:4896
	ds_read_b32 v239, v107 offset:72
	ds_read_b32 v234, v106 offset:72
	ds_read_b128 v[12:15], v54 offset:56832
	ds_read_b128 v[16:19], v54 offset:56848
	ds_read_b128 v[8:11], v54 offset:56864
	ds_read_b128 v[4:7], v54 offset:56880
	ds_read_b128 v[0:3], v54 offset:56896
	s_waitcnt lgkmcnt(5)
	s_and_b64 vcc, exec, s[50:51]
	v_lshlrev_b32_e32 v235, 16, v235
	v_mul_f32_e32 v235, v239, v235
	s_cbranch_vccnz .LBB0_471
	v_mul_f32_e32 v239, 0x3fb8aa3b, v234
	v_exp_f32_e32 v239, v239
	s_nop 0
	v_mul_f32_e32 v235, v235, v239
.LBB0_471:
	s_waitcnt lgkmcnt(0)
	v_fma_f32 v2, -v64, v12, v235
	v_fma_f32 v2, -v65, v13, v2
	v_fma_f32 v2, -v67, v14, v2
	v_fma_f32 v2, -v69, v15, v2
	v_fma_f32 v2, -v71, v16, v2
	v_fma_f32 v2, -v73, v17, v2
	v_fma_f32 v2, -v75, v18, v2
	v_fma_f32 v2, -v77, v19, v2
	v_fma_f32 v2, -v79, v8, v2
	v_fma_f32 v2, -v81, v9, v2
	v_fma_f32 v2, -v83, v10, v2
	v_fma_f32 v2, -v85, v11, v2
	v_fma_f32 v2, -v87, v4, v2
	v_fma_f32 v2, -v89, v5, v2
	v_fma_f32 v2, -v91, v6, v2
	v_fma_f32 v2, -v66, v7, v2
	v_fma_f32 v0, -v68, v0, v2
	s_and_b64 vcc, exec, s[52:53]
	v_fma_f32 v72, -v70, v1, v0
	s_cbranch_vccnz .LBB0_473
	v_cvt_pk_bf16_f32 v0, v72, s0
	global_store_short v[20:21], v0, off
.LBB0_473:
	v_lshl_add_u64 v[20:21], v[20:21], 0, s[0:1]
	ds_read_u16 v22, v108 offset:5168
	ds_read_b32 v23, v107 offset:76
	ds_read_b32 v234, v106 offset:76
	ds_read_b128 v[16:19], v54 offset:57088
	ds_read_b128 v[8:11], v54 offset:57104
	ds_read_b128 v[4:7], v54 offset:57120
	ds_read_b128 v[12:15], v54 offset:57136
	ds_read_b128 v[0:3], v54 offset:57152
	s_waitcnt lgkmcnt(5)
	v_lshlrev_b32_e32 v235, 16, v22
	s_and_b64 vcc, exec, s[50:51]
	v_mul_f32_e32 v235, v23, v235
	s_cbranch_vccnz .LBB0_475
	v_mul_f32_e32 v22, 0x3fb8aa3b, v234
	v_exp_f32_e32 v22, v22
	s_nop 0
	v_mul_f32_e32 v235, v235, v22
.LBB0_475:
	s_waitcnt lgkmcnt(0)
	v_fma_f32 v3, -v64, v16, v235
	v_fma_f32 v3, -v65, v17, v3
	v_fma_f32 v3, -v67, v18, v3
	v_fma_f32 v3, -v69, v19, v3
	v_fma_f32 v3, -v71, v8, v3
	v_fma_f32 v3, -v73, v9, v3
	v_fma_f32 v3, -v75, v10, v3
	v_fma_f32 v3, -v77, v11, v3
	v_fma_f32 v3, -v79, v4, v3
	v_fma_f32 v3, -v81, v5, v3
	v_fma_f32 v3, -v83, v6, v3
	v_fma_f32 v3, -v85, v7, v3
	v_fma_f32 v3, -v87, v12, v3
	v_fma_f32 v3, -v89, v13, v3
	v_fma_f32 v3, -v91, v14, v3
	v_fma_f32 v3, -v66, v15, v3
	v_fma_f32 v0, -v68, v0, v3
	v_fma_f32 v0, -v70, v1, v0
	s_and_b64 vcc, exec, s[52:53]
	v_fma_f32 v74, -v72, v2, v0
	s_cbranch_vccnz .LBB0_477
	v_cvt_pk_bf16_f32 v0, v74, s0
	global_store_short v[20:21], v0, off
.LBB0_477:
	v_lshl_add_u64 v[20:21], v[20:21], 0, s[0:1]
	ds_read_u16 v22, v108 offset:5440
	ds_read_b32 v23, v107 offset:80
	ds_read_b32 v234, v106 offset:80
	ds_read_b128 v[16:19], v54 offset:57344
	ds_read_b128 v[8:11], v54 offset:57360
	ds_read_b128 v[4:7], v54 offset:57376
	ds_read_b128 v[12:15], v54 offset:57392
	ds_read_b128 v[0:3], v54 offset:57408
	s_waitcnt lgkmcnt(5)
	v_lshlrev_b32_e32 v22, 16, v22
	s_and_b64 vcc, exec, s[50:51]
	v_mul_f32_e32 v22, v23, v22
	s_cbranch_vccnz .LBB0_479
	v_mul_f32_e32 v23, 0x3fb8aa3b, v234
	v_exp_f32_e32 v23, v23
	s_nop 0
	v_mul_f32_e32 v22, v22, v23
.LBB0_479:
	s_waitcnt lgkmcnt(4)
	v_fma_f32 v16, -v64, v16, v22
	v_fma_f32 v16, -v65, v17, v16
	v_fma_f32 v16, -v67, v18, v16
	v_fma_f32 v16, -v69, v19, v16
	s_waitcnt lgkmcnt(3)
	v_fma_f32 v8, -v71, v8, v16
	v_fma_f32 v8, -v73, v9, v8
	v_fma_f32 v8, -v75, v10, v8
	v_fma_f32 v8, -v77, v11, v8
	s_waitcnt lgkmcnt(2)
	v_fma_f32 v4, -v79, v4, v8
	v_fma_f32 v4, -v81, v5, v4
	v_fma_f32 v4, -v83, v6, v4
	v_fma_f32 v4, -v85, v7, v4
	s_waitcnt lgkmcnt(1)
	v_fma_f32 v4, -v87, v12, v4
	v_fma_f32 v4, -v89, v13, v4
	v_fma_f32 v4, -v91, v14, v4
	v_fma_f32 v4, -v66, v15, v4
	s_waitcnt lgkmcnt(0)
	v_fma_f32 v0, -v68, v0, v4
	v_fma_f32 v0, -v70, v1, v0
	v_fma_f32 v0, -v72, v2, v0
	s_and_b64 vcc, exec, s[52:53]
	v_fma_f32 v76, -v74, v3, v0
	s_cbranch_vccnz .LBB0_481
	v_cvt_pk_bf16_f32 v0, v76, s0
	global_store_short v[20:21], v0, off
.LBB0_481:
	v_lshl_add_u64 v[24:25], v[20:21], 0, s[0:1]
	ds_read_u16 v235, v108 offset:5712
	ds_read_b32 v239, v107 offset:84
	ds_read_b32 v234, v106 offset:84
	ds_read_b128 v[16:19], v54 offset:57600
	ds_read_b128 v[20:23], v54 offset:57616
	ds_read_b128 v[12:15], v54 offset:57632
	ds_read_b128 v[8:11], v54 offset:57648
	ds_read_b128 v[4:7], v54 offset:57664
	ds_read_b128 v[0:3], v54 offset:57680
	s_waitcnt lgkmcnt(6)
	s_and_b64 vcc, exec, s[50:51]
	v_lshlrev_b32_e32 v235, 16, v235
	v_mul_f32_e32 v235, v239, v235
	s_cbranch_vccnz .LBB0_483
	v_mul_f32_e32 v239, 0x3fb8aa3b, v234
	v_exp_f32_e32 v239, v239
	s_nop 0
	v_mul_f32_e32 v235, v235, v239
; __device__ __forceinline__ bf16_t f2bf(float f) { return (bf16_t)(cvt_pk_bf16(f, 0.f) & 0xffffu); }
; __device__ __forceinline__ float bf2f(bf16_t b) { return __uint_as_float(((unsigned)b) << 16); }
; template <int I>
; __device__ __forceinline__ void solve_rows(float (&x)[64], const f32x4* A4, const bf16_t* src, const float* sBeta, const float* sGam, int part, bf16_t* dst, int nvalid) {
;     if constexpr (I < 64) {
;         f32x4 a4[(I + 3) / 4 + 1];
; #pragma unroll
;         for (int q = 0; q < (I + 3) / 4; ++q) a4[q] = A4[I * 16 + q];
;         float a = bf2f(src[I * 136]) * sBeta[I];
;         if (part == 1) a *= __expf(sGam[I]);
; #pragma unroll
;         for (int j = 0; j < I; ++j) a -= a4[j >> 2][j & 3] * x[j];
;         x[I] = a;
;         if (I < nvalid) *dst = f2bf(a);
;         dst += 1024;
;         asm volatile("" : "+v"(dst) :: "memory");
;         solve_rows<I + 1>(x, A4, src, sBeta, sGam, part, dst, nvalid);
.LBB0_483:
	s_waitcnt lgkmcnt(0)
	v_fma_f32 v1, -v64, v16, v235
	v_fma_f32 v1, -v65, v17, v1
	v_fma_f32 v1, -v67, v18, v1
	v_fma_f32 v1, -v69, v19, v1
	v_fma_f32 v1, -v71, v20, v1
	v_fma_f32 v1, -v73, v21, v1
	v_fma_f32 v1, -v75, v22, v1
	v_fma_f32 v1, -v77, v23, v1
	v_fma_f32 v1, -v79, v12, v1
	v_fma_f32 v1, -v81, v13, v1
	v_fma_f32 v1, -v83, v14, v1
	v_fma_f32 v1, -v85, v15, v1
	v_fma_f32 v1, -v87, v8, v1
	v_fma_f32 v1, -v89, v9, v1
	v_fma_f32 v1, -v91, v10, v1
	v_fma_f32 v1, -v66, v11, v1
	v_fma_f32 v1, -v68, v4, v1
	v_fma_f32 v1, -v70, v5, v1
	v_fma_f32 v1, -v72, v6, v1
	v_fma_f32 v1, -v74, v7, v1
	s_and_b64 vcc, exec, s[52:53]
	v_fma_f32 v78, -v76, v0, v1
	s_cbranch_vccnz .LBB0_485
	v_cvt_pk_bf16_f32 v0, v78, s0
	global_store_short v[24:25], v0, off
.LBB0_485:
	v_lshl_add_u64 v[24:25], v[24:25], 0, s[0:1]
	ds_read_u16 v235, v108 offset:5984
	ds_read_b32 v239, v107 offset:88
	ds_read_b32 v234, v106 offset:88
	ds_read_b128 v[16:19], v54 offset:57856
	ds_read_b128 v[20:23], v54 offset:57872
	ds_read_b128 v[12:15], v54 offset:57888
	ds_read_b128 v[8:11], v54 offset:57904
	ds_read_b128 v[4:7], v54 offset:57920
	ds_read_b128 v[0:3], v54 offset:57936
	s_waitcnt lgkmcnt(6)
	s_and_b64 vcc, exec, s[50:51]
	v_lshlrev_b32_e32 v235, 16, v235
	v_mul_f32_e32 v235, v239, v235
	s_cbranch_vccnz .LBB0_487
	v_mul_f32_e32 v239, 0x3fb8aa3b, v234
	v_exp_f32_e32 v239, v239
	s_nop 0
	v_mul_f32_e32 v235, v235, v239
.LBB0_487:
	s_waitcnt lgkmcnt(0)
	v_fma_f32 v2, -v64, v16, v235
	v_fma_f32 v2, -v65, v17, v2
	v_fma_f32 v2, -v67, v18, v2
	v_fma_f32 v2, -v69, v19, v2
	v_fma_f32 v2, -v71, v20, v2
	v_fma_f32 v2, -v73, v21, v2
	v_fma_f32 v2, -v75, v22, v2
	v_fma_f32 v2, -v77, v23, v2
	v_fma_f32 v2, -v79, v12, v2
	v_fma_f32 v2, -v81, v13, v2
	v_fma_f32 v2, -v83, v14, v2
	v_fma_f32 v2, -v85, v15, v2
	v_fma_f32 v2, -v87, v8, v2
	v_fma_f32 v2, -v89, v9, v2
	v_fma_f32 v2, -v91, v10, v2
	v_fma_f32 v2, -v66, v11, v2
	v_fma_f32 v2, -v68, v4, v2
	v_fma_f32 v2, -v70, v5, v2
	v_fma_f32 v2, -v72, v6, v2
	v_fma_f32 v2, -v74, v7, v2
	v_fma_f32 v0, -v76, v0, v2
	s_and_b64 vcc, exec, s[52:53]
	v_fma_f32 v80, -v78, v1, v0
	s_cbranch_vccnz .LBB0_489
	v_cvt_pk_bf16_f32 v0, v80, s0
	global_store_short v[24:25], v0, off
.LBB0_489:
	v_lshl_add_u64 v[24:25], v[24:25], 0, s[0:1]
	ds_read_u16 v26, v108 offset:6256
	ds_read_b32 v27, v107 offset:92
	ds_read_b32 v234, v106 offset:92
	ds_read_b128 v[20:23], v54 offset:58112
	ds_read_b128 v[16:19], v54 offset:58128
	ds_read_b128 v[12:15], v54 offset:58144
	ds_read_b128 v[8:11], v54 offset:58160
	ds_read_b128 v[0:3], v54 offset:58176
	ds_read_b128 v[4:7], v54 offset:58192
	s_waitcnt lgkmcnt(6)
	s_and_b64 vcc, exec, s[50:51]
	v_lshlrev_b32_e32 v235, 16, v26
	v_mul_f32_e32 v235, v27, v235
	s_cbranch_vccnz .LBB0_491
	v_mul_f32_e32 v26, 0x3fb8aa3b, v234
	v_exp_f32_e32 v26, v26
	s_nop 0
	v_mul_f32_e32 v235, v235, v26
.LBB0_491:
	s_waitcnt lgkmcnt(0)
	v_fma_f32 v7, -v64, v20, v235
	v_fma_f32 v7, -v65, v21, v7
	v_fma_f32 v7, -v67, v22, v7
	v_fma_f32 v7, -v69, v23, v7
	v_fma_f32 v7, -v71, v16, v7
	v_fma_f32 v7, -v73, v17, v7
	v_fma_f32 v7, -v75, v18, v7
	v_fma_f32 v7, -v77, v19, v7
	v_fma_f32 v7, -v79, v12, v7
	v_fma_f32 v7, -v81, v13, v7
	v_fma_f32 v7, -v83, v14, v7
	v_fma_f32 v7, -v85, v15, v7
	v_fma_f32 v7, -v87, v8, v7
	v_fma_f32 v7, -v89, v9, v7
	v_fma_f32 v7, -v91, v10, v7
	v_fma_f32 v7, -v66, v11, v7
	v_fma_f32 v0, -v68, v0, v7
	v_fma_f32 v0, -v70, v1, v0
	v_fma_f32 v0, -v72, v2, v0
	v_fma_f32 v0, -v74, v3, v0
	v_fma_f32 v0, -v76, v4, v0
	v_fma_f32 v0, -v78, v5, v0
	s_and_b64 vcc, exec, s[52:53]
	v_fma_f32 v82, -v80, v6, v0
	s_cbranch_vccnz .LBB0_493
	v_cvt_pk_bf16_f32 v0, v82, s0
	global_store_short v[24:25], v0, off
.LBB0_493:
	v_lshl_add_u64 v[24:25], v[24:25], 0, s[0:1]
	ds_read_u16 v26, v108 offset:6528
	ds_read_b32 v27, v107 offset:96
	ds_read_b32 v234, v106 offset:96
	ds_read_b128 v[20:23], v54 offset:58368
	ds_read_b128 v[16:19], v54 offset:58384
	ds_read_b128 v[12:15], v54 offset:58400
	ds_read_b128 v[8:11], v54 offset:58416
	ds_read_b128 v[0:3], v54 offset:58432
	ds_read_b128 v[4:7], v54 offset:58448
	s_waitcnt lgkmcnt(6)
	s_and_b64 vcc, exec, s[50:51]
	v_lshlrev_b32_e32 v26, 16, v26
	v_mul_f32_e32 v26, v27, v26
	s_cbranch_vccnz .LBB0_495
	v_mul_f32_e32 v27, 0x3fb8aa3b, v234
	v_exp_f32_e32 v27, v27
	s_nop 0
	v_mul_f32_e32 v26, v26, v27
.LBB0_495:
	s_waitcnt lgkmcnt(5)
	v_fma_f32 v20, -v64, v20, v26
	v_fma_f32 v20, -v65, v21, v20
	v_fma_f32 v20, -v67, v22, v20
	v_fma_f32 v20, -v69, v23, v20
	s_waitcnt lgkmcnt(4)
	v_fma_f32 v16, -v71, v16, v20
	v_fma_f32 v16, -v73, v17, v16
	v_fma_f32 v16, -v75, v18, v16
	v_fma_f32 v16, -v77, v19, v16
	s_waitcnt lgkmcnt(3)
	v_fma_f32 v12, -v79, v12, v16
	v_fma_f32 v12, -v81, v13, v12
	v_fma_f32 v12, -v83, v14, v12
	v_fma_f32 v12, -v85, v15, v12
	s_waitcnt lgkmcnt(2)
	v_fma_f32 v8, -v87, v8, v12
	v_fma_f32 v8, -v89, v9, v8
	v_fma_f32 v8, -v91, v10, v8
	v_fma_f32 v8, -v66, v11, v8
	s_waitcnt lgkmcnt(1)
	v_fma_f32 v0, -v68, v0, v8
	v_fma_f32 v0, -v70, v1, v0
	v_fma_f32 v0, -v72, v2, v0
	v_fma_f32 v0, -v74, v3, v0
	s_waitcnt lgkmcnt(0)
	v_fma_f32 v0, -v76, v4, v0
	v_fma_f32 v0, -v78, v5, v0
	v_fma_f32 v0, -v80, v6, v0
	s_and_b64 vcc, exec, s[52:53]
	v_fma_f32 v84, -v82, v7, v0
	s_cbranch_vccnz .LBB0_497
	v_cvt_pk_bf16_f32 v0, v84, s0
	global_store_short v[24:25], v0, off
; __device__ __forceinline__ bf16_t f2bf(float f) { return (bf16_t)(cvt_pk_bf16(f, 0.f) & 0xffffu); }
; __device__ __forceinline__ float bf2f(bf16_t b) { return __uint_as_float(((unsigned)b) << 16); }
; template <int I>
; __device__ __forceinline__ void solve_rows(float (&x)[64], const f32x4* A4, const bf16_t* src, const float* sBeta, const float* sGam, int part, bf16_t* dst, int nvalid) {
;     if constexpr (I < 64) {
;         f32x4 a4[(I + 3) / 4 + 1];
; #pragma unroll
;         for (int q = 0; q < (I + 3) / 4; ++q) a4[q] = A4[I * 16 + q];
;         float a = bf2f(src[I * 136]) * sBeta[I];
;         if (part == 1) a *= __expf(sGam[I]);
; #pragma unroll
;         for (int j = 0; j < I; ++j) a -= a4[j >> 2][j & 3] * x[j];
;         x[I] = a;
;         if (I < nvalid) *dst = f2bf(a);
;         dst += 1024;
;         asm volatile("" : "+v"(dst) :: "memory");
;         solve_rows<I + 1>(x, A4, src, sBeta, sGam, part, dst, nvalid);
.LBB0_497:
	v_lshl_add_u64 v[28:29], v[24:25], 0, s[0:1]
	ds_read_u16 v235, v108 offset:6800
	ds_read_b32 v239, v107 offset:100
	ds_read_b32 v234, v106 offset:100
	ds_read_b128 v[20:23], v54 offset:58624
	ds_read_b128 v[24:27], v54 offset:58640
	ds_read_b128 v[16:19], v54 offset:58656
	ds_read_b128 v[12:15], v54 offset:58672
	ds_read_b128 v[8:11], v54 offset:58688
	ds_read_b128 v[4:7], v54 offset:58704
	ds_read_b128 v[0:3], v54 offset:58720
	s_waitcnt lgkmcnt(7)
	s_and_b64 vcc, exec, s[50:51]
	v_lshlrev_b32_e32 v235, 16, v235
	v_mul_f32_e32 v235, v239, v235
	s_cbranch_vccnz .LBB0_499
	v_mul_f32_e32 v239, 0x3fb8aa3b, v234
	v_exp_f32_e32 v239, v239
	s_nop 0
	v_mul_f32_e32 v235, v235, v239
.LBB0_499:
	s_waitcnt lgkmcnt(0)
	v_fma_f32 v1, -v64, v20, v235
	v_fma_f32 v1, -v65, v21, v1
	v_fma_f32 v1, -v67, v22, v1
	v_fma_f32 v1, -v69, v23, v1
	v_fma_f32 v1, -v71, v24, v1
	v_fma_f32 v1, -v73, v25, v1
	v_fma_f32 v1, -v75, v26, v1
	v_fma_f32 v1, -v77, v27, v1
	v_fma_f32 v1, -v79, v16, v1
	v_fma_f32 v1, -v81, v17, v1
	v_fma_f32 v1, -v83, v18, v1
	v_fma_f32 v1, -v85, v19, v1
	v_fma_f32 v1, -v87, v12, v1
	v_fma_f32 v1, -v89, v13, v1
	v_fma_f32 v1, -v91, v14, v1
	v_fma_f32 v1, -v66, v15, v1
	v_fma_f32 v1, -v68, v8, v1
	v_fma_f32 v1, -v70, v9, v1
	v_fma_f32 v1, -v72, v10, v1
	v_fma_f32 v1, -v74, v11, v1
	v_fma_f32 v1, -v76, v4, v1
	v_fma_f32 v1, -v78, v5, v1
	v_fma_f32 v1, -v80, v6, v1
	v_fma_f32 v1, -v82, v7, v1
	s_and_b64 vcc, exec, s[52:53]
	v_fma_f32 v86, -v84, v0, v1
	s_cbranch_vccnz .LBB0_501
	v_cvt_pk_bf16_f32 v0, v86, s0
	global_store_short v[28:29], v0, off
.LBB0_501:
	v_lshl_add_u64 v[28:29], v[28:29], 0, s[0:1]
	ds_read_u16 v235, v108 offset:7072
	ds_read_b32 v239, v107 offset:104
	ds_read_b32 v234, v106 offset:104
	ds_read_b128 v[20:23], v54 offset:58880
	ds_read_b128 v[24:27], v54 offset:58896
	ds_read_b128 v[16:19], v54 offset:58912
	ds_read_b128 v[12:15], v54 offset:58928
	ds_read_b128 v[8:11], v54 offset:58944
	ds_read_b128 v[4:7], v54 offset:58960
	ds_read_b128 v[0:3], v54 offset:58976
	s_waitcnt lgkmcnt(7)
	s_and_b64 vcc, exec, s[50:51]
	v_lshlrev_b32_e32 v235, 16, v235
	v_mul_f32_e32 v235, v239, v235
	s_cbranch_vccnz .LBB0_503
	v_mul_f32_e32 v239, 0x3fb8aa3b, v234
	v_exp_f32_e32 v239, v239
	s_nop 0
	v_mul_f32_e32 v235, v235, v239
.LBB0_503:
	s_waitcnt lgkmcnt(0)
	v_fma_f32 v2, -v64, v20, v235
	v_fma_f32 v2, -v65, v21, v2
	v_fma_f32 v2, -v67, v22, v2
	v_fma_f32 v2, -v69, v23, v2
	v_fma_f32 v2, -v71, v24, v2
	v_fma_f32 v2, -v73, v25, v2
	v_fma_f32 v2, -v75, v26, v2
	v_fma_f32 v2, -v77, v27, v2
	v_fma_f32 v2, -v79, v16, v2
	v_fma_f32 v2, -v81, v17, v2
	v_fma_f32 v2, -v83, v18, v2
	v_fma_f32 v2, -v85, v19, v2
	v_fma_f32 v2, -v87, v12, v2
	v_fma_f32 v2, -v89, v13, v2
	v_fma_f32 v2, -v91, v14, v2
	v_fma_f32 v2, -v66, v15, v2
	v_fma_f32 v2, -v68, v8, v2
	v_fma_f32 v2, -v70, v9, v2
	v_fma_f32 v2, -v72, v10, v2
	v_fma_f32 v2, -v74, v11, v2
	v_fma_f32 v2, -v76, v4, v2
	v_fma_f32 v2, -v78, v5, v2
	v_fma_f32 v2, -v80, v6, v2
	v_fma_f32 v2, -v82, v7, v2
	v_fma_f32 v0, -v84, v0, v2
	s_and_b64 vcc, exec, s[52:53]
	v_fma_f32 v88, -v86, v1, v0
	s_cbranch_vccnz .LBB0_505
	v_cvt_pk_bf16_f32 v0, v88, s0
	global_store_short v[28:29], v0, off
.LBB0_505:
	v_lshl_add_u64 v[28:29], v[28:29], 0, s[0:1]
	ds_read_u16 v30, v108 offset:7344
	ds_read_b32 v31, v107 offset:108
	ds_read_b32 v234, v106 offset:108
	ds_read_b128 v[24:27], v54 offset:59136
	ds_read_b128 v[20:23], v54 offset:59152
	ds_read_b128 v[16:19], v54 offset:59168
	ds_read_b128 v[8:11], v54 offset:59184
	ds_read_b128 v[4:7], v54 offset:59200
	ds_read_b128 v[12:15], v54 offset:59216
	ds_read_b128 v[0:3], v54 offset:59232
	s_waitcnt lgkmcnt(7)
	v_lshlrev_b32_e32 v235, 16, v30
	s_and_b64 vcc, exec, s[50:51]
	v_mul_f32_e32 v235, v31, v235
	s_cbranch_vccnz .LBB0_507
	v_mul_f32_e32 v30, 0x3fb8aa3b, v234
	v_exp_f32_e32 v30, v30
	s_nop 0
	v_mul_f32_e32 v235, v235, v30
.LBB0_507:
	s_waitcnt lgkmcnt(0)
	v_fma_f32 v3, -v64, v24, v235
	v_fma_f32 v3, -v65, v25, v3
	v_fma_f32 v3, -v67, v26, v3
	v_fma_f32 v3, -v69, v27, v3
	v_fma_f32 v3, -v71, v20, v3
	v_fma_f32 v3, -v73, v21, v3
	v_fma_f32 v3, -v75, v22, v3
	v_fma_f32 v3, -v77, v23, v3
	v_fma_f32 v3, -v79, v16, v3
	v_fma_f32 v3, -v81, v17, v3
	v_fma_f32 v3, -v83, v18, v3
	v_fma_f32 v3, -v85, v19, v3
	v_fma_f32 v3, -v87, v8, v3
	v_fma_f32 v3, -v89, v9, v3
	v_fma_f32 v3, -v91, v10, v3
	v_fma_f32 v3, -v66, v11, v3
	v_fma_f32 v3, -v68, v4, v3
	v_fma_f32 v3, -v70, v5, v3
	v_fma_f32 v3, -v72, v6, v3
	v_fma_f32 v3, -v74, v7, v3
	v_fma_f32 v3, -v76, v12, v3
	v_fma_f32 v3, -v78, v13, v3
	v_fma_f32 v3, -v80, v14, v3
	v_fma_f32 v3, -v82, v15, v3
	v_fma_f32 v0, -v84, v0, v3
	v_fma_f32 v0, -v86, v1, v0
	s_and_b64 vcc, exec, s[52:53]
	v_fma_f32 v90, -v88, v2, v0
	s_cbranch_vccnz .LBB0_509
	v_cvt_pk_bf16_f32 v0, v90, s0
	global_store_short v[28:29], v0, off
.LBB0_509:
	v_lshl_add_u64 v[28:29], v[28:29], 0, s[0:1]
	ds_read_u16 v30, v108 offset:7616
	ds_read_b32 v31, v107 offset:112
	ds_read_b32 v234, v106 offset:112
	ds_read_b128 v[24:27], v54 offset:59392
	ds_read_b128 v[20:23], v54 offset:59408
	ds_read_b128 v[16:19], v54 offset:59424
	ds_read_b128 v[8:11], v54 offset:59440
	ds_read_b128 v[4:7], v54 offset:59456
	ds_read_b128 v[12:15], v54 offset:59472
	ds_read_b128 v[0:3], v54 offset:59488
	s_waitcnt lgkmcnt(7)
	v_lshlrev_b32_e32 v30, 16, v30
	s_and_b64 vcc, exec, s[50:51]
	v_mul_f32_e32 v30, v31, v30
	s_cbranch_vccnz .LBB0_511
	v_mul_f32_e32 v31, 0x3fb8aa3b, v234
	v_exp_f32_e32 v31, v31
	s_nop 0
	v_mul_f32_e32 v30, v30, v31
; __device__ __forceinline__ bf16_t f2bf(float f) { return (bf16_t)(cvt_pk_bf16(f, 0.f) & 0xffffu); }
; __device__ __forceinline__ float bf2f(bf16_t b) { return __uint_as_float(((unsigned)b) << 16); }
; template <int I>
; __device__ __forceinline__ void solve_rows(float (&x)[64], const f32x4* A4, const bf16_t* src, const float* sBeta, const float* sGam, int part, bf16_t* dst, int nvalid) {
;     if constexpr (I < 64) {
;         f32x4 a4[(I + 3) / 4 + 1];
; #pragma unroll
;         for (int q = 0; q < (I + 3) / 4; ++q) a4[q] = A4[I * 16 + q];
;         float a = bf2f(src[I * 136]) * sBeta[I];
;         if (part == 1) a *= __expf(sGam[I]);
; #pragma unroll
;         for (int j = 0; j < I; ++j) a -= a4[j >> 2][j & 3] * x[j];
;         x[I] = a;
;         if (I < nvalid) *dst = f2bf(a);
;         dst += 1024;
;         asm volatile("" : "+v"(dst) :: "memory");
;         solve_rows<I + 1>(x, A4, src, sBeta, sGam, part, dst, nvalid);
.LBB0_511:
	s_waitcnt lgkmcnt(6)
	v_fma_f32 v24, -v64, v24, v30
	v_fma_f32 v24, -v65, v25, v24
	v_fma_f32 v24, -v67, v26, v24
	v_fma_f32 v24, -v69, v27, v24
	s_waitcnt lgkmcnt(5)
	v_fma_f32 v20, -v71, v20, v24
	v_fma_f32 v20, -v73, v21, v20
	v_fma_f32 v20, -v75, v22, v20
	v_fma_f32 v20, -v77, v23, v20
	s_waitcnt lgkmcnt(4)
	v_fma_f32 v16, -v79, v16, v20
	v_fma_f32 v16, -v81, v17, v16
	v_fma_f32 v16, -v83, v18, v16
	v_fma_f32 v16, -v85, v19, v16
	s_waitcnt lgkmcnt(3)
	v_fma_f32 v8, -v87, v8, v16
	v_fma_f32 v8, -v89, v9, v8
	v_fma_f32 v8, -v91, v10, v8
	v_fma_f32 v8, -v66, v11, v8
	s_waitcnt lgkmcnt(2)
	v_fma_f32 v4, -v68, v4, v8
	v_fma_f32 v4, -v70, v5, v4
	v_fma_f32 v4, -v72, v6, v4
	v_fma_f32 v4, -v74, v7, v4
	s_waitcnt lgkmcnt(1)
	v_fma_f32 v4, -v76, v12, v4
	v_fma_f32 v4, -v78, v13, v4
	v_fma_f32 v4, -v80, v14, v4
	v_fma_f32 v4, -v82, v15, v4
	s_waitcnt lgkmcnt(0)
	v_fma_f32 v0, -v84, v0, v4
	v_fma_f32 v0, -v86, v1, v0
	v_fma_f32 v0, -v88, v2, v0
	s_and_b64 vcc, exec, s[52:53]
	v_fma_f32 v109, -v90, v3, v0
	s_cbranch_vccnz .LBB0_513
	v_cvt_pk_bf16_f32 v0, v109, s0
	global_store_short v[28:29], v0, off
.LBB0_513:
	v_lshl_add_u64 v[32:33], v[28:29], 0, s[0:1]
	ds_read_u16 v235, v108 offset:7888
	ds_read_b32 v239, v107 offset:116
	ds_read_b32 v234, v106 offset:116
	ds_read_b128 v[24:27], v54 offset:59648
	ds_read_b128 v[28:31], v54 offset:59664
	ds_read_b128 v[20:23], v54 offset:59680
	ds_read_b128 v[16:19], v54 offset:59696
	ds_read_b128 v[12:15], v54 offset:59712
	ds_read_b128 v[8:11], v54 offset:59728
	ds_read_b128 v[4:7], v54 offset:59744
	ds_read_b128 v[0:3], v54 offset:59760
	s_waitcnt lgkmcnt(8)
	s_and_b64 vcc, exec, s[50:51]
	v_lshlrev_b32_e32 v235, 16, v235
	v_mul_f32_e32 v235, v239, v235
	s_cbranch_vccnz .LBB0_515
	v_mul_f32_e32 v239, 0x3fb8aa3b, v234
	v_exp_f32_e32 v239, v239
	s_nop 0
	v_mul_f32_e32 v235, v235, v239
.LBB0_515:
	s_waitcnt lgkmcnt(0)
	v_fma_f32 v1, -v64, v24, v235
	v_fma_f32 v1, -v65, v25, v1
	v_fma_f32 v1, -v67, v26, v1
	v_fma_f32 v1, -v69, v27, v1
	v_fma_f32 v1, -v71, v28, v1
	v_fma_f32 v1, -v73, v29, v1
	v_fma_f32 v1, -v75, v30, v1
	v_fma_f32 v1, -v77, v31, v1
	v_fma_f32 v1, -v79, v20, v1
	v_fma_f32 v1, -v81, v21, v1
	v_fma_f32 v1, -v83, v22, v1
	v_fma_f32 v1, -v85, v23, v1
	v_fma_f32 v1, -v87, v16, v1
	v_fma_f32 v1, -v89, v17, v1
	v_fma_f32 v1, -v91, v18, v1
	v_fma_f32 v1, -v66, v19, v1
	v_fma_f32 v1, -v68, v12, v1
	v_fma_f32 v1, -v70, v13, v1
	v_fma_f32 v1, -v72, v14, v1
	v_fma_f32 v1, -v74, v15, v1
	v_fma_f32 v1, -v76, v8, v1
	v_fma_f32 v1, -v78, v9, v1
	v_fma_f32 v1, -v80, v10, v1
	v_fma_f32 v1, -v82, v11, v1
	v_fma_f32 v1, -v84, v4, v1
	v_fma_f32 v1, -v86, v5, v1
	v_fma_f32 v1, -v88, v6, v1
	v_fma_f32 v1, -v90, v7, v1
	s_and_b64 vcc, exec, s[52:53]
	v_fma_f32 v110, -v109, v0, v1
	s_cbranch_vccnz .LBB0_517
	v_cvt_pk_bf16_f32 v0, v110, s0
	global_store_short v[32:33], v0, off
.LBB0_517:
	v_lshl_add_u64 v[32:33], v[32:33], 0, s[0:1]
	ds_read_u16 v235, v108 offset:8160
	ds_read_b32 v239, v107 offset:120
	ds_read_b32 v234, v106 offset:120
	ds_read_b128 v[24:27], v54 offset:59904
	ds_read_b128 v[28:31], v54 offset:59920
	ds_read_b128 v[20:23], v54 offset:59936
	ds_read_b128 v[16:19], v54 offset:59952
	ds_read_b128 v[12:15], v54 offset:59968
	ds_read_b128 v[8:11], v54 offset:59984
	ds_read_b128 v[4:7], v54 offset:60000
	ds_read_b128 v[0:3], v54 offset:60016
	s_waitcnt lgkmcnt(8)
	s_and_b64 vcc, exec, s[50:51]
	v_lshlrev_b32_e32 v235, 16, v235
	v_mul_f32_e32 v235, v239, v235
	s_cbranch_vccnz .LBB0_519
	v_mul_f32_e32 v239, 0x3fb8aa3b, v234
	v_exp_f32_e32 v239, v239
	s_nop 0
	v_mul_f32_e32 v235, v235, v239
.LBB0_519:
	s_waitcnt lgkmcnt(0)
	v_fma_f32 v2, -v64, v24, v235
	v_fma_f32 v2, -v65, v25, v2
	v_fma_f32 v2, -v67, v26, v2
	v_fma_f32 v2, -v69, v27, v2
	v_fma_f32 v2, -v71, v28, v2
	v_fma_f32 v2, -v73, v29, v2
	v_fma_f32 v2, -v75, v30, v2
	v_fma_f32 v2, -v77, v31, v2
	v_fma_f32 v2, -v79, v20, v2
	v_fma_f32 v2, -v81, v21, v2
	v_fma_f32 v2, -v83, v22, v2
	v_fma_f32 v2, -v85, v23, v2
	v_fma_f32 v2, -v87, v16, v2
	v_fma_f32 v2, -v89, v17, v2
	v_fma_f32 v2, -v91, v18, v2
	v_fma_f32 v2, -v66, v19, v2
	v_fma_f32 v2, -v68, v12, v2
	v_fma_f32 v2, -v70, v13, v2
	v_fma_f32 v2, -v72, v14, v2
	v_fma_f32 v2, -v74, v15, v2
	v_fma_f32 v2, -v76, v8, v2
	v_fma_f32 v2, -v78, v9, v2
	v_fma_f32 v2, -v80, v10, v2
	v_fma_f32 v2, -v82, v11, v2
	v_fma_f32 v2, -v84, v4, v2
	v_fma_f32 v2, -v86, v5, v2
	v_fma_f32 v2, -v88, v6, v2
	v_fma_f32 v2, -v90, v7, v2
	v_fma_f32 v0, -v109, v0, v2
	s_and_b64 vcc, exec, s[52:53]
	v_fma_f32 v111, -v110, v1, v0
	s_cbranch_vccnz .LBB0_521
	v_cvt_pk_bf16_f32 v0, v111, s0
	global_store_short v[32:33], v0, off
.LBB0_521:
	v_lshl_add_u64 v[32:33], v[32:33], 0, s[0:1]
	ds_read_u16 v34, v108 offset:8432
	ds_read_b32 v35, v107 offset:124
	ds_read_b32 v234, v106 offset:124
	ds_read_b128 v[28:31], v54 offset:60160
	ds_read_b128 v[24:27], v54 offset:60176
	ds_read_b128 v[20:23], v54 offset:60192
	ds_read_b128 v[16:19], v54 offset:60208
	ds_read_b128 v[12:15], v54 offset:60224
	ds_read_b128 v[8:11], v54 offset:60240
	ds_read_b128 v[0:3], v54 offset:60256
	ds_read_b128 v[4:7], v54 offset:60272
	s_waitcnt lgkmcnt(8)
	s_and_b64 vcc, exec, s[50:51]
	v_lshlrev_b32_e32 v235, 16, v34
	v_mul_f32_e32 v235, v35, v235
	s_cbranch_vccnz .LBB0_523
	v_mul_f32_e32 v34, 0x3fb8aa3b, v234
	v_exp_f32_e32 v34, v34
	s_nop 0
	v_mul_f32_e32 v235, v235, v34
; __device__ __forceinline__ bf16_t f2bf(float f) { return (bf16_t)(cvt_pk_bf16(f, 0.f) & 0xffffu); }
; __device__ __forceinline__ float bf2f(bf16_t b) { return __uint_as_float(((unsigned)b) << 16); }
; template <int I>
; __device__ __forceinline__ void solve_rows(float (&x)[64], const f32x4* A4, const bf16_t* src, const float* sBeta, const float* sGam, int part, bf16_t* dst, int nvalid) {
;     if constexpr (I < 64) {
;         f32x4 a4[(I + 3) / 4 + 1];
; #pragma unroll
;         for (int q = 0; q < (I + 3) / 4; ++q) a4[q] = A4[I * 16 + q];
;         float a = bf2f(src[I * 136]) * sBeta[I];
;         if (part == 1) a *= __expf(sGam[I]);
; #pragma unroll
;         for (int j = 0; j < I; ++j) a -= a4[j >> 2][j & 3] * x[j];
;         x[I] = a;
;         if (I < nvalid) *dst = f2bf(a);
;         dst += 1024;
;         asm volatile("" : "+v"(dst) :: "memory");
;         solve_rows<I + 1>(x, A4, src, sBeta, sGam, part, dst, nvalid);
.LBB0_523:
	s_waitcnt lgkmcnt(0)
	v_fma_f32 v7, -v64, v28, v235
	v_fma_f32 v7, -v65, v29, v7
	v_fma_f32 v7, -v67, v30, v7
	v_fma_f32 v7, -v69, v31, v7
	v_fma_f32 v7, -v71, v24, v7
	v_fma_f32 v7, -v73, v25, v7
	v_fma_f32 v7, -v75, v26, v7
	v_fma_f32 v7, -v77, v27, v7
	v_fma_f32 v7, -v79, v20, v7
	v_fma_f32 v7, -v81, v21, v7
	v_fma_f32 v7, -v83, v22, v7
	v_fma_f32 v7, -v85, v23, v7
	v_fma_f32 v7, -v87, v16, v7
	v_fma_f32 v7, -v89, v17, v7
	v_fma_f32 v7, -v91, v18, v7
	v_fma_f32 v7, -v66, v19, v7
	v_fma_f32 v7, -v68, v12, v7
	v_fma_f32 v7, -v70, v13, v7
	v_fma_f32 v7, -v72, v14, v7
	v_fma_f32 v7, -v74, v15, v7
	v_fma_f32 v7, -v76, v8, v7
	v_fma_f32 v7, -v78, v9, v7
	v_fma_f32 v7, -v80, v10, v7
	v_fma_f32 v7, -v82, v11, v7
	v_fma_f32 v0, -v84, v0, v7
	v_fma_f32 v0, -v86, v1, v0
	v_fma_f32 v0, -v88, v2, v0
	v_fma_f32 v0, -v90, v3, v0
	v_fma_f32 v0, -v109, v4, v0
	v_fma_f32 v0, -v110, v5, v0
	s_and_b64 vcc, exec, s[52:53]
	v_fma_f32 v112, -v111, v6, v0
	s_cbranch_vccnz .LBB0_525
	v_cvt_pk_bf16_f32 v0, v112, s0
	global_store_short v[32:33], v0, off
.LBB0_525:
	v_lshl_add_u64 v[32:33], v[32:33], 0, s[0:1]
	ds_read_u16 v34, v108 offset:8704
	ds_read_b32 v35, v107 offset:128
	ds_read_b32 v234, v106 offset:128
	ds_read_b128 v[28:31], v54 offset:60416
	ds_read_b128 v[24:27], v54 offset:60432
	ds_read_b128 v[20:23], v54 offset:60448
	ds_read_b128 v[16:19], v54 offset:60464
	ds_read_b128 v[12:15], v54 offset:60480
	ds_read_b128 v[8:11], v54 offset:60496
	ds_read_b128 v[0:3], v54 offset:60512
	ds_read_b128 v[4:7], v54 offset:60528
	s_waitcnt lgkmcnt(8)
	s_and_b64 vcc, exec, s[50:51]
	v_lshlrev_b32_e32 v34, 16, v34
	v_mul_f32_e32 v34, v35, v34
	s_cbranch_vccnz .LBB0_527
	v_mul_f32_e32 v35, 0x3fb8aa3b, v234
	v_exp_f32_e32 v35, v35
	s_nop 0
	v_mul_f32_e32 v34, v34, v35
.LBB0_527:
	s_waitcnt lgkmcnt(7)
	v_fma_f32 v28, -v64, v28, v34
	v_fma_f32 v28, -v65, v29, v28
	v_fma_f32 v28, -v67, v30, v28
	v_fma_f32 v28, -v69, v31, v28
	s_waitcnt lgkmcnt(6)
	v_fma_f32 v24, -v71, v24, v28
	v_fma_f32 v24, -v73, v25, v24
	v_fma_f32 v24, -v75, v26, v24
	v_fma_f32 v24, -v77, v27, v24
	s_waitcnt lgkmcnt(5)
	v_fma_f32 v20, -v79, v20, v24
	v_fma_f32 v20, -v81, v21, v20
	v_fma_f32 v20, -v83, v22, v20
	v_fma_f32 v20, -v85, v23, v20
	s_waitcnt lgkmcnt(4)
	v_fma_f32 v16, -v87, v16, v20
	v_fma_f32 v16, -v89, v17, v16
	v_fma_f32 v16, -v91, v18, v16
	v_fma_f32 v16, -v66, v19, v16
	s_waitcnt lgkmcnt(3)
	v_fma_f32 v12, -v68, v12, v16
	v_fma_f32 v12, -v70, v13, v12
	v_fma_f32 v12, -v72, v14, v12
	v_fma_f32 v12, -v74, v15, v12
	s_waitcnt lgkmcnt(2)
	v_fma_f32 v8, -v76, v8, v12
	v_fma_f32 v8, -v78, v9, v8
	v_fma_f32 v8, -v80, v10, v8
	v_fma_f32 v8, -v82, v11, v8
	s_waitcnt lgkmcnt(1)
	v_fma_f32 v0, -v84, v0, v8
	v_fma_f32 v0, -v86, v1, v0
	v_fma_f32 v0, -v88, v2, v0
	v_fma_f32 v0, -v90, v3, v0
	s_waitcnt lgkmcnt(0)
	v_fma_f32 v0, -v109, v4, v0
	v_fma_f32 v0, -v110, v5, v0
	v_fma_f32 v0, -v111, v6, v0
	s_and_b64 vcc, exec, s[52:53]
	v_fma_f32 v113, -v112, v7, v0
	s_cbranch_vccnz .LBB0_529
	v_cvt_pk_bf16_f32 v0, v113, s0
	global_store_short v[32:33], v0, off
.LBB0_529:
	v_lshl_add_u64 v[36:37], v[32:33], 0, s[0:1]
	ds_read_u16 v235, v108 offset:8976
	ds_read_b32 v239, v107 offset:132
	ds_read_b32 v234, v106 offset:132
	ds_read_b128 v[28:31], v54 offset:60672
	ds_read_b128 v[32:35], v54 offset:60688
	ds_read_b128 v[24:27], v54 offset:60704
	ds_read_b128 v[20:23], v54 offset:60720
	ds_read_b128 v[16:19], v54 offset:60736
	ds_read_b128 v[12:15], v54 offset:60752
	ds_read_b128 v[8:11], v54 offset:60768
	ds_read_b128 v[4:7], v54 offset:60784
	ds_read_b128 v[0:3], v54 offset:60800
	s_waitcnt lgkmcnt(9)
	s_and_b64 vcc, exec, s[50:51]
	v_lshlrev_b32_e32 v235, 16, v235
	v_mul_f32_e32 v235, v239, v235
	s_cbranch_vccnz .LBB0_531
	v_mul_f32_e32 v239, 0x3fb8aa3b, v234
	v_exp_f32_e32 v239, v239
	s_nop 0
	v_mul_f32_e32 v235, v235, v239
.LBB0_531:
	s_waitcnt lgkmcnt(0)
	v_fma_f32 v1, -v64, v28, v235
	v_fma_f32 v1, -v65, v29, v1
	v_fma_f32 v1, -v67, v30, v1
	v_fma_f32 v1, -v69, v31, v1
	v_fma_f32 v1, -v71, v32, v1
	v_fma_f32 v1, -v73, v33, v1
	v_fma_f32 v1, -v75, v34, v1
	v_fma_f32 v1, -v77, v35, v1
	v_fma_f32 v1, -v79, v24, v1
	v_fma_f32 v1, -v81, v25, v1
	v_fma_f32 v1, -v83, v26, v1
	v_fma_f32 v1, -v85, v27, v1
	v_fma_f32 v1, -v87, v20, v1
	v_fma_f32 v1, -v89, v21, v1
	v_fma_f32 v1, -v91, v22, v1
	v_fma_f32 v1, -v66, v23, v1
	v_fma_f32 v1, -v68, v16, v1
	v_fma_f32 v1, -v70, v17, v1
	v_fma_f32 v1, -v72, v18, v1
	v_fma_f32 v1, -v74, v19, v1
	v_fma_f32 v1, -v76, v12, v1
	v_fma_f32 v1, -v78, v13, v1
	v_fma_f32 v1, -v80, v14, v1
	v_fma_f32 v1, -v82, v15, v1
	v_fma_f32 v1, -v84, v8, v1
	v_fma_f32 v1, -v86, v9, v1
	v_fma_f32 v1, -v88, v10, v1
	v_fma_f32 v1, -v90, v11, v1
	v_fma_f32 v1, -v109, v4, v1
	v_fma_f32 v1, -v110, v5, v1
	v_fma_f32 v1, -v111, v6, v1
	v_fma_f32 v1, -v112, v7, v1
	s_and_b64 vcc, exec, s[52:53]
	v_fma_f32 v114, -v113, v0, v1
	s_cbranch_vccnz .LBB0_533
	v_cvt_pk_bf16_f32 v0, v114, s0
	global_store_short v[36:37], v0, off
.LBB0_533:
	v_lshl_add_u64 v[36:37], v[36:37], 0, s[0:1]
	ds_read_u16 v235, v108 offset:9248
	ds_read_b32 v239, v107 offset:136
	ds_read_b32 v234, v106 offset:136
	ds_read_b128 v[28:31], v54 offset:60928
	ds_read_b128 v[32:35], v54 offset:60944
	ds_read_b128 v[24:27], v54 offset:60960
	ds_read_b128 v[20:23], v54 offset:60976
	ds_read_b128 v[16:19], v54 offset:60992
	ds_read_b128 v[12:15], v54 offset:61008
	ds_read_b128 v[8:11], v54 offset:61024
	ds_read_b128 v[4:7], v54 offset:61040
	ds_read_b128 v[0:3], v54 offset:61056
	s_waitcnt lgkmcnt(9)
	s_and_b64 vcc, exec, s[50:51]
	v_lshlrev_b32_e32 v235, 16, v235
	v_mul_f32_e32 v235, v239, v235
	s_cbranch_vccnz .LBB0_535
	v_mul_f32_e32 v239, 0x3fb8aa3b, v234
	v_exp_f32_e32 v239, v239
	s_nop 0
	v_mul_f32_e32 v235, v235, v239
; __device__ __forceinline__ bf16_t f2bf(float f) { return (bf16_t)(cvt_pk_bf16(f, 0.f) & 0xffffu); }
; __device__ __forceinline__ float bf2f(bf16_t b) { return __uint_as_float(((unsigned)b) << 16); }
; template <int I>
; __device__ __forceinline__ void solve_rows(float (&x)[64], const f32x4* A4, const bf16_t* src, const float* sBeta, const float* sGam, int part, bf16_t* dst, int nvalid) {
;     ...
;         for (int q = 0; q < (I + 3) / 4; ++q) a4[q] = A4[I * 16 + q];
;         float a = bf2f(src[I * 136]) * sBeta[I];
;         if (part == 1) a *= __expf(sGam[I]);
; #pragma unroll
;         for (int j = 0; j < I; ++j) a -= a4[j >> 2][j & 3] * x[j];
;         x[I] = a;
;         if (I < nvalid) *dst = f2bf(a);
;         dst += 1024;
;         asm volatile("" : "+v"(dst) :: "memory");
.LBB0_535:
	s_waitcnt lgkmcnt(0)
	v_fma_f32 v2, -v64, v28, v235
	v_fma_f32 v2, -v65, v29, v2
	v_fma_f32 v2, -v67, v30, v2
	v_fma_f32 v2, -v69, v31, v2
	v_fma_f32 v2, -v71, v32, v2
	v_fma_f32 v2, -v73, v33, v2
	v_fma_f32 v2, -v75, v34, v2
	v_fma_f32 v2, -v77, v35, v2
	v_fma_f32 v2, -v79, v24, v2
	v_fma_f32 v2, -v81, v25, v2
	v_fma_f32 v2, -v83, v26, v2
	v_fma_f32 v2, -v85, v27, v2
	v_fma_f32 v2, -v87, v20, v2
	v_fma_f32 v2, -v89, v21, v2
	v_fma_f32 v2, -v91, v22, v2
	v_fma_f32 v2, -v66, v23, v2
	v_fma_f32 v2, -v68, v16, v2
	v_fma_f32 v2, -v70, v17, v2
	v_fma_f32 v2, -v72, v18, v2
	v_fma_f32 v2, -v74, v19, v2
	v_fma_f32 v2, -v76, v12, v2
	v_fma_f32 v2, -v78, v13, v2
	v_fma_f32 v2, -v80, v14, v2
	v_fma_f32 v2, -v82, v15, v2
	v_fma_f32 v2, -v84, v8, v2
	v_fma_f32 v2, -v86, v9, v2
	v_fma_f32 v2, -v88, v10, v2
	v_fma_f32 v2, -v90, v11, v2
	v_fma_f32 v2, -v109, v4, v2
	v_fma_f32 v2, -v110, v5, v2
	v_fma_f32 v2, -v111, v6, v2
	v_fma_f32 v2, -v112, v7, v2
	v_fma_f32 v0, -v113, v0, v2
	s_and_b64 vcc, exec, s[52:53]
	v_fma_f32 v115, -v114, v1, v0
	s_cbranch_vccnz .LBB0_537
	v_cvt_pk_bf16_f32 v0, v115, s0
	global_store_short v[36:37], v0, off
.LBB0_537:
	v_lshl_add_u64 v[36:37], v[36:37], 0, s[0:1]
	ds_read_u16 v38, v108 offset:9520
	ds_read_b32 v39, v107 offset:140
	ds_read_b32 v234, v106 offset:140
	ds_read_b128 v[32:35], v54 offset:61184
	ds_read_b128 v[28:31], v54 offset:61200
	ds_read_b128 v[24:27], v54 offset:61216
	ds_read_b128 v[20:23], v54 offset:61232
	ds_read_b128 v[16:19], v54 offset:61248
	ds_read_b128 v[8:11], v54 offset:61264
	ds_read_b128 v[4:7], v54 offset:61280
	ds_read_b128 v[12:15], v54 offset:61296
	ds_read_b128 v[0:3], v54 offset:61312
	s_waitcnt lgkmcnt(9)
	v_lshlrev_b32_e32 v235, 16, v38
	s_and_b64 vcc, exec, s[50:51]
	v_mul_f32_e32 v235, v39, v235
	s_cbranch_vccnz .LBB0_539
	v_mul_f32_e32 v38, 0x3fb8aa3b, v234
	v_exp_f32_e32 v38, v38
	s_nop 0
	v_mul_f32_e32 v235, v235, v38
.LBB0_539:
	s_waitcnt lgkmcnt(0)
	v_fma_f32 v3, -v64, v32, v235
	v_fma_f32 v3, -v65, v33, v3
	v_fma_f32 v3, -v67, v34, v3
	v_fma_f32 v3, -v69, v35, v3
	v_fma_f32 v3, -v71, v28, v3
	v_fma_f32 v3, -v73, v29, v3
	v_fma_f32 v3, -v75, v30, v3
	v_fma_f32 v3, -v77, v31, v3
	v_fma_f32 v3, -v79, v24, v3
	v_fma_f32 v3, -v81, v25, v3
	v_fma_f32 v3, -v83, v26, v3
	v_fma_f32 v3, -v85, v27, v3
	v_fma_f32 v3, -v87, v20, v3
	v_fma_f32 v3, -v89, v21, v3
	v_fma_f32 v3, -v91, v22, v3
	v_fma_f32 v3, -v66, v23, v3
	v_fma_f32 v3, -v68, v16, v3
	v_fma_f32 v3, -v70, v17, v3
	v_fma_f32 v3, -v72, v18, v3
	v_fma_f32 v3, -v74, v19, v3
	v_fma_f32 v3, -v76, v8, v3
	v_fma_f32 v3, -v78, v9, v3
	v_fma_f32 v3, -v80, v10, v3
	v_fma_f32 v3, -v82, v11, v3
	v_fma_f32 v3, -v84, v4, v3
	v_fma_f32 v3, -v86, v5, v3
	v_fma_f32 v3, -v88, v6, v3
	v_fma_f32 v3, -v90, v7, v3
	v_fma_f32 v3, -v109, v12, v3
	v_fma_f32 v3, -v110, v13, v3
	v_fma_f32 v3, -v111, v14, v3
	v_fma_f32 v3, -v112, v15, v3
	v_fma_f32 v0, -v113, v0, v3
	v_fma_f32 v0, -v114, v1, v0
	s_and_b64 vcc, exec, s[52:53]
	v_fma_f32 v116, -v115, v2, v0
	s_cbranch_vccnz .LBB0_541
	v_cvt_pk_bf16_f32 v0, v116, s0
	global_store_short v[36:37], v0, off
.LBB0_541:
	v_lshl_add_u64 v[36:37], v[36:37], 0, s[0:1]
	ds_read_u16 v38, v108 offset:9792
	ds_read_b32 v39, v107 offset:144
	ds_read_b32 v234, v106 offset:144
	ds_read_b128 v[32:35], v54 offset:61440
	ds_read_b128 v[28:31], v54 offset:61456
	ds_read_b128 v[24:27], v54 offset:61472
	ds_read_b128 v[20:23], v54 offset:61488
	ds_read_b128 v[16:19], v54 offset:61504
	ds_read_b128 v[8:11], v54 offset:61520
	ds_read_b128 v[4:7], v54 offset:61536
	ds_read_b128 v[12:15], v54 offset:61552
	ds_read_b128 v[0:3], v54 offset:61568
	s_waitcnt lgkmcnt(9)
	v_lshlrev_b32_e32 v38, 16, v38
	s_and_b64 vcc, exec, s[50:51]
	v_mul_f32_e32 v38, v39, v38
	s_cbranch_vccnz .LBB0_543
	v_mul_f32_e32 v39, 0x3fb8aa3b, v234
	v_exp_f32_e32 v39, v39
	s_nop 0
	v_mul_f32_e32 v38, v38, v39
.LBB0_543:
	s_waitcnt lgkmcnt(8)
	v_fma_f32 v32, -v64, v32, v38
	v_fma_f32 v32, -v65, v33, v32
	v_fma_f32 v32, -v67, v34, v32
	v_fma_f32 v32, -v69, v35, v32
	s_waitcnt lgkmcnt(7)
	v_fma_f32 v28, -v71, v28, v32
	v_fma_f32 v28, -v73, v29, v28
	v_fma_f32 v28, -v75, v30, v28
	v_fma_f32 v28, -v77, v31, v28
	s_waitcnt lgkmcnt(6)
	v_fma_f32 v24, -v79, v24, v28
	v_fma_f32 v24, -v81, v25, v24
	v_fma_f32 v24, -v83, v26, v24
	v_fma_f32 v24, -v85, v27, v24
	s_waitcnt lgkmcnt(5)
	v_fma_f32 v20, -v87, v20, v24
	v_fma_f32 v20, -v89, v21, v20
	v_fma_f32 v20, -v91, v22, v20
	v_fma_f32 v20, -v66, v23, v20
	s_waitcnt lgkmcnt(4)
	v_fma_f32 v16, -v68, v16, v20
	v_fma_f32 v16, -v70, v17, v16
	v_fma_f32 v16, -v72, v18, v16
	v_fma_f32 v16, -v74, v19, v16
	s_waitcnt lgkmcnt(3)
	v_fma_f32 v8, -v76, v8, v16
	v_fma_f32 v8, -v78, v9, v8
	v_fma_f32 v8, -v80, v10, v8
	v_fma_f32 v8, -v82, v11, v8
	s_waitcnt lgkmcnt(2)
	v_fma_f32 v4, -v84, v4, v8
	v_fma_f32 v4, -v86, v5, v4
	v_fma_f32 v4, -v88, v6, v4
	v_fma_f32 v4, -v90, v7, v4
	s_waitcnt lgkmcnt(1)
	v_fma_f32 v4, -v109, v12, v4
	v_fma_f32 v4, -v110, v13, v4
	v_fma_f32 v4, -v111, v14, v4
	v_fma_f32 v4, -v112, v15, v4
	s_waitcnt lgkmcnt(0)
	v_fma_f32 v0, -v113, v0, v4
	v_fma_f32 v0, -v114, v1, v0
	v_fma_f32 v0, -v115, v2, v0
	s_and_b64 vcc, exec, s[52:53]
	v_fma_f32 v117, -v116, v3, v0
	s_cbranch_vccnz .LBB0_545
	v_cvt_pk_bf16_f32 v0, v117, s0
	global_store_short v[36:37], v0, off
; __device__ __forceinline__ bf16_t f2bf(float f) { return (bf16_t)(cvt_pk_bf16(f, 0.f) & 0xffffu); }
; __device__ __forceinline__ float bf2f(bf16_t b) { return __uint_as_float(((unsigned)b) << 16); }
; template <int I>
; __device__ __forceinline__ void solve_rows(float (&x)[64], const f32x4* A4, const bf16_t* src, const float* sBeta, const float* sGam, int part, bf16_t* dst, int nvalid) {
;     ...
;         for (int q = 0; q < (I + 3) / 4; ++q) a4[q] = A4[I * 16 + q];
;         float a = bf2f(src[I * 136]) * sBeta[I];
;         if (part == 1) a *= __expf(sGam[I]);
; #pragma unroll
;         for (int j = 0; j < I; ++j) a -= a4[j >> 2][j & 3] * x[j];
;         x[I] = a;
;         if (I < nvalid) *dst = f2bf(a);
;         dst += 1024;
;         asm volatile("" : "+v"(dst) :: "memory");
.LBB0_545:
	v_lshl_add_u64 v[40:41], v[36:37], 0, s[0:1]
	ds_read_u16 v235, v108 offset:10064
	ds_read_b32 v239, v107 offset:148
	ds_read_b32 v234, v106 offset:148
	ds_read_b128 v[32:35], v54 offset:61696
	ds_read_b128 v[36:39], v54 offset:61712
	ds_read_b128 v[28:31], v54 offset:61728
	ds_read_b128 v[24:27], v54 offset:61744
	ds_read_b128 v[20:23], v54 offset:61760
	ds_read_b128 v[16:19], v54 offset:61776
	ds_read_b128 v[12:15], v54 offset:61792
	ds_read_b128 v[8:11], v54 offset:61808
	ds_read_b128 v[4:7], v54 offset:61824
	ds_read_b128 v[0:3], v54 offset:61840
	s_waitcnt lgkmcnt(10)
	s_and_b64 vcc, exec, s[50:51]
	v_lshlrev_b32_e32 v235, 16, v235
	v_mul_f32_e32 v235, v239, v235
	s_cbranch_vccnz .LBB0_547
	v_mul_f32_e32 v239, 0x3fb8aa3b, v234
	v_exp_f32_e32 v239, v239
	s_nop 0
	v_mul_f32_e32 v235, v235, v239
.LBB0_547:
	s_waitcnt lgkmcnt(0)
	v_fma_f32 v1, -v64, v32, v235
	v_fma_f32 v1, -v65, v33, v1
	v_fma_f32 v1, -v67, v34, v1
	v_fma_f32 v1, -v69, v35, v1
	v_fma_f32 v1, -v71, v36, v1
	v_fma_f32 v1, -v73, v37, v1
	v_fma_f32 v1, -v75, v38, v1
	v_fma_f32 v1, -v77, v39, v1
	v_fma_f32 v1, -v79, v28, v1
	v_fma_f32 v1, -v81, v29, v1
	v_fma_f32 v1, -v83, v30, v1
	v_fma_f32 v1, -v85, v31, v1
	v_fma_f32 v1, -v87, v24, v1
	v_fma_f32 v1, -v89, v25, v1
	v_fma_f32 v1, -v91, v26, v1
	v_fma_f32 v1, -v66, v27, v1
	v_fma_f32 v1, -v68, v20, v1
	v_fma_f32 v1, -v70, v21, v1
	v_fma_f32 v1, -v72, v22, v1
	v_fma_f32 v1, -v74, v23, v1
	v_fma_f32 v1, -v76, v16, v1
	v_fma_f32 v1, -v78, v17, v1
	v_fma_f32 v1, -v80, v18, v1
	v_fma_f32 v1, -v82, v19, v1
	v_fma_f32 v1, -v84, v12, v1
	v_fma_f32 v1, -v86, v13, v1
	v_fma_f32 v1, -v88, v14, v1
	v_fma_f32 v1, -v90, v15, v1
	v_fma_f32 v1, -v109, v8, v1
	v_fma_f32 v1, -v110, v9, v1
	v_fma_f32 v1, -v111, v10, v1
	v_fma_f32 v1, -v112, v11, v1
	v_fma_f32 v1, -v113, v4, v1
	v_fma_f32 v1, -v114, v5, v1
	v_fma_f32 v1, -v115, v6, v1
	v_fma_f32 v1, -v116, v7, v1
	s_and_b64 vcc, exec, s[52:53]
	v_fma_f32 v118, -v117, v0, v1
	s_cbranch_vccnz .LBB0_549
	v_cvt_pk_bf16_f32 v0, v118, s0
	global_store_short v[40:41], v0, off
.LBB0_549:
	v_lshl_add_u64 v[40:41], v[40:41], 0, s[0:1]
	ds_read_u16 v235, v108 offset:10336
	ds_read_b32 v239, v107 offset:152
	ds_read_b32 v234, v106 offset:152
	ds_read_b128 v[32:35], v54 offset:61952
	ds_read_b128 v[36:39], v54 offset:61968
	ds_read_b128 v[28:31], v54 offset:61984
	ds_read_b128 v[24:27], v54 offset:62000
	ds_read_b128 v[20:23], v54 offset:62016
	ds_read_b128 v[16:19], v54 offset:62032
	ds_read_b128 v[12:15], v54 offset:62048
	ds_read_b128 v[8:11], v54 offset:62064
	ds_read_b128 v[4:7], v54 offset:62080
	ds_read_b128 v[0:3], v54 offset:62096
	s_waitcnt lgkmcnt(10)
	s_and_b64 vcc, exec, s[50:51]
	v_lshlrev_b32_e32 v235, 16, v235
	v_mul_f32_e32 v235, v239, v235
	s_cbranch_vccnz .LBB0_551
	v_mul_f32_e32 v239, 0x3fb8aa3b, v234
	v_exp_f32_e32 v239, v239
	s_nop 0
	v_mul_f32_e32 v235, v235, v239
.LBB0_551:
	s_waitcnt lgkmcnt(0)
	v_fma_f32 v2, -v64, v32, v235
	v_fma_f32 v2, -v65, v33, v2
	v_fma_f32 v2, -v67, v34, v2
	v_fma_f32 v2, -v69, v35, v2
	v_fma_f32 v2, -v71, v36, v2
	v_fma_f32 v2, -v73, v37, v2
	v_fma_f32 v2, -v75, v38, v2
	v_fma_f32 v2, -v77, v39, v2
	v_fma_f32 v2, -v79, v28, v2
	v_fma_f32 v2, -v81, v29, v2
	v_fma_f32 v2, -v83, v30, v2
	v_fma_f32 v2, -v85, v31, v2
	v_fma_f32 v2, -v87, v24, v2
	v_fma_f32 v2, -v89, v25, v2
	v_fma_f32 v2, -v91, v26, v2
	v_fma_f32 v2, -v66, v27, v2
	v_fma_f32 v2, -v68, v20, v2
	v_fma_f32 v2, -v70, v21, v2
	v_fma_f32 v2, -v72, v22, v2
	v_fma_f32 v2, -v74, v23, v2
	v_fma_f32 v2, -v76, v16, v2
	v_fma_f32 v2, -v78, v17, v2
	v_fma_f32 v2, -v80, v18, v2
	v_fma_f32 v2, -v82, v19, v2
	v_fma_f32 v2, -v84, v12, v2
	v_fma_f32 v2, -v86, v13, v2
	v_fma_f32 v2, -v88, v14, v2
	v_fma_f32 v2, -v90, v15, v2
	v_fma_f32 v2, -v109, v8, v2
	v_fma_f32 v2, -v110, v9, v2
	v_fma_f32 v2, -v111, v10, v2
	v_fma_f32 v2, -v112, v11, v2
	v_fma_f32 v2, -v113, v4, v2
	v_fma_f32 v2, -v114, v5, v2
	v_fma_f32 v2, -v115, v6, v2
	v_fma_f32 v2, -v116, v7, v2
	v_fma_f32 v0, -v117, v0, v2
	s_and_b64 vcc, exec, s[52:53]
	v_fma_f32 v119, -v118, v1, v0
	s_cbranch_vccnz .LBB0_553
	v_cvt_pk_bf16_f32 v0, v119, s0
	global_store_short v[40:41], v0, off
.LBB0_553:
	v_lshl_add_u64 v[40:41], v[40:41], 0, s[0:1]
	ds_read_u16 v42, v108 offset:10608
	ds_read_b32 v43, v107 offset:156
	ds_read_b32 v234, v106 offset:156
	ds_read_b128 v[36:39], v54 offset:62208
	ds_read_b128 v[32:35], v54 offset:62224
	ds_read_b128 v[28:31], v54 offset:62240
	ds_read_b128 v[24:27], v54 offset:62256
	ds_read_b128 v[20:23], v54 offset:62272
	ds_read_b128 v[16:19], v54 offset:62288
	ds_read_b128 v[12:15], v54 offset:62304
	ds_read_b128 v[8:11], v54 offset:62320
	ds_read_b128 v[0:3], v54 offset:62336
	ds_read_b128 v[4:7], v54 offset:62352
	s_waitcnt lgkmcnt(10)
	s_and_b64 vcc, exec, s[50:51]
	v_lshlrev_b32_e32 v235, 16, v42
	v_mul_f32_e32 v235, v43, v235
	s_cbranch_vccnz .LBB0_555
	v_mul_f32_e32 v42, 0x3fb8aa3b, v234
	v_exp_f32_e32 v42, v42
	s_nop 0
	v_mul_f32_e32 v235, v235, v42
.LBB0_555:
	s_waitcnt lgkmcnt(0)
	v_fma_f32 v7, -v64, v36, v235
	v_fma_f32 v7, -v65, v37, v7
	v_fma_f32 v7, -v67, v38, v7
	v_fma_f32 v7, -v69, v39, v7
	v_fma_f32 v7, -v71, v32, v7
	v_fma_f32 v7, -v73, v33, v7
	v_fma_f32 v7, -v75, v34, v7
	v_fma_f32 v7, -v77, v35, v7
	v_fma_f32 v7, -v79, v28, v7
	v_fma_f32 v7, -v81, v29, v7
	v_fma_f32 v7, -v83, v30, v7
	v_fma_f32 v7, -v85, v31, v7
	v_fma_f32 v7, -v87, v24, v7
	v_fma_f32 v7, -v89, v25, v7
	v_fma_f32 v7, -v91, v26, v7
	v_fma_f32 v7, -v66, v27, v7
	v_fma_f32 v7, -v68, v20, v7
	v_fma_f32 v7, -v70, v21, v7
	v_fma_f32 v7, -v72, v22, v7
	v_fma_f32 v7, -v74, v23, v7
	v_fma_f32 v7, -v76, v16, v7
	v_fma_f32 v7, -v78, v17, v7
	v_fma_f32 v7, -v80, v18, v7
	v_fma_f32 v7, -v82, v19, v7
	v_fma_f32 v7, -v84, v12, v7
	v_fma_f32 v7, -v86, v13, v7
	v_fma_f32 v7, -v88, v14, v7
	v_fma_f32 v7, -v90, v15, v7
	v_fma_f32 v7, -v109, v8, v7
	v_fma_f32 v7, -v110, v9, v7
	v_fma_f32 v7, -v111, v10, v7
	v_fma_f32 v7, -v112, v11, v7
	v_fma_f32 v0, -v113, v0, v7
	v_fma_f32 v0, -v114, v1, v0
	v_fma_f32 v0, -v115, v2, v0
	v_fma_f32 v0, -v116, v3, v0
	v_fma_f32 v0, -v117, v4, v0
	v_fma_f32 v0, -v118, v5, v0
	s_and_b64 vcc, exec, s[52:53]
	v_fma_f32 v120, -v119, v6, v0
	s_cbranch_vccnz .LBB0_557
	v_cvt_pk_bf16_f32 v0, v120, s0
	global_store_short v[40:41], v0, off
; __device__ __forceinline__ bf16_t f2bf(float f) { return (bf16_t)(cvt_pk_bf16(f, 0.f) & 0xffffu); }
; __device__ __forceinline__ float bf2f(bf16_t b) { return __uint_as_float(((unsigned)b) << 16); }
; template <int I>
; __device__ __forceinline__ void solve_rows(float (&x)[64], const f32x4* A4, const bf16_t* src, const float* sBeta, const float* sGam, int part, bf16_t* dst, int nvalid) {
;     ...
;         for (int q = 0; q < (I + 3) / 4; ++q) a4[q] = A4[I * 16 + q];
;         float a = bf2f(src[I * 136]) * sBeta[I];
;         if (part == 1) a *= __expf(sGam[I]);
; #pragma unroll
;         for (int j = 0; j < I; ++j) a -= a4[j >> 2][j & 3] * x[j];
;         x[I] = a;
;         if (I < nvalid) *dst = f2bf(a);
;         dst += 1024;
;         asm volatile("" : "+v"(dst) :: "memory");
.LBB0_557:
	v_lshl_add_u64 v[40:41], v[40:41], 0, s[0:1]
	ds_read_u16 v42, v108 offset:10880
	ds_read_b32 v43, v107 offset:160
	ds_read_b32 v234, v106 offset:160
	ds_read_b128 v[36:39], v54 offset:62464
	ds_read_b128 v[32:35], v54 offset:62480
	ds_read_b128 v[28:31], v54 offset:62496
	ds_read_b128 v[24:27], v54 offset:62512
	ds_read_b128 v[20:23], v54 offset:62528
	ds_read_b128 v[16:19], v54 offset:62544
	ds_read_b128 v[12:15], v54 offset:62560
	ds_read_b128 v[8:11], v54 offset:62576
	ds_read_b128 v[0:3], v54 offset:62592
	ds_read_b128 v[4:7], v54 offset:62608
	s_waitcnt lgkmcnt(10)
	s_and_b64 vcc, exec, s[50:51]
	v_lshlrev_b32_e32 v42, 16, v42
	v_mul_f32_e32 v42, v43, v42
	s_cbranch_vccnz .LBB0_559
	v_mul_f32_e32 v43, 0x3fb8aa3b, v234
	v_exp_f32_e32 v43, v43
	s_nop 0
	v_mul_f32_e32 v42, v42, v43
.LBB0_559:
	s_waitcnt lgkmcnt(9)
	v_fma_f32 v36, -v64, v36, v42
	v_fma_f32 v36, -v65, v37, v36
	v_fma_f32 v36, -v67, v38, v36
	v_fma_f32 v36, -v69, v39, v36
	s_waitcnt lgkmcnt(8)
	v_fma_f32 v32, -v71, v32, v36
	v_fma_f32 v32, -v73, v33, v32
	v_fma_f32 v32, -v75, v34, v32
	v_fma_f32 v32, -v77, v35, v32
	s_waitcnt lgkmcnt(7)
	v_fma_f32 v28, -v79, v28, v32
	v_fma_f32 v28, -v81, v29, v28
	v_fma_f32 v28, -v83, v30, v28
	v_fma_f32 v28, -v85, v31, v28
	s_waitcnt lgkmcnt(6)
	v_fma_f32 v24, -v87, v24, v28
	v_fma_f32 v24, -v89, v25, v24
	v_fma_f32 v24, -v91, v26, v24
	v_fma_f32 v24, -v66, v27, v24
	s_waitcnt lgkmcnt(5)
	v_fma_f32 v20, -v68, v20, v24
	v_fma_f32 v20, -v70, v21, v20
	v_fma_f32 v20, -v72, v22, v20
	v_fma_f32 v20, -v74, v23, v20
	s_waitcnt lgkmcnt(4)
	v_fma_f32 v16, -v76, v16, v20
	v_fma_f32 v16, -v78, v17, v16
	v_fma_f32 v16, -v80, v18, v16
	v_fma_f32 v16, -v82, v19, v16
	s_waitcnt lgkmcnt(3)
	v_fma_f32 v12, -v84, v12, v16
	v_fma_f32 v12, -v86, v13, v12
	v_fma_f32 v12, -v88, v14, v12
	v_fma_f32 v12, -v90, v15, v12
	s_waitcnt lgkmcnt(2)
	v_fma_f32 v8, -v109, v8, v12
	v_fma_f32 v8, -v110, v9, v8
	v_fma_f32 v8, -v111, v10, v8
	v_fma_f32 v8, -v112, v11, v8
	s_waitcnt lgkmcnt(1)
	v_fma_f32 v0, -v113, v0, v8
	v_fma_f32 v0, -v114, v1, v0
	v_fma_f32 v0, -v115, v2, v0
	v_fma_f32 v0, -v116, v3, v0
	s_waitcnt lgkmcnt(0)
	v_fma_f32 v0, -v117, v4, v0
	v_fma_f32 v0, -v118, v5, v0
	v_fma_f32 v0, -v119, v6, v0
	s_and_b64 vcc, exec, s[52:53]
	v_fma_f32 v121, -v120, v7, v0
	s_cbranch_vccnz .LBB0_561
	v_cvt_pk_bf16_f32 v0, v121, s0
	global_store_short v[40:41], v0, off
.LBB0_561:
	v_lshl_add_u64 v[44:45], v[40:41], 0, s[0:1]
	ds_read_u16 v235, v108 offset:11152
	ds_read_b32 v239, v107 offset:164
	ds_read_b32 v234, v106 offset:164
	ds_read_b128 v[36:39], v54 offset:62720
	ds_read_b128 v[40:43], v54 offset:62736
	ds_read_b128 v[32:35], v54 offset:62752
	ds_read_b128 v[28:31], v54 offset:62768
	ds_read_b128 v[24:27], v54 offset:62784
	ds_read_b128 v[20:23], v54 offset:62800
	ds_read_b128 v[16:19], v54 offset:62816
	ds_read_b128 v[12:15], v54 offset:62832
	ds_read_b128 v[8:11], v54 offset:62848
	ds_read_b128 v[4:7], v54 offset:62864
	ds_read_b128 v[0:3], v54 offset:62880
	s_waitcnt lgkmcnt(11)
	s_and_b64 vcc, exec, s[50:51]
	v_lshlrev_b32_e32 v235, 16, v235
	v_mul_f32_e32 v235, v239, v235
	s_cbranch_vccnz .LBB0_563
	v_mul_f32_e32 v239, 0x3fb8aa3b, v234
	v_exp_f32_e32 v239, v239
	s_nop 0
	v_mul_f32_e32 v235, v235, v239
.LBB0_563:
	s_waitcnt lgkmcnt(0)
	v_fma_f32 v1, -v64, v36, v235
	v_fma_f32 v1, -v65, v37, v1
	v_fma_f32 v1, -v67, v38, v1
	v_fma_f32 v1, -v69, v39, v1
	v_fma_f32 v1, -v71, v40, v1
	v_fma_f32 v1, -v73, v41, v1
	v_fma_f32 v1, -v75, v42, v1
	v_fma_f32 v1, -v77, v43, v1
	v_fma_f32 v1, -v79, v32, v1
	v_fma_f32 v1, -v81, v33, v1
	v_fma_f32 v1, -v83, v34, v1
	v_fma_f32 v1, -v85, v35, v1
	v_fma_f32 v1, -v87, v28, v1
	v_fma_f32 v1, -v89, v29, v1
	v_fma_f32 v1, -v91, v30, v1
	v_fma_f32 v1, -v66, v31, v1
	v_fma_f32 v1, -v68, v24, v1
	v_fma_f32 v1, -v70, v25, v1
	v_fma_f32 v1, -v72, v26, v1
	v_fma_f32 v1, -v74, v27, v1
	v_fma_f32 v1, -v76, v20, v1
	v_fma_f32 v1, -v78, v21, v1
	v_fma_f32 v1, -v80, v22, v1
	v_fma_f32 v1, -v82, v23, v1
	v_fma_f32 v1, -v84, v16, v1
	v_fma_f32 v1, -v86, v17, v1
	v_fma_f32 v1, -v88, v18, v1
	v_fma_f32 v1, -v90, v19, v1
	v_fma_f32 v1, -v109, v12, v1
	v_fma_f32 v1, -v110, v13, v1
	v_fma_f32 v1, -v111, v14, v1
	v_fma_f32 v1, -v112, v15, v1
	v_fma_f32 v1, -v113, v8, v1
	v_fma_f32 v1, -v114, v9, v1
	v_fma_f32 v1, -v115, v10, v1
	v_fma_f32 v1, -v116, v11, v1
	v_fma_f32 v1, -v117, v4, v1
	v_fma_f32 v1, -v118, v5, v1
	v_fma_f32 v1, -v119, v6, v1
	v_fma_f32 v1, -v120, v7, v1
	s_and_b64 vcc, exec, s[52:53]
	v_fma_f32 v122, -v121, v0, v1
	s_cbranch_vccnz .LBB0_565
	v_cvt_pk_bf16_f32 v0, v122, s0
	global_store_short v[44:45], v0, off
.LBB0_565:
	v_lshl_add_u64 v[44:45], v[44:45], 0, s[0:1]
	ds_read_u16 v235, v108 offset:11424
	ds_read_b32 v239, v107 offset:168
	ds_read_b32 v234, v106 offset:168
	ds_read_b128 v[36:39], v54 offset:62976
	ds_read_b128 v[40:43], v54 offset:62992
	ds_read_b128 v[32:35], v54 offset:63008
	ds_read_b128 v[28:31], v54 offset:63024
	ds_read_b128 v[24:27], v54 offset:63040
	ds_read_b128 v[20:23], v54 offset:63056
	ds_read_b128 v[16:19], v54 offset:63072
	ds_read_b128 v[12:15], v54 offset:63088
	ds_read_b128 v[8:11], v54 offset:63104
	ds_read_b128 v[4:7], v54 offset:63120
	ds_read_b128 v[0:3], v54 offset:63136
	s_waitcnt lgkmcnt(11)
	s_and_b64 vcc, exec, s[50:51]
	v_lshlrev_b32_e32 v235, 16, v235
	v_mul_f32_e32 v235, v239, v235
	s_cbranch_vccnz .LBB0_567
	v_mul_f32_e32 v239, 0x3fb8aa3b, v234
	v_exp_f32_e32 v239, v239
	s_nop 0
	v_mul_f32_e32 v235, v235, v239
; __device__ __forceinline__ bf16_t f2bf(float f) { return (bf16_t)(cvt_pk_bf16(f, 0.f) & 0xffffu); }
; __device__ __forceinline__ float bf2f(bf16_t b) { return __uint_as_float(((unsigned)b) << 16); }
; template <int I>
; __device__ __forceinline__ void solve_rows(float (&x)[64], const f32x4* A4, const bf16_t* src, const float* sBeta, const float* sGam, int part, bf16_t* dst, int nvalid) {
;     ...
;         for (int q = 0; q < (I + 3) / 4; ++q) a4[q] = A4[I * 16 + q];
;         float a = bf2f(src[I * 136]) * sBeta[I];
;         if (part == 1) a *= __expf(sGam[I]);
; #pragma unroll
;         for (int j = 0; j < I; ++j) a -= a4[j >> 2][j & 3] * x[j];
;         x[I] = a;
;         if (I < nvalid) *dst = f2bf(a);
;         dst += 1024;
;         asm volatile("" : "+v"(dst) :: "memory");
.LBB0_567:
	s_waitcnt lgkmcnt(0)
	v_fma_f32 v2, -v64, v36, v235
	v_fma_f32 v2, -v65, v37, v2
	v_fma_f32 v2, -v67, v38, v2
	v_fma_f32 v2, -v69, v39, v2
	v_fma_f32 v2, -v71, v40, v2
	v_fma_f32 v2, -v73, v41, v2
	v_fma_f32 v2, -v75, v42, v2
	v_fma_f32 v2, -v77, v43, v2
	v_fma_f32 v2, -v79, v32, v2
	v_fma_f32 v2, -v81, v33, v2
	v_fma_f32 v2, -v83, v34, v2
	v_fma_f32 v2, -v85, v35, v2
	v_fma_f32 v2, -v87, v28, v2
	v_fma_f32 v2, -v89, v29, v2
	v_fma_f32 v2, -v91, v30, v2
	v_fma_f32 v2, -v66, v31, v2
	v_fma_f32 v2, -v68, v24, v2
	v_fma_f32 v2, -v70, v25, v2
	v_fma_f32 v2, -v72, v26, v2
	v_fma_f32 v2, -v74, v27, v2
	v_fma_f32 v2, -v76, v20, v2
	v_fma_f32 v2, -v78, v21, v2
	v_fma_f32 v2, -v80, v22, v2
	v_fma_f32 v2, -v82, v23, v2
	v_fma_f32 v2, -v84, v16, v2
	v_fma_f32 v2, -v86, v17, v2
	v_fma_f32 v2, -v88, v18, v2
	v_fma_f32 v2, -v90, v19, v2
	v_fma_f32 v2, -v109, v12, v2
	v_fma_f32 v2, -v110, v13, v2
	v_fma_f32 v2, -v111, v14, v2
	v_fma_f32 v2, -v112, v15, v2
	v_fma_f32 v2, -v113, v8, v2
	v_fma_f32 v2, -v114, v9, v2
	v_fma_f32 v2, -v115, v10, v2
	v_fma_f32 v2, -v116, v11, v2
	v_fma_f32 v2, -v117, v4, v2
	v_fma_f32 v2, -v118, v5, v2
	v_fma_f32 v2, -v119, v6, v2
	v_fma_f32 v2, -v120, v7, v2
	v_fma_f32 v0, -v121, v0, v2
	s_and_b64 vcc, exec, s[52:53]
	v_fma_f32 v123, -v122, v1, v0
	s_cbranch_vccnz .LBB0_569
	v_cvt_pk_bf16_f32 v0, v123, s0
	global_store_short v[44:45], v0, off
.LBB0_569:
	v_lshl_add_u64 v[44:45], v[44:45], 0, s[0:1]
	ds_read_u16 v46, v108 offset:11696
	ds_read_b32 v47, v107 offset:172
	ds_read_b32 v234, v106 offset:172
	ds_read_b128 v[40:43], v54 offset:63232
	ds_read_b128 v[36:39], v54 offset:63248
	ds_read_b128 v[32:35], v54 offset:63264
	ds_read_b128 v[28:31], v54 offset:63280
	ds_read_b128 v[24:27], v54 offset:63296
	ds_read_b128 v[20:23], v54 offset:63312
	ds_read_b128 v[16:19], v54 offset:63328
	ds_read_b128 v[8:11], v54 offset:63344
	ds_read_b128 v[4:7], v54 offset:63360
	ds_read_b128 v[12:15], v54 offset:63376
	ds_read_b128 v[0:3], v54 offset:63392
	s_waitcnt lgkmcnt(11)
	v_lshlrev_b32_e32 v235, 16, v46
	s_and_b64 vcc, exec, s[50:51]
	v_mul_f32_e32 v235, v47, v235
	s_cbranch_vccnz .LBB0_571
	v_mul_f32_e32 v46, 0x3fb8aa3b, v234
	v_exp_f32_e32 v46, v46
	s_nop 0
	v_mul_f32_e32 v235, v235, v46
.LBB0_571:
	s_waitcnt lgkmcnt(0)
	v_fma_f32 v3, -v64, v40, v235
	v_fma_f32 v3, -v65, v41, v3
	v_fma_f32 v3, -v67, v42, v3
	v_fma_f32 v3, -v69, v43, v3
	v_fma_f32 v3, -v71, v36, v3
	v_fma_f32 v3, -v73, v37, v3
	v_fma_f32 v3, -v75, v38, v3
	v_fma_f32 v3, -v77, v39, v3
	v_fma_f32 v3, -v79, v32, v3
	v_fma_f32 v3, -v81, v33, v3
	v_fma_f32 v3, -v83, v34, v3
	v_fma_f32 v3, -v85, v35, v3
	v_fma_f32 v3, -v87, v28, v3
	v_fma_f32 v3, -v89, v29, v3
	v_fma_f32 v3, -v91, v30, v3
	v_fma_f32 v3, -v66, v31, v3
	v_fma_f32 v3, -v68, v24, v3
	v_fma_f32 v3, -v70, v25, v3
	v_fma_f32 v3, -v72, v26, v3
	v_fma_f32 v3, -v74, v27, v3
	v_fma_f32 v3, -v76, v20, v3
	v_fma_f32 v3, -v78, v21, v3
	v_fma_f32 v3, -v80, v22, v3
	v_fma_f32 v3, -v82, v23, v3
	v_fma_f32 v3, -v84, v16, v3
	v_fma_f32 v3, -v86, v17, v3
	v_fma_f32 v3, -v88, v18, v3
	v_fma_f32 v3, -v90, v19, v3
	v_fma_f32 v3, -v109, v8, v3
	v_fma_f32 v3, -v110, v9, v3
	v_fma_f32 v3, -v111, v10, v3
	v_fma_f32 v3, -v112, v11, v3
	v_fma_f32 v3, -v113, v4, v3
	v_fma_f32 v3, -v114, v5, v3
	v_fma_f32 v3, -v115, v6, v3
	v_fma_f32 v3, -v116, v7, v3
	v_fma_f32 v3, -v117, v12, v3
	v_fma_f32 v3, -v118, v13, v3
	v_fma_f32 v3, -v119, v14, v3
	v_fma_f32 v3, -v120, v15, v3
	v_fma_f32 v0, -v121, v0, v3
	v_fma_f32 v0, -v122, v1, v0
	s_and_b64 vcc, exec, s[52:53]
	v_fma_f32 v124, -v123, v2, v0
	s_cbranch_vccnz .LBB0_573
	v_cvt_pk_bf16_f32 v0, v124, s0
	global_store_short v[44:45], v0, off
.LBB0_573:
	v_lshl_add_u64 v[44:45], v[44:45], 0, s[0:1]
	ds_read_u16 v46, v108 offset:11968
	ds_read_b32 v47, v107 offset:176
	ds_read_b32 v234, v106 offset:176
	ds_read_b128 v[40:43], v54 offset:63488
	ds_read_b128 v[36:39], v54 offset:63504
	ds_read_b128 v[32:35], v54 offset:63520
	ds_read_b128 v[28:31], v54 offset:63536
	ds_read_b128 v[24:27], v54 offset:63552
	ds_read_b128 v[20:23], v54 offset:63568
	ds_read_b128 v[16:19], v54 offset:63584
	ds_read_b128 v[8:11], v54 offset:63600
	ds_read_b128 v[4:7], v54 offset:63616
	ds_read_b128 v[12:15], v54 offset:63632
	ds_read_b128 v[0:3], v54 offset:63648
	s_waitcnt lgkmcnt(11)
	v_lshlrev_b32_e32 v46, 16, v46
	s_and_b64 vcc, exec, s[50:51]
	v_mul_f32_e32 v46, v47, v46
	s_cbranch_vccnz .LBB0_575
	v_mul_f32_e32 v47, 0x3fb8aa3b, v234
	v_exp_f32_e32 v47, v47
	s_nop 0
	v_mul_f32_e32 v46, v46, v47
.LBB0_575:
	s_waitcnt lgkmcnt(10)
	v_fma_f32 v40, -v64, v40, v46
	v_fma_f32 v40, -v65, v41, v40
	v_fma_f32 v40, -v67, v42, v40
	v_fma_f32 v40, -v69, v43, v40
	s_waitcnt lgkmcnt(9)
	v_fma_f32 v36, -v71, v36, v40
	v_fma_f32 v36, -v73, v37, v36
	v_fma_f32 v36, -v75, v38, v36
	v_fma_f32 v36, -v77, v39, v36
	s_waitcnt lgkmcnt(8)
	v_fma_f32 v32, -v79, v32, v36
	v_fma_f32 v32, -v81, v33, v32
	v_fma_f32 v32, -v83, v34, v32
	v_fma_f32 v32, -v85, v35, v32
	s_waitcnt lgkmcnt(7)
	v_fma_f32 v28, -v87, v28, v32
	v_fma_f32 v28, -v89, v29, v28
	v_fma_f32 v28, -v91, v30, v28
	v_fma_f32 v28, -v66, v31, v28
	s_waitcnt lgkmcnt(6)
	v_fma_f32 v24, -v68, v24, v28
	v_fma_f32 v24, -v70, v25, v24
	v_fma_f32 v24, -v72, v26, v24
	v_fma_f32 v24, -v74, v27, v24
	s_waitcnt lgkmcnt(5)
	v_fma_f32 v20, -v76, v20, v24
	v_fma_f32 v20, -v78, v21, v20
	v_fma_f32 v20, -v80, v22, v20
	v_fma_f32 v20, -v82, v23, v20
	s_waitcnt lgkmcnt(4)
	v_fma_f32 v16, -v84, v16, v20
	v_fma_f32 v16, -v86, v17, v16
	v_fma_f32 v16, -v88, v18, v16
	v_fma_f32 v16, -v90, v19, v16
	s_waitcnt lgkmcnt(3)
	v_fma_f32 v8, -v109, v8, v16
	v_fma_f32 v8, -v110, v9, v8
	v_fma_f32 v8, -v111, v10, v8
	v_fma_f32 v8, -v112, v11, v8
	s_waitcnt lgkmcnt(2)
	v_fma_f32 v4, -v113, v4, v8
	v_fma_f32 v4, -v114, v5, v4
	v_fma_f32 v4, -v115, v6, v4
	v_fma_f32 v4, -v116, v7, v4
	s_waitcnt lgkmcnt(1)
	v_fma_f32 v4, -v117, v12, v4
	v_fma_f32 v4, -v118, v13, v4
	v_fma_f32 v4, -v119, v14, v4
	v_fma_f32 v4, -v120, v15, v4
	s_waitcnt lgkmcnt(0)
	v_fma_f32 v0, -v121, v0, v4
	v_fma_f32 v0, -v122, v1, v0
	v_fma_f32 v0, -v123, v2, v0
	s_and_b64 vcc, exec, s[52:53]
	v_fma_f32 v125, -v124, v3, v0
	s_cbranch_vccnz .LBB0_577
	v_cvt_pk_bf16_f32 v0, v125, s0
	global_store_short v[44:45], v0, off
; __device__ __forceinline__ bf16_t f2bf(float f) { return (bf16_t)(cvt_pk_bf16(f, 0.f) & 0xffffu); }
; __device__ __forceinline__ float bf2f(bf16_t b) { return __uint_as_float(((unsigned)b) << 16); }
; template <int I>
; __device__ __forceinline__ void solve_rows(float (&x)[64], const f32x4* A4, const bf16_t* src, const float* sBeta, const float* sGam, int part, bf16_t* dst, int nvalid) {
;     ...
;         for (int q = 0; q < (I + 3) / 4; ++q) a4[q] = A4[I * 16 + q];
;         float a = bf2f(src[I * 136]) * sBeta[I];
;         if (part == 1) a *= __expf(sGam[I]);
; #pragma unroll
;         for (int j = 0; j < I; ++j) a -= a4[j >> 2][j & 3] * x[j];
;         x[I] = a;
;         if (I < nvalid) *dst = f2bf(a);
;         dst += 1024;
;         asm volatile("" : "+v"(dst) :: "memory");
.LBB0_577:
	v_lshl_add_u64 v[48:49], v[44:45], 0, s[0:1]
	ds_read_u16 v235, v108 offset:12240
	ds_read_b32 v239, v107 offset:180
	ds_read_b32 v234, v106 offset:180
	ds_read_b128 v[40:43], v54 offset:63744
	ds_read_b128 v[44:47], v54 offset:63760
	ds_read_b128 v[36:39], v54 offset:63776
	ds_read_b128 v[32:35], v54 offset:63792
	ds_read_b128 v[28:31], v54 offset:63808
	ds_read_b128 v[24:27], v54 offset:63824
	ds_read_b128 v[20:23], v54 offset:63840
	ds_read_b128 v[16:19], v54 offset:63856
	ds_read_b128 v[12:15], v54 offset:63872
	ds_read_b128 v[8:11], v54 offset:63888
	ds_read_b128 v[4:7], v54 offset:63904
	ds_read_b128 v[0:3], v54 offset:63920
	s_waitcnt lgkmcnt(12)
	s_and_b64 vcc, exec, s[50:51]
	v_lshlrev_b32_e32 v235, 16, v235
	v_mul_f32_e32 v235, v239, v235
	s_cbranch_vccnz .LBB0_579
	v_mul_f32_e32 v239, 0x3fb8aa3b, v234
	v_exp_f32_e32 v239, v239
	s_nop 0
	v_mul_f32_e32 v235, v235, v239
.LBB0_579:
	s_waitcnt lgkmcnt(0)
	v_fma_f32 v1, -v64, v40, v235
	v_fma_f32 v1, -v65, v41, v1
	v_fma_f32 v1, -v67, v42, v1
	v_fma_f32 v1, -v69, v43, v1
	v_fma_f32 v1, -v71, v44, v1
	v_fma_f32 v1, -v73, v45, v1
	v_fma_f32 v1, -v75, v46, v1
	v_fma_f32 v1, -v77, v47, v1
	v_fma_f32 v1, -v79, v36, v1
	v_fma_f32 v1, -v81, v37, v1
	v_fma_f32 v1, -v83, v38, v1
	v_fma_f32 v1, -v85, v39, v1
	v_fma_f32 v1, -v87, v32, v1
	v_fma_f32 v1, -v89, v33, v1
	v_fma_f32 v1, -v91, v34, v1
	v_fma_f32 v1, -v66, v35, v1
	v_fma_f32 v1, -v68, v28, v1
	v_fma_f32 v1, -v70, v29, v1
	v_fma_f32 v1, -v72, v30, v1
	v_fma_f32 v1, -v74, v31, v1
	v_fma_f32 v1, -v76, v24, v1
	v_fma_f32 v1, -v78, v25, v1
	v_fma_f32 v1, -v80, v26, v1
	v_fma_f32 v1, -v82, v27, v1
	v_fma_f32 v1, -v84, v20, v1
	v_fma_f32 v1, -v86, v21, v1
	v_fma_f32 v1, -v88, v22, v1
	v_fma_f32 v1, -v90, v23, v1
	v_fma_f32 v1, -v109, v16, v1
	v_fma_f32 v1, -v110, v17, v1
	v_fma_f32 v1, -v111, v18, v1
	v_fma_f32 v1, -v112, v19, v1
	v_fma_f32 v1, -v113, v12, v1
	v_fma_f32 v1, -v114, v13, v1
	v_fma_f32 v1, -v115, v14, v1
	v_fma_f32 v1, -v116, v15, v1
	v_fma_f32 v1, -v117, v8, v1
	v_fma_f32 v1, -v118, v9, v1
	v_fma_f32 v1, -v119, v10, v1
	v_fma_f32 v1, -v120, v11, v1
	v_fma_f32 v1, -v121, v4, v1
	v_fma_f32 v1, -v122, v5, v1
	v_fma_f32 v1, -v123, v6, v1
	v_fma_f32 v1, -v124, v7, v1
	s_and_b64 vcc, exec, s[52:53]
	v_fma_f32 v126, -v125, v0, v1
	s_cbranch_vccnz .LBB0_581
	v_cvt_pk_bf16_f32 v0, v126, s0
	global_store_short v[48:49], v0, off
.LBB0_581:
	v_lshl_add_u64 v[48:49], v[48:49], 0, s[0:1]
	ds_read_u16 v235, v108 offset:12512
	ds_read_b32 v239, v107 offset:184
	ds_read_b32 v234, v106 offset:184
	ds_read_b128 v[40:43], v54 offset:64000
	ds_read_b128 v[44:47], v54 offset:64016
	ds_read_b128 v[36:39], v54 offset:64032
	ds_read_b128 v[32:35], v54 offset:64048
	ds_read_b128 v[28:31], v54 offset:64064
	ds_read_b128 v[24:27], v54 offset:64080
	ds_read_b128 v[20:23], v54 offset:64096
	ds_read_b128 v[16:19], v54 offset:64112
	ds_read_b128 v[12:15], v54 offset:64128
	ds_read_b128 v[8:11], v54 offset:64144
	ds_read_b128 v[4:7], v54 offset:64160
	ds_read_b128 v[0:3], v54 offset:64176
	s_waitcnt lgkmcnt(12)
	s_and_b64 vcc, exec, s[50:51]
	v_lshlrev_b32_e32 v235, 16, v235
	v_mul_f32_e32 v235, v239, v235
	s_cbranch_vccnz .LBB0_583
	v_mul_f32_e32 v239, 0x3fb8aa3b, v234
	v_exp_f32_e32 v239, v239
	s_nop 0
	v_mul_f32_e32 v235, v235, v239
.LBB0_583:
	s_waitcnt lgkmcnt(0)
	v_fma_f32 v2, -v64, v40, v235
	v_fma_f32 v2, -v65, v41, v2
	v_fma_f32 v2, -v67, v42, v2
	v_fma_f32 v2, -v69, v43, v2
	v_fma_f32 v2, -v71, v44, v2
	v_fma_f32 v2, -v73, v45, v2
	v_fma_f32 v2, -v75, v46, v2
	v_fma_f32 v2, -v77, v47, v2
	v_fma_f32 v2, -v79, v36, v2
	v_fma_f32 v2, -v81, v37, v2
	v_fma_f32 v2, -v83, v38, v2
	v_fma_f32 v2, -v85, v39, v2
	v_fma_f32 v2, -v87, v32, v2
	v_fma_f32 v2, -v89, v33, v2
	v_fma_f32 v2, -v91, v34, v2
	v_fma_f32 v2, -v66, v35, v2
	v_fma_f32 v2, -v68, v28, v2
	v_fma_f32 v2, -v70, v29, v2
	v_fma_f32 v2, -v72, v30, v2
	v_fma_f32 v2, -v74, v31, v2
	v_fma_f32 v2, -v76, v24, v2
	v_fma_f32 v2, -v78, v25, v2
	v_fma_f32 v2, -v80, v26, v2
	v_fma_f32 v2, -v82, v27, v2
	v_fma_f32 v2, -v84, v20, v2
	v_fma_f32 v2, -v86, v21, v2
	v_fma_f32 v2, -v88, v22, v2
	v_fma_f32 v2, -v90, v23, v2
	v_fma_f32 v2, -v109, v16, v2
	v_fma_f32 v2, -v110, v17, v2
	v_fma_f32 v2, -v111, v18, v2
	v_fma_f32 v2, -v112, v19, v2
	v_fma_f32 v2, -v113, v12, v2
	v_fma_f32 v2, -v114, v13, v2
	v_fma_f32 v2, -v115, v14, v2
	v_fma_f32 v2, -v116, v15, v2
	v_fma_f32 v2, -v117, v8, v2
	v_fma_f32 v2, -v118, v9, v2
	v_fma_f32 v2, -v119, v10, v2
	v_fma_f32 v2, -v120, v11, v2
	v_fma_f32 v2, -v121, v4, v2
	v_fma_f32 v2, -v122, v5, v2
	v_fma_f32 v2, -v123, v6, v2
	v_fma_f32 v2, -v124, v7, v2
	v_fma_f32 v0, -v125, v0, v2
	s_and_b64 vcc, exec, s[52:53]
	v_fma_f32 v127, -v126, v1, v0
	s_cbranch_vccnz .LBB0_585
	v_cvt_pk_bf16_f32 v0, v127, s0
	global_store_short v[48:49], v0, off
.LBB0_585:
	v_lshl_add_u64 v[48:49], v[48:49], 0, s[0:1]
	ds_read_u16 v50, v108 offset:12784
	ds_read_b32 v51, v107 offset:188
	ds_read_b32 v234, v106 offset:188
	ds_read_b128 v[44:47], v54 offset:64256
	ds_read_b128 v[40:43], v54 offset:64272
	ds_read_b128 v[36:39], v54 offset:64288
	ds_read_b128 v[32:35], v54 offset:64304
	ds_read_b128 v[28:31], v54 offset:64320
	ds_read_b128 v[24:27], v54 offset:64336
	ds_read_b128 v[20:23], v54 offset:64352
	ds_read_b128 v[16:19], v54 offset:64368
	ds_read_b128 v[12:15], v54 offset:64384
	ds_read_b128 v[8:11], v54 offset:64400
	ds_read_b128 v[0:3], v54 offset:64416
	ds_read_b128 v[4:7], v54 offset:64432
	s_waitcnt lgkmcnt(12)
	s_and_b64 vcc, exec, s[50:51]
	v_lshlrev_b32_e32 v235, 16, v50
	v_mul_f32_e32 v235, v51, v235
	s_cbranch_vccnz .LBB0_587
	v_mul_f32_e32 v50, 0x3fb8aa3b, v234
	v_exp_f32_e32 v50, v50
	s_nop 0
	v_mul_f32_e32 v235, v235, v50
; __device__ __forceinline__ bf16_t f2bf(float f) { return (bf16_t)(cvt_pk_bf16(f, 0.f) & 0xffffu); }
; __device__ __forceinline__ float bf2f(bf16_t b) { return __uint_as_float(((unsigned)b) << 16); }
; template <int I>
; __device__ __forceinline__ void solve_rows(float (&x)[64], const f32x4* A4, const bf16_t* src, const float* sBeta, const float* sGam, int part, bf16_t* dst, int nvalid) {
;     ...
;         for (int q = 0; q < (I + 3) / 4; ++q) a4[q] = A4[I * 16 + q];
;         float a = bf2f(src[I * 136]) * sBeta[I];
;         if (part == 1) a *= __expf(sGam[I]);
; #pragma unroll
;         for (int j = 0; j < I; ++j) a -= a4[j >> 2][j & 3] * x[j];
;         x[I] = a;
;         if (I < nvalid) *dst = f2bf(a);
;         dst += 1024;
;         asm volatile("" : "+v"(dst) :: "memory");
.LBB0_587:
	s_waitcnt lgkmcnt(0)
	v_fma_f32 v7, -v64, v44, v235
	v_fma_f32 v7, -v65, v45, v7
	v_fma_f32 v7, -v67, v46, v7
	v_fma_f32 v7, -v69, v47, v7
	v_fma_f32 v7, -v71, v40, v7
	v_fma_f32 v7, -v73, v41, v7
	v_fma_f32 v7, -v75, v42, v7
	v_fma_f32 v7, -v77, v43, v7
	v_fma_f32 v7, -v79, v36, v7
	v_fma_f32 v7, -v81, v37, v7
	v_fma_f32 v7, -v83, v38, v7
	v_fma_f32 v7, -v85, v39, v7
	v_fma_f32 v7, -v87, v32, v7
	v_fma_f32 v7, -v89, v33, v7
	v_fma_f32 v7, -v91, v34, v7
	v_fma_f32 v7, -v66, v35, v7
	v_fma_f32 v7, -v68, v28, v7
	v_fma_f32 v7, -v70, v29, v7
	v_fma_f32 v7, -v72, v30, v7
	v_fma_f32 v7, -v74, v31, v7
	v_fma_f32 v7, -v76, v24, v7
	v_fma_f32 v7, -v78, v25, v7
	v_fma_f32 v7, -v80, v26, v7
	v_fma_f32 v7, -v82, v27, v7
	v_fma_f32 v7, -v84, v20, v7
	v_fma_f32 v7, -v86, v21, v7
	v_fma_f32 v7, -v88, v22, v7
	v_fma_f32 v7, -v90, v23, v7
	v_fma_f32 v7, -v109, v16, v7
	v_fma_f32 v7, -v110, v17, v7
	v_fma_f32 v7, -v111, v18, v7
	v_fma_f32 v7, -v112, v19, v7
	v_fma_f32 v7, -v113, v12, v7
	v_fma_f32 v7, -v114, v13, v7
	v_fma_f32 v7, -v115, v14, v7
	v_fma_f32 v7, -v116, v15, v7
	v_fma_f32 v7, -v117, v8, v7
	v_fma_f32 v7, -v118, v9, v7
	v_fma_f32 v7, -v119, v10, v7
	v_fma_f32 v7, -v120, v11, v7
	v_fma_f32 v0, -v121, v0, v7
	v_fma_f32 v0, -v122, v1, v0
	v_fma_f32 v0, -v123, v2, v0
	v_fma_f32 v0, -v124, v3, v0
	v_fma_f32 v0, -v125, v4, v0
	v_fma_f32 v0, -v126, v5, v0
	s_and_b64 vcc, exec, s[52:53]
	v_fma_f32 v137, -v127, v6, v0
	s_cbranch_vccnz .LBB0_589
	v_cvt_pk_bf16_f32 v0, v137, s0
	global_store_short v[48:49], v0, off
.LBB0_589:
	v_lshl_add_u64 v[48:49], v[48:49], 0, s[0:1]
	ds_read_u16 v50, v108 offset:13056
	ds_read_b32 v51, v107 offset:192
	ds_read_b32 v234, v106 offset:192
	ds_read_b128 v[44:47], v54 offset:64512
	ds_read_b128 v[40:43], v54 offset:64528
	ds_read_b128 v[36:39], v54 offset:64544
	ds_read_b128 v[32:35], v54 offset:64560
	ds_read_b128 v[28:31], v54 offset:64576
	ds_read_b128 v[24:27], v54 offset:64592
	ds_read_b128 v[20:23], v54 offset:64608
	ds_read_b128 v[16:19], v54 offset:64624
	ds_read_b128 v[12:15], v54 offset:64640
	ds_read_b128 v[8:11], v54 offset:64656
	ds_read_b128 v[0:3], v54 offset:64672
	ds_read_b128 v[4:7], v54 offset:64688
	s_waitcnt lgkmcnt(12)
	s_and_b64 vcc, exec, s[50:51]
	v_lshlrev_b32_e32 v50, 16, v50
	v_mul_f32_e32 v50, v51, v50
	s_cbranch_vccnz .LBB0_591
	v_mul_f32_e32 v51, 0x3fb8aa3b, v234
	v_exp_f32_e32 v51, v51
	s_nop 0
	v_mul_f32_e32 v50, v50, v51
.LBB0_591:
	s_waitcnt lgkmcnt(11)
	v_fma_f32 v44, -v64, v44, v50
	v_fma_f32 v44, -v65, v45, v44
	v_fma_f32 v44, -v67, v46, v44
	v_fma_f32 v44, -v69, v47, v44
	s_waitcnt lgkmcnt(10)
	v_fma_f32 v40, -v71, v40, v44
	v_fma_f32 v40, -v73, v41, v40
	v_fma_f32 v40, -v75, v42, v40
	v_fma_f32 v40, -v77, v43, v40
	s_waitcnt lgkmcnt(9)
	v_fma_f32 v36, -v79, v36, v40
	v_fma_f32 v36, -v81, v37, v36
	v_fma_f32 v36, -v83, v38, v36
	v_fma_f32 v36, -v85, v39, v36
	s_waitcnt lgkmcnt(8)
	v_fma_f32 v32, -v87, v32, v36
	v_fma_f32 v32, -v89, v33, v32
	v_fma_f32 v32, -v91, v34, v32
	v_fma_f32 v32, -v66, v35, v32
	s_waitcnt lgkmcnt(7)
	v_fma_f32 v28, -v68, v28, v32
	v_fma_f32 v28, -v70, v29, v28
	v_fma_f32 v28, -v72, v30, v28
	v_fma_f32 v28, -v74, v31, v28
	s_waitcnt lgkmcnt(6)
	v_fma_f32 v24, -v76, v24, v28
	v_fma_f32 v24, -v78, v25, v24
	v_fma_f32 v24, -v80, v26, v24
	v_fma_f32 v24, -v82, v27, v24
	s_waitcnt lgkmcnt(5)
	v_fma_f32 v20, -v84, v20, v24
	v_fma_f32 v20, -v86, v21, v20
	v_fma_f32 v20, -v88, v22, v20
	v_fma_f32 v20, -v90, v23, v20
	s_waitcnt lgkmcnt(4)
	v_fma_f32 v16, -v109, v16, v20
	v_fma_f32 v16, -v110, v17, v16
	v_fma_f32 v16, -v111, v18, v16
	v_fma_f32 v16, -v112, v19, v16
	s_waitcnt lgkmcnt(3)
	v_fma_f32 v12, -v113, v12, v16
	v_fma_f32 v12, -v114, v13, v12
	v_fma_f32 v12, -v115, v14, v12
	v_fma_f32 v12, -v116, v15, v12
	s_waitcnt lgkmcnt(2)
	v_fma_f32 v8, -v117, v8, v12
	v_fma_f32 v8, -v118, v9, v8
	v_fma_f32 v8, -v119, v10, v8
	v_fma_f32 v8, -v120, v11, v8
	s_waitcnt lgkmcnt(1)
	v_fma_f32 v0, -v121, v0, v8
	v_fma_f32 v0, -v122, v1, v0
	v_fma_f32 v0, -v123, v2, v0
	v_fma_f32 v0, -v124, v3, v0
	s_waitcnt lgkmcnt(0)
	v_fma_f32 v0, -v125, v4, v0
	v_fma_f32 v0, -v126, v5, v0
	v_fma_f32 v0, -v127, v6, v0
	s_and_b64 vcc, exec, s[52:53]
	v_fma_f32 v139, -v137, v7, v0
	s_cbranch_vccnz .LBB0_593
	v_cvt_pk_bf16_f32 v0, v139, s0
	global_store_short v[48:49], v0, off
.LBB0_593:
	v_lshl_add_u64 v[52:53], v[48:49], 0, s[0:1]
	ds_read_u16 v235, v108 offset:13328
	ds_read_b32 v239, v107 offset:196
	ds_read_b32 v234, v106 offset:196
	ds_read_b128 v[44:47], v54 offset:64768
	ds_read_b128 v[48:51], v54 offset:64784
	ds_read_b128 v[40:43], v54 offset:64800
	ds_read_b128 v[36:39], v54 offset:64816
	ds_read_b128 v[32:35], v54 offset:64832
	ds_read_b128 v[28:31], v54 offset:64848
	ds_read_b128 v[24:27], v54 offset:64864
	ds_read_b128 v[20:23], v54 offset:64880
	ds_read_b128 v[16:19], v54 offset:64896
	ds_read_b128 v[12:15], v54 offset:64912
	ds_read_b128 v[8:11], v54 offset:64928
	ds_read_b128 v[4:7], v54 offset:64944
	ds_read_b128 v[0:3], v54 offset:64960
	s_waitcnt lgkmcnt(13)
	s_and_b64 vcc, exec, s[50:51]
	v_lshlrev_b32_e32 v235, 16, v235
	v_mul_f32_e32 v235, v239, v235
	s_cbranch_vccnz .LBB0_595
	v_mul_f32_e32 v239, 0x3fb8aa3b, v234
	v_exp_f32_e32 v239, v239
	s_nop 0
	v_mul_f32_e32 v235, v235, v239
; __device__ __forceinline__ bf16_t f2bf(float f) { return (bf16_t)(cvt_pk_bf16(f, 0.f) & 0xffffu); }
; __device__ __forceinline__ float bf2f(bf16_t b) { return __uint_as_float(((unsigned)b) << 16); }
; template <int I>
; __device__ __forceinline__ void solve_rows(float (&x)[64], const f32x4* A4, const bf16_t* src, const float* sBeta, const float* sGam, int part, bf16_t* dst, int nvalid) {
;     ...
;         for (int q = 0; q < (I + 3) / 4; ++q) a4[q] = A4[I * 16 + q];
;         float a = bf2f(src[I * 136]) * sBeta[I];
;         if (part == 1) a *= __expf(sGam[I]);
; #pragma unroll
;         for (int j = 0; j < I; ++j) a -= a4[j >> 2][j & 3] * x[j];
;         x[I] = a;
;         if (I < nvalid) *dst = f2bf(a);
;         dst += 1024;
;         asm volatile("" : "+v"(dst) :: "memory");
.LBB0_595:
	s_waitcnt lgkmcnt(0)
	v_fma_f32 v1, -v64, v44, v235
	v_fma_f32 v1, -v65, v45, v1
	v_fma_f32 v1, -v67, v46, v1
	v_fma_f32 v1, -v69, v47, v1
	v_fma_f32 v1, -v71, v48, v1
	v_fma_f32 v1, -v73, v49, v1
	v_fma_f32 v1, -v75, v50, v1
	v_fma_f32 v1, -v77, v51, v1
	v_fma_f32 v1, -v79, v40, v1
	v_fma_f32 v1, -v81, v41, v1
	v_fma_f32 v1, -v83, v42, v1
	v_fma_f32 v1, -v85, v43, v1
	v_fma_f32 v1, -v87, v36, v1
	v_fma_f32 v1, -v89, v37, v1
	v_fma_f32 v1, -v91, v38, v1
	v_fma_f32 v1, -v66, v39, v1
	v_fma_f32 v1, -v68, v32, v1
	v_fma_f32 v1, -v70, v33, v1
	v_fma_f32 v1, -v72, v34, v1
	v_fma_f32 v1, -v74, v35, v1
	v_fma_f32 v1, -v76, v28, v1
	v_fma_f32 v1, -v78, v29, v1
	v_fma_f32 v1, -v80, v30, v1
	v_fma_f32 v1, -v82, v31, v1
	v_fma_f32 v1, -v84, v24, v1
	v_fma_f32 v1, -v86, v25, v1
	v_fma_f32 v1, -v88, v26, v1
	v_fma_f32 v1, -v90, v27, v1
	v_fma_f32 v1, -v109, v20, v1
	v_fma_f32 v1, -v110, v21, v1
	v_fma_f32 v1, -v111, v22, v1
	v_fma_f32 v1, -v112, v23, v1
	v_fma_f32 v1, -v113, v16, v1
	v_fma_f32 v1, -v114, v17, v1
	v_fma_f32 v1, -v115, v18, v1
	v_fma_f32 v1, -v116, v19, v1
	v_fma_f32 v1, -v117, v12, v1
	v_fma_f32 v1, -v118, v13, v1
	v_fma_f32 v1, -v119, v14, v1
	v_fma_f32 v1, -v120, v15, v1
	v_fma_f32 v1, -v121, v8, v1
	v_fma_f32 v1, -v122, v9, v1
	v_fma_f32 v1, -v123, v10, v1
	v_fma_f32 v1, -v124, v11, v1
	v_fma_f32 v1, -v125, v4, v1
	v_fma_f32 v1, -v126, v5, v1
	v_fma_f32 v1, -v127, v6, v1
	v_fma_f32 v1, -v137, v7, v1
	s_and_b64 vcc, exec, s[52:53]
	v_fma_f32 v140, -v139, v0, v1
	s_cbranch_vccnz .LBB0_597
	v_cvt_pk_bf16_f32 v0, v140, s0
	global_store_short v[52:53], v0, off
.LBB0_597:
	v_lshl_add_u64 v[52:53], v[52:53], 0, s[0:1]
	ds_read_u16 v235, v108 offset:13600
	ds_read_b32 v239, v107 offset:200
	ds_read_b32 v234, v106 offset:200
	ds_read_b128 v[44:47], v54 offset:65024
	ds_read_b128 v[48:51], v54 offset:65040
	ds_read_b128 v[40:43], v54 offset:65056
	ds_read_b128 v[36:39], v54 offset:65072
	ds_read_b128 v[32:35], v54 offset:65088
	ds_read_b128 v[28:31], v54 offset:65104
	ds_read_b128 v[24:27], v54 offset:65120
	ds_read_b128 v[20:23], v54 offset:65136
	ds_read_b128 v[16:19], v54 offset:65152
	ds_read_b128 v[12:15], v54 offset:65168
	ds_read_b128 v[8:11], v54 offset:65184
	ds_read_b128 v[4:7], v54 offset:65200
	ds_read_b128 v[0:3], v54 offset:65216
	s_waitcnt lgkmcnt(13)
	s_and_b64 vcc, exec, s[50:51]
	v_lshlrev_b32_e32 v235, 16, v235
	v_mul_f32_e32 v235, v239, v235
	s_cbranch_vccnz .LBB0_599
	v_mul_f32_e32 v239, 0x3fb8aa3b, v234
	v_exp_f32_e32 v239, v239
	s_nop 0
	v_mul_f32_e32 v235, v235, v239
.LBB0_599:
	s_waitcnt lgkmcnt(0)
	v_fma_f32 v2, -v64, v44, v235
	v_fma_f32 v2, -v65, v45, v2
	v_fma_f32 v2, -v67, v46, v2
	v_fma_f32 v2, -v69, v47, v2
	v_fma_f32 v2, -v71, v48, v2
	v_fma_f32 v2, -v73, v49, v2
	v_fma_f32 v2, -v75, v50, v2
	v_fma_f32 v2, -v77, v51, v2
	v_fma_f32 v2, -v79, v40, v2
	v_fma_f32 v2, -v81, v41, v2
	v_fma_f32 v2, -v83, v42, v2
	v_fma_f32 v2, -v85, v43, v2
	v_fma_f32 v2, -v87, v36, v2
	v_fma_f32 v2, -v89, v37, v2
	v_fma_f32 v2, -v91, v38, v2
	v_fma_f32 v2, -v66, v39, v2
	v_fma_f32 v2, -v68, v32, v2
	v_fma_f32 v2, -v70, v33, v2
	v_fma_f32 v2, -v72, v34, v2
	v_fma_f32 v2, -v74, v35, v2
	v_fma_f32 v2, -v76, v28, v2
	v_fma_f32 v2, -v78, v29, v2
	v_fma_f32 v2, -v80, v30, v2
	v_fma_f32 v2, -v82, v31, v2
	v_fma_f32 v2, -v84, v24, v2
	v_fma_f32 v2, -v86, v25, v2
	v_fma_f32 v2, -v88, v26, v2
	v_fma_f32 v2, -v90, v27, v2
	v_fma_f32 v2, -v109, v20, v2
	v_fma_f32 v2, -v110, v21, v2
	v_fma_f32 v2, -v111, v22, v2
	v_fma_f32 v2, -v112, v23, v2
	v_fma_f32 v2, -v113, v16, v2
	v_fma_f32 v2, -v114, v17, v2
	v_fma_f32 v2, -v115, v18, v2
	v_fma_f32 v2, -v116, v19, v2
	v_fma_f32 v2, -v117, v12, v2
	v_fma_f32 v2, -v118, v13, v2
	v_fma_f32 v2, -v119, v14, v2
	v_fma_f32 v2, -v120, v15, v2
	v_fma_f32 v2, -v121, v8, v2
	v_fma_f32 v2, -v122, v9, v2
	v_fma_f32 v2, -v123, v10, v2
	v_fma_f32 v2, -v124, v11, v2
	v_fma_f32 v2, -v125, v4, v2
	v_fma_f32 v2, -v126, v5, v2
	v_fma_f32 v2, -v127, v6, v2
	v_fma_f32 v2, -v137, v7, v2
	v_fma_f32 v0, -v139, v0, v2
	s_and_b64 vcc, exec, s[52:53]
	v_fma_f32 v142, -v140, v1, v0
	s_cbranch_vccnz .LBB0_601
	v_cvt_pk_bf16_f32 v0, v142, s0
	global_store_short v[52:53], v0, off
.LBB0_601:
	v_lshl_add_u64 v[52:53], v[52:53], 0, s[0:1]
	ds_read_u16 v55, v108 offset:13872
	ds_read_b32 v56, v107 offset:204
	ds_read_b32 v234, v106 offset:204
	ds_read_b128 v[48:51], v54 offset:65280
	ds_read_b128 v[44:47], v54 offset:65296
	ds_read_b128 v[40:43], v54 offset:65312
	ds_read_b128 v[36:39], v54 offset:65328
	ds_read_b128 v[32:35], v54 offset:65344
	ds_read_b128 v[28:31], v54 offset:65360
	ds_read_b128 v[24:27], v54 offset:65376
	ds_read_b128 v[20:23], v54 offset:65392
	ds_read_b128 v[16:19], v54 offset:65408
	ds_read_b128 v[8:11], v54 offset:65424
	ds_read_b128 v[4:7], v54 offset:65440
	ds_read_b128 v[12:15], v54 offset:65456
	ds_read_b128 v[0:3], v54 offset:65472
	s_waitcnt lgkmcnt(13)
	v_lshlrev_b32_e32 v235, 16, v55
	s_and_b64 vcc, exec, s[50:51]
	v_mul_f32_e32 v235, v56, v235
	s_cbranch_vccnz .LBB0_603
	v_mul_f32_e32 v55, 0x3fb8aa3b, v234
	v_exp_f32_e32 v55, v55
	s_nop 0
	v_mul_f32_e32 v235, v235, v55
.LBB0_603:
	s_waitcnt lgkmcnt(0)
	v_fma_f32 v3, -v64, v48, v235
	v_fma_f32 v3, -v65, v49, v3
	v_fma_f32 v3, -v67, v50, v3
	v_fma_f32 v3, -v69, v51, v3
	v_fma_f32 v3, -v71, v44, v3
	v_fma_f32 v3, -v73, v45, v3
	v_fma_f32 v3, -v75, v46, v3
	v_fma_f32 v3, -v77, v47, v3
	v_fma_f32 v3, -v79, v40, v3
	v_fma_f32 v3, -v81, v41, v3
	v_fma_f32 v3, -v83, v42, v3
	v_fma_f32 v3, -v85, v43, v3
	v_fma_f32 v3, -v87, v36, v3
	v_fma_f32 v3, -v89, v37, v3
	v_fma_f32 v3, -v91, v38, v3
	v_fma_f32 v3, -v66, v39, v3
	v_fma_f32 v3, -v68, v32, v3
	v_fma_f32 v3, -v70, v33, v3
	v_fma_f32 v3, -v72, v34, v3
	v_fma_f32 v3, -v74, v35, v3
	v_fma_f32 v3, -v76, v28, v3
	v_fma_f32 v3, -v78, v29, v3
	v_fma_f32 v3, -v80, v30, v3
	v_fma_f32 v3, -v82, v31, v3
	v_fma_f32 v3, -v84, v24, v3
	v_fma_f32 v3, -v86, v25, v3
	v_fma_f32 v3, -v88, v26, v3
	v_fma_f32 v3, -v90, v27, v3
	v_fma_f32 v3, -v109, v20, v3
	v_fma_f32 v3, -v110, v21, v3
	v_fma_f32 v3, -v111, v22, v3
	v_fma_f32 v3, -v112, v23, v3
	v_fma_f32 v3, -v113, v16, v3
	v_fma_f32 v3, -v114, v17, v3
	v_fma_f32 v3, -v115, v18, v3
	v_fma_f32 v3, -v116, v19, v3
	v_fma_f32 v3, -v117, v8, v3
	v_fma_f32 v3, -v118, v9, v3
	v_fma_f32 v3, -v119, v10, v3
	v_fma_f32 v3, -v120, v11, v3
	v_fma_f32 v3, -v121, v4, v3
	v_fma_f32 v3, -v122, v5, v3
	v_fma_f32 v3, -v123, v6, v3
	v_fma_f32 v3, -v124, v7, v3
	v_fma_f32 v3, -v125, v12, v3
	v_fma_f32 v3, -v126, v13, v3
	v_fma_f32 v3, -v127, v14, v3
	v_fma_f32 v3, -v137, v15, v3
	v_fma_f32 v0, -v139, v0, v3
	v_fma_f32 v0, -v140, v1, v0
	s_and_b64 vcc, exec, s[52:53]
	v_fma_f32 v92, -v142, v2, v0
	s_cbranch_vccnz .LBB0_605
	v_cvt_pk_bf16_f32 v0, v92, s0
	global_store_short v[52:53], v0, off

; __device__ __forceinline__ bf16_t f2bf(float f) { return (bf16_t)(cvt_pk_bf16(f, 0.f) & 0xffffu); }
; __device__ __forceinline__ float bf2f(bf16_t b) { return __uint_as_float(((unsigned)b) << 16); }
; template <int I>
; __device__ __forceinline__ void solve_rows(float (&x)[64], const f32x4* A4, const bf16_t* src, const float* sBeta, const float* sGam, int part, bf16_t* dst, int nvalid) {
;     ...
;         for (int q = 0; q < (I + 3) / 4; ++q) a4[q] = A4[I * 16 + q];
;         float a = bf2f(src[I * 136]) * sBeta[I];
;         if (part == 1) a *= __expf(sGam[I]);
; #pragma unroll
;         for (int j = 0; j < I; ++j) a -= a4[j >> 2][j & 3] * x[j];
;         x[I] = a;
;         if (I < nvalid) *dst = f2bf(a);
;         dst += 1024;
;         asm volatile("" : "+v"(dst) :: "memory");
.LBB0_607:
	v_fma_f32 v48, -v64, v48, v54
	v_fma_f32 v48, -v65, v49, v48
	v_fma_f32 v48, -v67, v50, v48
	v_fma_f32 v48, -v69, v51, v48
	v_fma_f32 v44, -v71, v44, v48
	v_fma_f32 v44, -v73, v45, v44
	v_fma_f32 v44, -v75, v46, v44
	v_fma_f32 v44, -v77, v47, v44
	v_fma_f32 v40, -v79, v40, v44
	v_fma_f32 v40, -v81, v41, v40
	v_fma_f32 v40, -v83, v42, v40
	v_fma_f32 v40, -v85, v43, v40
	v_fma_f32 v36, -v87, v36, v40
	v_fma_f32 v36, -v89, v37, v36
	v_fma_f32 v36, -v91, v38, v36
	v_fma_f32 v36, -v66, v39, v36
	v_fma_f32 v32, -v68, v32, v36
	v_fma_f32 v32, -v70, v33, v32
	v_fma_f32 v32, -v72, v34, v32
	v_fma_f32 v32, -v74, v35, v32
	v_fma_f32 v28, -v76, v28, v32
	v_fma_f32 v28, -v78, v29, v28
	v_fma_f32 v28, -v80, v30, v28
	v_fma_f32 v28, -v82, v31, v28
	v_fma_f32 v24, -v84, v24, v28
	v_fma_f32 v24, -v86, v25, v24
	v_fma_f32 v24, -v88, v26, v24
	v_fma_f32 v24, -v90, v27, v24
	v_fma_f32 v20, -v109, v20, v24
	v_fma_f32 v20, -v110, v21, v20
	v_fma_f32 v20, -v111, v22, v20
	v_fma_f32 v20, -v112, v23, v20
	v_fma_f32 v16, -v113, v16, v20
	v_fma_f32 v16, -v114, v17, v16
	v_fma_f32 v16, -v115, v18, v16
	v_fma_f32 v16, -v116, v19, v16
	v_fma_f32 v8, -v117, v8, v16
	v_fma_f32 v8, -v118, v9, v8
	v_fma_f32 v8, -v119, v10, v8
	v_fma_f32 v8, -v120, v11, v8
	v_fma_f32 v4, -v121, v4, v8
	v_fma_f32 v4, -v122, v5, v4
	v_fma_f32 v4, -v123, v6, v4
	v_fma_f32 v4, -v124, v7, v4
	v_fma_f32 v4, -v125, v12, v4
	v_fma_f32 v4, -v126, v13, v4
	v_fma_f32 v4, -v127, v14, v4
	v_fma_f32 v4, -v137, v15, v4
	v_fma_f32 v0, -v139, v0, v4
	v_fma_f32 v0, -v140, v1, v0
	v_fma_f32 v0, -v142, v2, v0
	s_and_b64 vcc, exec, s[52:53]
	v_fma_f32 v93, -v92, v3, v0
	s_cbranch_vccnz .LBB0_609
	v_cvt_pk_bf16_f32 v0, v93, s0
	global_store_short v[52:53], v0, off

; __device__ __forceinline__ bf16_t f2bf(float f) { return (bf16_t)(cvt_pk_bf16(f, 0.f) & 0xffffu); }
; __device__ __forceinline__ float bf2f(bf16_t b) { return __uint_as_float(((unsigned)b) << 16); }
; template <int I>
; __device__ __forceinline__ void solve_rows(float (&x)[64], const f32x4* A4, const bf16_t* src, const float* sBeta, const float* sGam, int part, bf16_t* dst, int nvalid) {
;     ...
;         for (int q = 0; q < (I + 3) / 4; ++q) a4[q] = A4[I * 16 + q];
;         float a = bf2f(src[I * 136]) * sBeta[I];
;         if (part == 1) a *= __expf(sGam[I]);
; #pragma unroll
;         for (int j = 0; j < I; ++j) a -= a4[j >> 2][j & 3] * x[j];
;         x[I] = a;
;         if (I < nvalid) *dst = f2bf(a);
;         dst += 1024;
;         asm volatile("" : "+v"(dst) :: "memory");
.LBB0_611:
	v_fma_f32 v1, -v64, v48, v1
	v_fma_f32 v1, -v65, v49, v1
	v_fma_f32 v1, -v67, v50, v1
	v_fma_f32 v1, -v69, v51, v1
	v_fma_f32 v1, -v71, v52, v1
	v_fma_f32 v1, -v73, v53, v1
	v_fma_f32 v1, -v75, v54, v1
	v_fma_f32 v1, -v77, v55, v1
	v_fma_f32 v1, -v79, v44, v1
	v_fma_f32 v1, -v81, v45, v1
	v_fma_f32 v1, -v83, v46, v1
	v_fma_f32 v1, -v85, v47, v1
	v_fma_f32 v1, -v87, v40, v1
	v_fma_f32 v1, -v89, v41, v1
	v_fma_f32 v1, -v91, v42, v1
	v_fma_f32 v1, -v66, v43, v1
	v_fma_f32 v1, -v68, v36, v1
	v_fma_f32 v1, -v70, v37, v1
	v_fma_f32 v1, -v72, v38, v1
	v_fma_f32 v1, -v74, v39, v1
	v_fma_f32 v1, -v76, v32, v1
	v_fma_f32 v1, -v78, v33, v1
	v_fma_f32 v1, -v80, v34, v1
	v_fma_f32 v1, -v82, v35, v1
	v_fma_f32 v1, -v84, v28, v1
	v_fma_f32 v1, -v86, v29, v1
	v_fma_f32 v1, -v88, v30, v1
	v_fma_f32 v1, -v90, v31, v1
	v_fma_f32 v1, -v109, v24, v1
	v_fma_f32 v1, -v110, v25, v1
	v_fma_f32 v1, -v111, v26, v1
	v_fma_f32 v1, -v112, v27, v1
	v_fma_f32 v1, -v113, v20, v1
	v_fma_f32 v1, -v114, v21, v1
	v_fma_f32 v1, -v115, v22, v1
	v_fma_f32 v1, -v116, v23, v1
	v_fma_f32 v1, -v117, v16, v1
	v_fma_f32 v1, -v118, v17, v1
	v_fma_f32 v1, -v119, v18, v1
	v_fma_f32 v1, -v120, v19, v1
	v_fma_f32 v1, -v121, v12, v1
	v_fma_f32 v1, -v122, v13, v1
	v_fma_f32 v1, -v123, v14, v1
	v_fma_f32 v1, -v124, v15, v1
	v_fma_f32 v1, -v125, v8, v1
	v_fma_f32 v1, -v126, v9, v1
	v_fma_f32 v1, -v127, v10, v1
	v_fma_f32 v1, -v137, v11, v1
	v_fma_f32 v1, -v139, v4, v1
	v_fma_f32 v1, -v140, v5, v1
	v_fma_f32 v1, -v142, v6, v1
	v_fma_f32 v1, -v92, v7, v1
	s_and_b64 vcc, exec, s[52:53]
	v_fma_f32 v94, -v93, v0, v1
	s_cbranch_vccnz .LBB0_613
	v_cvt_pk_bf16_f32 v0, v94, s0
	global_store_short v[56:57], v0, off

; __device__ __forceinline__ bf16_t f2bf(float f) { return (bf16_t)(cvt_pk_bf16(f, 0.f) & 0xffffu); }
; __device__ __forceinline__ float bf2f(bf16_t b) { return __uint_as_float(((unsigned)b) << 16); }
; template <int I>
; __device__ __forceinline__ void solve_rows(float (&x)[64], const f32x4* A4, const bf16_t* src, const float* sBeta, const float* sGam, int part, bf16_t* dst, int nvalid) {
;     ...
;         for (int q = 0; q < (I + 3) / 4; ++q) a4[q] = A4[I * 16 + q];
;         float a = bf2f(src[I * 136]) * sBeta[I];
;         if (part == 1) a *= __expf(sGam[I]);
; #pragma unroll
;         for (int j = 0; j < I; ++j) a -= a4[j >> 2][j & 3] * x[j];
;         x[I] = a;
;         if (I < nvalid) *dst = f2bf(a);
;         dst += 1024;
;         asm volatile("" : "+v"(dst) :: "memory");
.LBB0_615:
	v_fma_f32 v2, -v64, v48, v2
	v_fma_f32 v2, -v65, v49, v2
	v_fma_f32 v2, -v67, v50, v2
	v_fma_f32 v2, -v69, v51, v2
	v_fma_f32 v2, -v71, v52, v2
	v_fma_f32 v2, -v73, v53, v2
	v_fma_f32 v2, -v75, v54, v2
	v_fma_f32 v2, -v77, v55, v2
	v_fma_f32 v2, -v79, v44, v2
	v_fma_f32 v2, -v81, v45, v2
	v_fma_f32 v2, -v83, v46, v2
	v_fma_f32 v2, -v85, v47, v2
	v_fma_f32 v2, -v87, v40, v2
	v_fma_f32 v2, -v89, v41, v2
	v_fma_f32 v2, -v91, v42, v2
	v_fma_f32 v2, -v66, v43, v2
	v_fma_f32 v2, -v68, v36, v2
	v_fma_f32 v2, -v70, v37, v2
	v_fma_f32 v2, -v72, v38, v2
	v_fma_f32 v2, -v74, v39, v2
	v_fma_f32 v2, -v76, v32, v2
	v_fma_f32 v2, -v78, v33, v2
	v_fma_f32 v2, -v80, v34, v2
	v_fma_f32 v2, -v82, v35, v2
	v_fma_f32 v2, -v84, v28, v2
	v_fma_f32 v2, -v86, v29, v2
	v_fma_f32 v2, -v88, v30, v2
	v_fma_f32 v2, -v90, v31, v2
	v_fma_f32 v2, -v109, v24, v2
	v_fma_f32 v2, -v110, v25, v2
	v_fma_f32 v2, -v111, v26, v2
	v_fma_f32 v2, -v112, v27, v2
	v_fma_f32 v2, -v113, v20, v2
	v_fma_f32 v2, -v114, v21, v2
	v_fma_f32 v2, -v115, v22, v2
	v_fma_f32 v2, -v116, v23, v2
	v_fma_f32 v2, -v117, v16, v2
	v_fma_f32 v2, -v118, v17, v2
	v_fma_f32 v2, -v119, v18, v2
	v_fma_f32 v2, -v120, v19, v2
	v_fma_f32 v2, -v121, v12, v2
	v_fma_f32 v2, -v122, v13, v2
	v_fma_f32 v2, -v123, v14, v2
	v_fma_f32 v2, -v124, v15, v2
	v_fma_f32 v2, -v125, v8, v2
	v_fma_f32 v2, -v126, v9, v2
	v_fma_f32 v2, -v127, v10, v2
	v_fma_f32 v2, -v137, v11, v2
	v_fma_f32 v2, -v139, v4, v2
	v_fma_f32 v2, -v140, v5, v2
	v_fma_f32 v2, -v142, v6, v2
	v_fma_f32 v2, -v92, v7, v2
	v_fma_f32 v0, -v93, v0, v2
	s_and_b64 vcc, exec, s[52:53]
	v_fma_f32 v95, -v94, v1, v0
	s_cbranch_vccnz .LBB0_617
	v_cvt_pk_bf16_f32 v0, v95, s0
	global_store_short v[56:57], v0, off

; __device__ __forceinline__ bf16_t f2bf(float f) { return (bf16_t)(cvt_pk_bf16(f, 0.f) & 0xffffu); }
; __device__ __forceinline__ float bf2f(bf16_t b) { return __uint_as_float(((unsigned)b) << 16); }
; template <int I>
; __device__ __forceinline__ void solve_rows(float (&x)[64], const f32x4* A4, const bf16_t* src, const float* sBeta, const float* sGam, int part, bf16_t* dst, int nvalid) {
;     ...
;         for (int q = 0; q < (I + 3) / 4; ++q) a4[q] = A4[I * 16 + q];
;         float a = bf2f(src[I * 136]) * sBeta[I];
;         if (part == 1) a *= __expf(sGam[I]);
; #pragma unroll
;         for (int j = 0; j < I; ++j) a -= a4[j >> 2][j & 3] * x[j];
;         x[I] = a;
;         if (I < nvalid) *dst = f2bf(a);
;         dst += 1024;
;         asm volatile("" : "+v"(dst) :: "memory");
.LBB0_619:
	v_fma_f32 v7, -v64, v52, v7
	v_fma_f32 v7, -v65, v53, v7
	v_fma_f32 v7, -v67, v54, v7
	v_fma_f32 v7, -v69, v55, v7
	v_fma_f32 v7, -v71, v48, v7
	v_fma_f32 v7, -v73, v49, v7
	v_fma_f32 v7, -v75, v50, v7
	v_fma_f32 v7, -v77, v51, v7
	v_fma_f32 v7, -v79, v44, v7
	v_fma_f32 v7, -v81, v45, v7
	v_fma_f32 v7, -v83, v46, v7
	v_fma_f32 v7, -v85, v47, v7
	v_fma_f32 v7, -v87, v40, v7
	v_fma_f32 v7, -v89, v41, v7
	v_fma_f32 v7, -v91, v42, v7
	v_fma_f32 v7, -v66, v43, v7
	v_fma_f32 v7, -v68, v36, v7
	v_fma_f32 v7, -v70, v37, v7
	v_fma_f32 v7, -v72, v38, v7
	v_fma_f32 v7, -v74, v39, v7
	v_fma_f32 v7, -v76, v32, v7
	v_fma_f32 v7, -v78, v33, v7
	v_fma_f32 v7, -v80, v34, v7
	v_fma_f32 v7, -v82, v35, v7
	v_fma_f32 v7, -v84, v28, v7
	v_fma_f32 v7, -v86, v29, v7
	v_fma_f32 v7, -v88, v30, v7
	v_fma_f32 v7, -v90, v31, v7
	v_fma_f32 v7, -v109, v24, v7
	v_fma_f32 v7, -v110, v25, v7
	v_fma_f32 v7, -v111, v26, v7
	v_fma_f32 v7, -v112, v27, v7
	v_fma_f32 v7, -v113, v20, v7
	v_fma_f32 v7, -v114, v21, v7
	v_fma_f32 v7, -v115, v22, v7
	v_fma_f32 v7, -v116, v23, v7
	v_fma_f32 v7, -v117, v16, v7
	v_fma_f32 v7, -v118, v17, v7
	v_fma_f32 v7, -v119, v18, v7
	v_fma_f32 v7, -v120, v19, v7
	v_fma_f32 v7, -v121, v12, v7
	v_fma_f32 v7, -v122, v13, v7
	v_fma_f32 v7, -v123, v14, v7
	v_fma_f32 v7, -v124, v15, v7
	v_fma_f32 v7, -v125, v8, v7
	v_fma_f32 v7, -v126, v9, v7
	v_fma_f32 v7, -v127, v10, v7
	v_fma_f32 v7, -v137, v11, v7
	v_fma_f32 v0, -v139, v0, v7
	v_fma_f32 v0, -v140, v1, v0
	v_fma_f32 v0, -v142, v2, v0
	v_fma_f32 v0, -v92, v3, v0
	v_fma_f32 v0, -v93, v4, v0
	v_fma_f32 v0, -v94, v5, v0
	s_and_b64 vcc, exec, s[52:53]
	v_fma_f32 v96, -v95, v6, v0
	s_cbranch_vccnz .LBB0_621
	v_cvt_pk_bf16_f32 v0, v96, s0
	global_store_short v[56:57], v0, off

; __device__ __forceinline__ bf16_t f2bf(float f) { return (bf16_t)(cvt_pk_bf16(f, 0.f) & 0xffffu); }
; __device__ __forceinline__ float bf2f(bf16_t b) { return __uint_as_float(((unsigned)b) << 16); }
; template <int I>
; __device__ __forceinline__ void solve_rows(float (&x)[64], const f32x4* A4, const bf16_t* src, const float* sBeta, const float* sGam, int part, bf16_t* dst, int nvalid) {
;     ...
;         for (int q = 0; q < (I + 3) / 4; ++q) a4[q] = A4[I * 16 + q];
;         float a = bf2f(src[I * 136]) * sBeta[I];
;         if (part == 1) a *= __expf(sGam[I]);
; #pragma unroll
;         for (int j = 0; j < I; ++j) a -= a4[j >> 2][j & 3] * x[j];
;         x[I] = a;
;         if (I < nvalid) *dst = f2bf(a);
;         dst += 1024;
;         asm volatile("" : "+v"(dst) :: "memory");
.LBB0_623:
	v_fma_f32 v52, -v64, v52, v58
	v_fma_f32 v52, -v65, v53, v52
	v_fma_f32 v52, -v67, v54, v52
	v_fma_f32 v52, -v69, v55, v52
	v_fma_f32 v48, -v71, v48, v52
	v_fma_f32 v48, -v73, v49, v48
	v_fma_f32 v48, -v75, v50, v48
	v_fma_f32 v48, -v77, v51, v48
	v_fma_f32 v44, -v79, v44, v48
	v_fma_f32 v44, -v81, v45, v44
	v_fma_f32 v44, -v83, v46, v44
	v_fma_f32 v44, -v85, v47, v44
	v_fma_f32 v40, -v87, v40, v44
	v_fma_f32 v40, -v89, v41, v40
	v_fma_f32 v40, -v91, v42, v40
	v_fma_f32 v40, -v66, v43, v40
	v_fma_f32 v36, -v68, v36, v40
	v_fma_f32 v36, -v70, v37, v36
	v_fma_f32 v36, -v72, v38, v36
	v_fma_f32 v36, -v74, v39, v36
	v_fma_f32 v32, -v76, v32, v36
	v_fma_f32 v32, -v78, v33, v32
	v_fma_f32 v32, -v80, v34, v32
	v_fma_f32 v32, -v82, v35, v32
	v_fma_f32 v28, -v84, v28, v32
	v_fma_f32 v28, -v86, v29, v28
	v_fma_f32 v28, -v88, v30, v28
	v_fma_f32 v28, -v90, v31, v28
	v_fma_f32 v24, -v109, v24, v28
	v_fma_f32 v24, -v110, v25, v24
	v_fma_f32 v24, -v111, v26, v24
	v_fma_f32 v24, -v112, v27, v24
	v_fma_f32 v20, -v113, v20, v24
	v_fma_f32 v20, -v114, v21, v20
	v_fma_f32 v20, -v115, v22, v20
	v_fma_f32 v20, -v116, v23, v20
	v_fma_f32 v16, -v117, v16, v20
	v_fma_f32 v16, -v118, v17, v16
	v_fma_f32 v16, -v119, v18, v16
	v_fma_f32 v16, -v120, v19, v16
	v_fma_f32 v12, -v121, v12, v16
	v_fma_f32 v12, -v122, v13, v12
	v_fma_f32 v12, -v123, v14, v12
	v_fma_f32 v12, -v124, v15, v12
	v_fma_f32 v8, -v125, v8, v12
	v_fma_f32 v8, -v126, v9, v8
	v_fma_f32 v8, -v127, v10, v8
	v_fma_f32 v8, -v137, v11, v8
	v_fma_f32 v0, -v139, v0, v8
	v_fma_f32 v0, -v140, v1, v0
	v_fma_f32 v0, -v142, v2, v0
	v_fma_f32 v0, -v92, v3, v0
	v_fma_f32 v0, -v93, v4, v0
	v_fma_f32 v0, -v94, v5, v0
	v_fma_f32 v0, -v95, v6, v0
	s_and_b64 vcc, exec, s[52:53]
	v_fma_f32 v97, -v96, v7, v0
	s_cbranch_vccnz .LBB0_625
	v_cvt_pk_bf16_f32 v0, v97, s0
	global_store_short v[56:57], v0, off

; __device__ __forceinline__ bf16_t f2bf(float f) { return (bf16_t)(cvt_pk_bf16(f, 0.f) & 0xffffu); }
; __device__ __forceinline__ float bf2f(bf16_t b) { return __uint_as_float(((unsigned)b) << 16); }
; template <int I>
; __device__ __forceinline__ void solve_rows(float (&x)[64], const f32x4* A4, const bf16_t* src, const float* sBeta, const float* sGam, int part, bf16_t* dst, int nvalid) {
;     ...
;         for (int q = 0; q < (I + 3) / 4; ++q) a4[q] = A4[I * 16 + q];
;         float a = bf2f(src[I * 136]) * sBeta[I];
;         if (part == 1) a *= __expf(sGam[I]);
; #pragma unroll
;         for (int j = 0; j < I; ++j) a -= a4[j >> 2][j & 3] * x[j];
;         x[I] = a;
;         if (I < nvalid) *dst = f2bf(a);
;         dst += 1024;
;         asm volatile("" : "+v"(dst) :: "memory");
.LBB0_627:
	v_fma_f32 v1, -v64, v52, v1
	v_fma_f32 v1, -v65, v53, v1
	v_fma_f32 v1, -v67, v54, v1
	v_fma_f32 v1, -v69, v55, v1
	v_fma_f32 v1, -v71, v56, v1
	v_fma_f32 v1, -v73, v57, v1
	v_fma_f32 v1, -v75, v58, v1
	v_fma_f32 v1, -v77, v59, v1
	v_fma_f32 v1, -v79, v48, v1
	v_fma_f32 v1, -v81, v49, v1
	v_fma_f32 v1, -v83, v50, v1
	v_fma_f32 v1, -v85, v51, v1
	v_fma_f32 v1, -v87, v44, v1
	v_fma_f32 v1, -v89, v45, v1
	v_fma_f32 v1, -v91, v46, v1
	v_fma_f32 v1, -v66, v47, v1
	v_fma_f32 v1, -v68, v40, v1
	v_fma_f32 v1, -v70, v41, v1
	v_fma_f32 v1, -v72, v42, v1
	v_fma_f32 v1, -v74, v43, v1
	v_fma_f32 v1, -v76, v36, v1
	v_fma_f32 v1, -v78, v37, v1
	v_fma_f32 v1, -v80, v38, v1
	v_fma_f32 v1, -v82, v39, v1
	v_fma_f32 v1, -v84, v32, v1
	v_fma_f32 v1, -v86, v33, v1
	v_fma_f32 v1, -v88, v34, v1
	v_fma_f32 v1, -v90, v35, v1
	v_fma_f32 v1, -v109, v28, v1
	v_fma_f32 v1, -v110, v29, v1
	v_fma_f32 v1, -v111, v30, v1
	v_fma_f32 v1, -v112, v31, v1
	v_fma_f32 v1, -v113, v24, v1
	v_fma_f32 v1, -v114, v25, v1
	v_fma_f32 v1, -v115, v26, v1
	v_fma_f32 v1, -v116, v27, v1
	v_fma_f32 v1, -v117, v20, v1
	v_fma_f32 v1, -v118, v21, v1
	v_fma_f32 v1, -v119, v22, v1
	v_fma_f32 v1, -v120, v23, v1
	v_fma_f32 v1, -v121, v16, v1
	v_fma_f32 v1, -v122, v17, v1
	v_fma_f32 v1, -v123, v18, v1
	v_fma_f32 v1, -v124, v19, v1
	v_fma_f32 v1, -v125, v12, v1
	v_fma_f32 v1, -v126, v13, v1
	v_fma_f32 v1, -v127, v14, v1
	v_fma_f32 v1, -v137, v15, v1
	v_fma_f32 v1, -v139, v8, v1
	v_fma_f32 v1, -v140, v9, v1
	v_fma_f32 v1, -v142, v10, v1
	v_fma_f32 v1, -v92, v11, v1
	v_fma_f32 v1, -v93, v4, v1
	v_fma_f32 v1, -v94, v5, v1
	v_fma_f32 v1, -v95, v6, v1
	v_fma_f32 v1, -v96, v7, v1
	s_and_b64 vcc, exec, s[52:53]
	v_fma_f32 v98, -v97, v0, v1
	s_cbranch_vccnz .LBB0_629
	v_cvt_pk_bf16_f32 v0, v98, s0
	global_store_short v[60:61], v0, off

; __device__ __forceinline__ bf16_t f2bf(float f) { return (bf16_t)(cvt_pk_bf16(f, 0.f) & 0xffffu); }
; __device__ __forceinline__ float bf2f(bf16_t b) { return __uint_as_float(((unsigned)b) << 16); }
; template <int I>
; __device__ __forceinline__ void solve_rows(float (&x)[64], const f32x4* A4, const bf16_t* src, const float* sBeta, const float* sGam, int part, bf16_t* dst, int nvalid) {
;     ...
;         for (int q = 0; q < (I + 3) / 4; ++q) a4[q] = A4[I * 16 + q];
;         float a = bf2f(src[I * 136]) * sBeta[I];
;         if (part == 1) a *= __expf(sGam[I]);
; #pragma unroll
;         for (int j = 0; j < I; ++j) a -= a4[j >> 2][j & 3] * x[j];
;         x[I] = a;
;         if (I < nvalid) *dst = f2bf(a);
;         dst += 1024;
;         asm volatile("" : "+v"(dst) :: "memory");
.LBB0_631:
	v_fma_f32 v2, -v64, v52, v2
	v_fma_f32 v2, -v65, v53, v2
	v_fma_f32 v2, -v67, v54, v2
	v_fma_f32 v2, -v69, v55, v2
	v_fma_f32 v2, -v71, v56, v2
	v_fma_f32 v2, -v73, v57, v2
	v_fma_f32 v2, -v75, v58, v2
	v_fma_f32 v2, -v77, v59, v2
	v_fma_f32 v2, -v79, v48, v2
	v_fma_f32 v2, -v81, v49, v2
	v_fma_f32 v2, -v83, v50, v2
	v_fma_f32 v2, -v85, v51, v2
	v_fma_f32 v2, -v87, v44, v2
	v_fma_f32 v2, -v89, v45, v2
	v_fma_f32 v2, -v91, v46, v2
	v_fma_f32 v2, -v66, v47, v2
	v_fma_f32 v2, -v68, v40, v2
	v_fma_f32 v2, -v70, v41, v2
	v_fma_f32 v2, -v72, v42, v2
	v_fma_f32 v2, -v74, v43, v2
	v_fma_f32 v2, -v76, v36, v2
	v_fma_f32 v2, -v78, v37, v2
	v_fma_f32 v2, -v80, v38, v2
	v_fma_f32 v2, -v82, v39, v2
	v_fma_f32 v2, -v84, v32, v2
	v_fma_f32 v2, -v86, v33, v2
	v_fma_f32 v2, -v88, v34, v2
	v_fma_f32 v2, -v90, v35, v2
	v_fma_f32 v2, -v109, v28, v2
	v_fma_f32 v2, -v110, v29, v2
	v_fma_f32 v2, -v111, v30, v2
	v_fma_f32 v2, -v112, v31, v2
	v_fma_f32 v2, -v113, v24, v2
	v_fma_f32 v2, -v114, v25, v2
	v_fma_f32 v2, -v115, v26, v2
	v_fma_f32 v2, -v116, v27, v2
	v_fma_f32 v2, -v117, v20, v2
	v_fma_f32 v2, -v118, v21, v2
	v_fma_f32 v2, -v119, v22, v2
	v_fma_f32 v2, -v120, v23, v2
	v_fma_f32 v2, -v121, v16, v2
	v_fma_f32 v2, -v122, v17, v2
	v_fma_f32 v2, -v123, v18, v2
	v_fma_f32 v2, -v124, v19, v2
	v_fma_f32 v2, -v125, v12, v2
	v_fma_f32 v2, -v126, v13, v2
	v_fma_f32 v2, -v127, v14, v2
	v_fma_f32 v2, -v137, v15, v2
	v_fma_f32 v2, -v139, v8, v2
	v_fma_f32 v2, -v140, v9, v2
	v_fma_f32 v2, -v142, v10, v2
	v_fma_f32 v2, -v92, v11, v2
	v_fma_f32 v2, -v93, v4, v2
	v_fma_f32 v2, -v94, v5, v2
	v_fma_f32 v2, -v95, v6, v2
	v_fma_f32 v2, -v96, v7, v2
	v_fma_f32 v0, -v97, v0, v2
	s_and_b64 vcc, exec, s[52:53]
	v_fma_f32 v99, -v98, v1, v0
	s_cbranch_vccnz .LBB0_633
	v_cvt_pk_bf16_f32 v0, v99, s0
	global_store_short v[60:61], v0, off

; __device__ __forceinline__ bf16_t f2bf(float f) { return (bf16_t)(cvt_pk_bf16(f, 0.f) & 0xffffu); }
; __device__ __forceinline__ float bf2f(bf16_t b) { return __uint_as_float(((unsigned)b) << 16); }
; template <int I>
; __device__ __forceinline__ void solve_rows(float (&x)[64], const f32x4* A4, const bf16_t* src, const float* sBeta, const float* sGam, int part, bf16_t* dst, int nvalid) {
;     ...
;         for (int q = 0; q < (I + 3) / 4; ++q) a4[q] = A4[I * 16 + q];
;         float a = bf2f(src[I * 136]) * sBeta[I];
;         if (part == 1) a *= __expf(sGam[I]);
; #pragma unroll
;         for (int j = 0; j < I; ++j) a -= a4[j >> 2][j & 3] * x[j];
;         x[I] = a;
;         if (I < nvalid) *dst = f2bf(a);
;         dst += 1024;
;         asm volatile("" : "+v"(dst) :: "memory");
.LBB0_635:
	v_fma_f32 v3, -v64, v56, v3
	v_fma_f32 v3, -v65, v57, v3
	v_fma_f32 v3, -v67, v58, v3
	v_fma_f32 v3, -v69, v59, v3
	v_fma_f32 v3, -v71, v52, v3
	v_fma_f32 v3, -v73, v53, v3
	v_fma_f32 v3, -v75, v54, v3
	v_fma_f32 v3, -v77, v55, v3
	v_fma_f32 v3, -v79, v48, v3
	v_fma_f32 v3, -v81, v49, v3
	v_fma_f32 v3, -v83, v50, v3
	v_fma_f32 v3, -v85, v51, v3
	v_fma_f32 v3, -v87, v44, v3
	v_fma_f32 v3, -v89, v45, v3
	v_fma_f32 v3, -v91, v46, v3
	v_fma_f32 v3, -v66, v47, v3
	v_fma_f32 v3, -v68, v40, v3
	v_fma_f32 v3, -v70, v41, v3
	v_fma_f32 v3, -v72, v42, v3
	v_fma_f32 v3, -v74, v43, v3
	v_fma_f32 v3, -v76, v36, v3
	v_fma_f32 v3, -v78, v37, v3
	v_fma_f32 v3, -v80, v38, v3
	v_fma_f32 v3, -v82, v39, v3
	v_fma_f32 v3, -v84, v32, v3
	v_fma_f32 v3, -v86, v33, v3
	v_fma_f32 v3, -v88, v34, v3
	v_fma_f32 v3, -v90, v35, v3
	v_fma_f32 v3, -v109, v28, v3
	v_fma_f32 v3, -v110, v29, v3
	v_fma_f32 v3, -v111, v30, v3
	v_fma_f32 v3, -v112, v31, v3
	v_fma_f32 v3, -v113, v24, v3
	v_fma_f32 v3, -v114, v25, v3
	v_fma_f32 v3, -v115, v26, v3
	v_fma_f32 v3, -v116, v27, v3
	v_fma_f32 v3, -v117, v20, v3
	v_fma_f32 v3, -v118, v21, v3
	v_fma_f32 v3, -v119, v22, v3
	v_fma_f32 v3, -v120, v23, v3
	v_fma_f32 v3, -v121, v16, v3
	v_fma_f32 v3, -v122, v17, v3
	v_fma_f32 v3, -v123, v18, v3
	v_fma_f32 v3, -v124, v19, v3
	v_fma_f32 v3, -v125, v8, v3
	v_fma_f32 v3, -v126, v9, v3
	v_fma_f32 v3, -v127, v10, v3
	v_fma_f32 v3, -v137, v11, v3
	v_fma_f32 v3, -v139, v4, v3
	v_fma_f32 v3, -v140, v5, v3
	v_fma_f32 v3, -v142, v6, v3
	v_fma_f32 v3, -v92, v7, v3
	v_fma_f32 v3, -v93, v12, v3
	v_fma_f32 v3, -v94, v13, v3
	v_fma_f32 v3, -v95, v14, v3
	v_fma_f32 v3, -v96, v15, v3
	v_fma_f32 v0, -v97, v0, v3
	v_fma_f32 v0, -v98, v1, v0
	s_and_b64 vcc, exec, s[52:53]
	v_fma_f32 v100, -v99, v2, v0
	s_cbranch_vccnz .LBB0_637
	v_cvt_pk_bf16_f32 v0, v100, s0
	global_store_short v[60:61], v0, off

; __device__ __forceinline__ bf16_t f2bf(float f) { return (bf16_t)(cvt_pk_bf16(f, 0.f) & 0xffffu); }
; __device__ __forceinline__ float bf2f(bf16_t b) { return __uint_as_float(((unsigned)b) << 16); }
; template <int I>
; __device__ __forceinline__ void solve_rows(float (&x)[64], const f32x4* A4, const bf16_t* src, const float* sBeta, const float* sGam, int part, bf16_t* dst, int nvalid) {
;     ...
;         for (int q = 0; q < (I + 3) / 4; ++q) a4[q] = A4[I * 16 + q];
;         float a = bf2f(src[I * 136]) * sBeta[I];
;         if (part == 1) a *= __expf(sGam[I]);
; #pragma unroll
;         for (int j = 0; j < I; ++j) a -= a4[j >> 2][j & 3] * x[j];
;         x[I] = a;
;         if (I < nvalid) *dst = f2bf(a);
;         dst += 1024;
;         asm volatile("" : "+v"(dst) :: "memory");
.LBB0_639:
	v_fma_f32 v56, -v64, v56, v62
	v_fma_f32 v56, -v65, v57, v56
	v_fma_f32 v56, -v67, v58, v56
	v_fma_f32 v56, -v69, v59, v56
	v_fma_f32 v52, -v71, v52, v56
	v_fma_f32 v52, -v73, v53, v52
	v_fma_f32 v52, -v75, v54, v52
	v_fma_f32 v52, -v77, v55, v52
	v_fma_f32 v48, -v79, v48, v52
	v_fma_f32 v48, -v81, v49, v48
	v_fma_f32 v48, -v83, v50, v48
	v_fma_f32 v48, -v85, v51, v48
	v_fma_f32 v44, -v87, v44, v48
	v_fma_f32 v44, -v89, v45, v44
	v_fma_f32 v44, -v91, v46, v44
	v_fma_f32 v44, -v66, v47, v44
	v_fma_f32 v40, -v68, v40, v44
	v_fma_f32 v40, -v70, v41, v40
	v_fma_f32 v40, -v72, v42, v40
	v_fma_f32 v40, -v74, v43, v40
	v_fma_f32 v36, -v76, v36, v40
	v_fma_f32 v36, -v78, v37, v36
	v_fma_f32 v36, -v80, v38, v36
	v_fma_f32 v36, -v82, v39, v36
	v_fma_f32 v32, -v84, v32, v36
	v_fma_f32 v32, -v86, v33, v32
	v_fma_f32 v32, -v88, v34, v32
	v_fma_f32 v32, -v90, v35, v32
	v_fma_f32 v28, -v109, v28, v32
	v_fma_f32 v28, -v110, v29, v28
	v_fma_f32 v28, -v111, v30, v28
	v_fma_f32 v28, -v112, v31, v28
	v_fma_f32 v24, -v113, v24, v28
	v_fma_f32 v24, -v114, v25, v24
	v_fma_f32 v24, -v115, v26, v24
	v_fma_f32 v24, -v116, v27, v24
	v_fma_f32 v20, -v117, v20, v24
	v_fma_f32 v20, -v118, v21, v20
	v_fma_f32 v20, -v119, v22, v20
	v_fma_f32 v20, -v120, v23, v20
	v_fma_f32 v16, -v121, v16, v20
	v_fma_f32 v16, -v122, v17, v16
	v_fma_f32 v16, -v123, v18, v16
	v_fma_f32 v16, -v124, v19, v16
	v_fma_f32 v8, -v125, v8, v16
	v_fma_f32 v8, -v126, v9, v8
	v_fma_f32 v8, -v127, v10, v8
	v_fma_f32 v8, -v137, v11, v8
	v_fma_f32 v4, -v139, v4, v8
	v_fma_f32 v4, -v140, v5, v4
	v_fma_f32 v4, -v142, v6, v4
	v_fma_f32 v4, -v92, v7, v4
	v_fma_f32 v4, -v93, v12, v4
	v_fma_f32 v4, -v94, v13, v4
	v_fma_f32 v4, -v95, v14, v4
	v_fma_f32 v4, -v96, v15, v4
	v_fma_f32 v0, -v97, v0, v4
	v_fma_f32 v0, -v98, v1, v0
	v_fma_f32 v0, -v99, v2, v0
	s_and_b64 vcc, exec, s[52:53]
	v_fma_f32 v101, -v100, v3, v0
	s_cbranch_vccnz .LBB0_641
	v_cvt_pk_bf16_f32 v0, v101, s0
	global_store_short v[60:61], v0, off

; __device__ __forceinline__ bf16_t f2bf(float f) { return (bf16_t)(cvt_pk_bf16(f, 0.f) & 0xffffu); }
; __device__ __forceinline__ float bf2f(bf16_t b) { return __uint_as_float(((unsigned)b) << 16); }
; template <int I>
; __device__ __forceinline__ void solve_rows(float (&x)[64], const f32x4* A4, const bf16_t* src, const float* sBeta, const float* sGam, int part, bf16_t* dst, int nvalid) {
;     ...
;         for (int q = 0; q < (I + 3) / 4; ++q) a4[q] = A4[I * 16 + q];
;         float a = bf2f(src[I * 136]) * sBeta[I];
;         if (part == 1) a *= __expf(sGam[I]);
; #pragma unroll
;         for (int j = 0; j < I; ++j) a -= a4[j >> 2][j & 3] * x[j];
;         x[I] = a;
;         if (I < nvalid) *dst = f2bf(a);
;         dst += 1024;
;         asm volatile("" : "+v"(dst) :: "memory");
.LBB0_643:
	v_fma_f32 v1, -v64, v56, v1
	v_fma_f32 v1, -v65, v57, v1
	v_fma_f32 v1, -v67, v58, v1
	v_fma_f32 v1, -v69, v59, v1
	v_fma_f32 v1, -v71, v60, v1
	v_fma_f32 v1, -v73, v61, v1
	v_fma_f32 v1, -v75, v62, v1
	v_fma_f32 v1, -v77, v63, v1
	v_fma_f32 v1, -v79, v52, v1
	v_fma_f32 v1, -v81, v53, v1
	v_fma_f32 v1, -v83, v54, v1
	v_fma_f32 v1, -v85, v55, v1
	v_fma_f32 v1, -v87, v48, v1
	v_fma_f32 v1, -v89, v49, v1
	v_fma_f32 v1, -v91, v50, v1
	v_fma_f32 v1, -v66, v51, v1
	v_fma_f32 v1, -v68, v44, v1
	v_fma_f32 v1, -v70, v45, v1
	v_fma_f32 v1, -v72, v46, v1
	v_fma_f32 v1, -v74, v47, v1
	v_fma_f32 v1, -v76, v40, v1
	v_fma_f32 v1, -v78, v41, v1
	v_fma_f32 v1, -v80, v42, v1
	v_fma_f32 v1, -v82, v43, v1
	v_fma_f32 v1, -v84, v36, v1
	v_fma_f32 v1, -v86, v37, v1
	v_fma_f32 v1, -v88, v38, v1
	v_fma_f32 v1, -v90, v39, v1
	v_fma_f32 v1, -v109, v32, v1
	v_fma_f32 v1, -v110, v33, v1
	v_fma_f32 v1, -v111, v34, v1
	v_fma_f32 v1, -v112, v35, v1
	v_fma_f32 v1, -v113, v28, v1
	v_fma_f32 v1, -v114, v29, v1
	v_fma_f32 v1, -v115, v30, v1
	v_fma_f32 v1, -v116, v31, v1
	v_fma_f32 v1, -v117, v24, v1
	v_fma_f32 v1, -v118, v25, v1
	v_fma_f32 v1, -v119, v26, v1
	v_fma_f32 v1, -v120, v27, v1
	v_fma_f32 v1, -v121, v20, v1
	v_fma_f32 v1, -v122, v21, v1
	v_fma_f32 v1, -v123, v22, v1
	v_fma_f32 v1, -v124, v23, v1
	v_fma_f32 v1, -v125, v16, v1
	v_fma_f32 v1, -v126, v17, v1
	v_fma_f32 v1, -v127, v18, v1
	v_fma_f32 v1, -v137, v19, v1
	v_fma_f32 v1, -v139, v12, v1
	v_fma_f32 v1, -v140, v13, v1
	v_fma_f32 v1, -v142, v14, v1
	v_fma_f32 v1, -v92, v15, v1
	v_fma_f32 v1, -v93, v8, v1
	v_fma_f32 v1, -v94, v9, v1
	v_fma_f32 v1, -v95, v10, v1
	v_fma_f32 v1, -v96, v11, v1
	v_fma_f32 v1, -v97, v4, v1
	v_fma_f32 v1, -v98, v5, v1
	v_fma_f32 v1, -v99, v6, v1
	v_fma_f32 v1, -v100, v7, v1
	s_and_b64 vcc, exec, s[52:53]
	v_fma_f32 v102, -v101, v0, v1
	s_cbranch_vccnz .LBB0_645
	v_cvt_pk_bf16_f32 v0, v102, s0
	global_store_short v[104:105], v0, off

; __device__ __forceinline__ bf16_t f2bf(float f) { return (bf16_t)(cvt_pk_bf16(f, 0.f) & 0xffffu); }
; __device__ __forceinline__ float bf2f(bf16_t b) { return __uint_as_float(((unsigned)b) << 16); }
; template <int I>
; __device__ __forceinline__ void solve_rows(float (&x)[64], const f32x4* A4, const bf16_t* src, const float* sBeta, const float* sGam, int part, bf16_t* dst, int nvalid) {
;     ...
;         for (int q = 0; q < (I + 3) / 4; ++q) a4[q] = A4[I * 16 + q];
;         float a = bf2f(src[I * 136]) * sBeta[I];
;         if (part == 1) a *= __expf(sGam[I]);
; #pragma unroll
;         for (int j = 0; j < I; ++j) a -= a4[j >> 2][j & 3] * x[j];
;         x[I] = a;
;         if (I < nvalid) *dst = f2bf(a);
;         dst += 1024;
;         asm volatile("" : "+v"(dst) :: "memory");
.LBB0_647:
	v_fma_f32 v2, -v64, v56, v2
	v_fma_f32 v2, -v65, v57, v2
	v_fma_f32 v2, -v67, v58, v2
	v_fma_f32 v2, -v69, v59, v2
	v_fma_f32 v2, -v71, v60, v2
	v_fma_f32 v2, -v73, v61, v2
	v_fma_f32 v2, -v75, v62, v2
	v_fma_f32 v2, -v77, v63, v2
	v_fma_f32 v2, -v79, v52, v2
	v_fma_f32 v2, -v81, v53, v2
	v_fma_f32 v2, -v83, v54, v2
	v_fma_f32 v2, -v85, v55, v2
	v_fma_f32 v2, -v87, v48, v2
	v_fma_f32 v2, -v89, v49, v2
	v_fma_f32 v2, -v91, v50, v2
	v_fma_f32 v2, -v66, v51, v2
	v_fma_f32 v2, -v68, v44, v2
	v_fma_f32 v2, -v70, v45, v2
	v_fma_f32 v2, -v72, v46, v2
	v_fma_f32 v2, -v74, v47, v2
	v_fma_f32 v2, -v76, v40, v2
	v_fma_f32 v2, -v78, v41, v2
	v_fma_f32 v2, -v80, v42, v2
	v_fma_f32 v2, -v82, v43, v2
	v_fma_f32 v2, -v84, v36, v2
	v_fma_f32 v2, -v86, v37, v2
	v_fma_f32 v2, -v88, v38, v2
	v_fma_f32 v2, -v90, v39, v2
	v_fma_f32 v2, -v109, v32, v2
	v_fma_f32 v2, -v110, v33, v2
	v_fma_f32 v2, -v111, v34, v2
	v_fma_f32 v2, -v112, v35, v2
	v_fma_f32 v2, -v113, v28, v2
	v_fma_f32 v2, -v114, v29, v2
	v_fma_f32 v2, -v115, v30, v2
	v_fma_f32 v2, -v116, v31, v2
	v_fma_f32 v2, -v117, v24, v2
	v_fma_f32 v2, -v118, v25, v2
	v_fma_f32 v2, -v119, v26, v2
	v_fma_f32 v2, -v120, v27, v2
	v_fma_f32 v2, -v121, v20, v2
	v_fma_f32 v2, -v122, v21, v2
	v_fma_f32 v2, -v123, v22, v2
	v_fma_f32 v2, -v124, v23, v2
	v_fma_f32 v2, -v125, v16, v2
	v_fma_f32 v2, -v126, v17, v2
	v_fma_f32 v2, -v127, v18, v2
	v_fma_f32 v2, -v137, v19, v2
	v_fma_f32 v2, -v139, v12, v2
	v_fma_f32 v2, -v140, v13, v2
	v_fma_f32 v2, -v142, v14, v2
	v_fma_f32 v2, -v92, v15, v2
	v_fma_f32 v2, -v93, v8, v2
	v_fma_f32 v2, -v94, v9, v2
	v_fma_f32 v2, -v95, v10, v2
	v_fma_f32 v2, -v96, v11, v2
	v_fma_f32 v2, -v97, v4, v2
	v_fma_f32 v2, -v98, v5, v2
	v_fma_f32 v2, -v99, v6, v2
	v_fma_f32 v2, -v100, v7, v2
	v_fma_f32 v0, -v101, v0, v2
	s_and_b64 vcc, exec, s[52:53]
	v_fma_f32 v103, -v102, v1, v0
	s_cbranch_vccnz .LBB0_649
	v_cvt_pk_bf16_f32 v0, v103, s0
	global_store_short v[104:105], v0, off

; __device__ __forceinline__ bf16_t f2bf(float f) { return (bf16_t)(cvt_pk_bf16(f, 0.f) & 0xffffu); }
; __device__ __forceinline__ float bf2f(bf16_t b) { return __uint_as_float(((unsigned)b) << 16); }
; template <int I>
; __device__ __forceinline__ void solve_rows(float (&x)[64], const f32x4* A4, const bf16_t* src, const float* sBeta, const float* sGam, int part, bf16_t* dst, int nvalid) {
;     ...
;         for (int q = 0; q < (I + 3) / 4; ++q) a4[q] = A4[I * 16 + q];
;         float a = bf2f(src[I * 136]) * sBeta[I];
;         if (part == 1) a *= __expf(sGam[I]);
; #pragma unroll
;         for (int j = 0; j < I; ++j) a -= a4[j >> 2][j & 3] * x[j];
;         x[I] = a;
;         if (I < nvalid) *dst = f2bf(a);
;         dst += 1024;
;         asm volatile("" : "+v"(dst) :: "memory");
.LBB0_651:
	s_and_b64 vcc, exec, s[52:53]
	s_cbranch_vccnz .LBB0_653
	v_fma_f32 v3, -v64, v60, v3
	v_fma_f32 v3, -v65, v61, v3
	v_fma_f32 v3, -v67, v62, v3
	v_fma_f32 v3, -v69, v63, v3
	v_fma_f32 v3, -v71, v56, v3
	v_fma_f32 v3, -v73, v57, v3
	v_fma_f32 v3, -v75, v58, v3
	v_fma_f32 v3, -v77, v59, v3
	v_fma_f32 v3, -v79, v52, v3
	v_fma_f32 v3, -v81, v53, v3
	v_fma_f32 v3, -v83, v54, v3
	v_fma_f32 v3, -v85, v55, v3
	v_fma_f32 v3, -v87, v48, v3
	v_fma_f32 v3, -v89, v49, v3
	v_fma_f32 v3, -v91, v50, v3
	v_fma_f32 v3, -v66, v51, v3
	v_fma_f32 v3, -v68, v44, v3
	v_fma_f32 v3, -v70, v45, v3
	v_fma_f32 v3, -v72, v46, v3
	v_fma_f32 v3, -v74, v47, v3
	v_fma_f32 v3, -v76, v40, v3
	v_fma_f32 v3, -v78, v41, v3
	v_fma_f32 v3, -v80, v42, v3
	v_fma_f32 v3, -v82, v43, v3
	v_fma_f32 v3, -v84, v36, v3
	v_fma_f32 v3, -v86, v37, v3
	v_fma_f32 v3, -v88, v38, v3
	v_fma_f32 v3, -v90, v39, v3
	v_fma_f32 v3, -v109, v32, v3
	v_fma_f32 v3, -v110, v33, v3
	v_fma_f32 v3, -v111, v34, v3
	v_fma_f32 v3, -v112, v35, v3
	v_fma_f32 v3, -v113, v28, v3
	v_fma_f32 v3, -v114, v29, v3
	v_fma_f32 v3, -v115, v30, v3
	v_fma_f32 v3, -v116, v31, v3
	v_fma_f32 v3, -v117, v24, v3
	v_fma_f32 v3, -v118, v25, v3
	v_fma_f32 v3, -v119, v26, v3
	v_fma_f32 v3, -v120, v27, v3
	v_fma_f32 v3, -v121, v20, v3
	v_fma_f32 v3, -v122, v21, v3
	v_fma_f32 v3, -v123, v22, v3
	v_fma_f32 v3, -v124, v23, v3
	v_fma_f32 v3, -v125, v16, v3
	v_fma_f32 v3, -v126, v17, v3
	v_fma_f32 v3, -v127, v18, v3
	v_fma_f32 v3, -v137, v19, v3
	v_fma_f32 v3, -v139, v12, v3
	v_fma_f32 v3, -v140, v13, v3
	v_pk_mov_b32 v[12:13], v[14:15], v[8:9] op_sel:[1,0]
	v_fma_f32 v3, -v142, v14, v3
	v_pk_mul_f32 v[12:13], v[92:93], v[12:13]
	v_mov_b32_e32 v8, v9
	v_sub_f32_e32 v3, v3, v12
	v_mov_b32_e32 v9, v10
	v_sub_f32_e32 v3, v3, v13
	v_pk_mul_f32 v[8:9], v[94:95], v[8:9]
	s_nop 0
	v_sub_f32_e32 v3, v3, v8
	v_sub_f32_e32 v3, v3, v9
	v_pk_mov_b32 v[8:9], v[10:11], v[4:5] op_sel:[1,0]
	v_mov_b32_e32 v4, v5
	v_pk_mul_f32 v[8:9], v[96:97], v[8:9]
	v_mov_b32_e32 v5, v6
	v_sub_f32_e32 v3, v3, v8
	v_sub_f32_e32 v3, v3, v9
	v_pk_mul_f32 v[4:5], v[98:99], v[4:5]
	s_nop 0
	v_sub_f32_e32 v3, v3, v4
	v_sub_f32_e32 v3, v3, v5
	v_pk_mov_b32 v[4:5], v[6:7], v[0:1] op_sel:[1,0]
	s_nop 0
	v_pk_mul_f32 v[4:5], v[100:101], v[4:5]
	s_nop 0
	v_sub_f32_e32 v0, v3, v4
	v_sub_f32_e32 v3, v0, v5
	v_mov_b32_e32 v0, v1
	v_mov_b32_e32 v1, v2
	v_pk_mul_f32 v[0:1], v[102:103], v[0:1]
	s_nop 0
	v_sub_f32_e32 v0, v3, v0
	v_sub_f32_e32 v0, v0, v1
	v_cvt_pk_bf16_f32 v0, v0, s0
	global_store_short v[104:105], v0, off
